# full stack plus SADDR-form LDS-DMA loads where base is scalar (61 loads, 25 VALU adds removed)
# speedup vs baseline: 1.0084x; 1.0026x over previous
; #define PG8_STAGEX(b, gbase) do { if constexpr (XR) { if (lane < 16) __builtin_amdgcn_global_load_lds((const unsigned*)((const char*)(gbase) + voffX), (PG8_LAS unsigned*)(lds + XR_OFF + (b) * 2048 + wid * 256), 16, 0, 0); } } while (0)
; #define PG8_LDX(b) do { if constexpr (XR) { _Pragma("unroll") for (int k = 0; k < 2; ++k) Ax_[k] = *(const PG8_LAS bf16x8*)(lds + XR_OFF + (b) * 2048 + aoffx + k * 1024); } } while (0)
; #define PG8_MMAX() do { if constexpr (XR) { if (hasx) { __builtin_amdgcn_s_setprio(1); if (wr == 0) PG8_MMAX_(B0); else PG8_MMAX_(B1); __builtin_amdgcn_s_setprio(0); } } } while (0)
; #define PG8_WAIT_LOOP() do { if constexpr (XR) PG8_WAIT_V(9); else PG8_WAIT_V(8); } while (0)
; #define PG8_STAGE(bufoff, gbase, voff) do { _Pragma("unroll") for (int _i = 0; _i < 2; ++_i) \
;         __builtin_amdgcn_global_load_lds((const unsigned*)((const char*)(gbase) + (voff)[_i]), (PG8_LAS unsigned*)(lds + (bufoff) + ldsw + _i * 8192), 16, 0, 0); } while (0)
; #define PG8_WAIT_L(n) asm volatile("s_waitcnt lgkmcnt(" #n ")" ::: "memory")
; #define PG8_BAR __builtin_amdgcn_s_barrier()
; template <class Epi, class Sched, bool ALIGN_EPI = false, bool SP2 = false, bool DRAIN = true, bool XR = false>
; __device__ __forceinline__ void gemm_phase(PG8_LAS unsigned char* lds, const Gemm g, const Sched& S, const Epi& E) {
;     ...
;             const char* a1 = cA + PG8_KOA(t) + kstep;
;             const char* a2 = last ? nA + ka0 : cA + PG8_KOA(t + 2); const char* b2 = last ? nB + kb0 : cB + PG8_KOB(t + 2);
;             const char* x2 = XR ? (last ? nX + kx0 : cX + PG8_KOX(t + 2)) : nullptr; const char* x3 = XR ? x2 + kstep : nullptr;
;             const char* a3 = a2 + kstep; const char* b3 = b2 + kstep;
;             if (last && has_next) S.a_ready(nxt);
;             if constexpr (SP2) {
;             PG8_LDB(B0, 0, 0); PG8_LDB(B1, 0, 1); PG8_SCHED; PG8_LDA(At, 0, 0); PG8_LDX(0); PG8_STAGE(PG8_SA(1, 1), a1 + hstepA, voffA);
;             PG8_WAIT_LOOP(); PG8_WAIT_L(0); PG8_BAR; PG8_MMA(0, 0, At, B0); PG8_MMA(0, 1, At, B1); PG8_MMAX(); PG8_BAR; PG8_SCHED;
;             PG8_LDA(At, 0, 1); PG8_STAGE(PG8_SB(0, 0), b2, voffB); PG8_STAGE(PG8_SB(0, 1), b2 + hstep, voffB); PG8_STAGE(PG8_SA(0, 0), a2, voffA); PG8_STAGEX(0, x2);
;             PG8_WAIT_LOOP(); PG8_WAIT_L(0); PG8_BAR; PG8_MMA(1, 0, At, B0); PG8_MMA(1, 1, At, B1); PG8_BAR; PG8_SCHED;
.LBB0_325:
	s_add_i32 s26, s61, s25
	s_and_b32 s27, s26, s43
	s_lshr_b32 s84, s27, 2
	s_lshl_b32 s27, s27, 7
	s_lshl_b64 s[0:1], s[84:85], 9
	s_and_b32 s27, s27, 0x100
	s_add_u32 s0, s80, s0
	s_addc_u32 s1, s81, s1
	s_add_u32 s40, s0, s27
	s_addc_u32 s41, s1, 0
	s_add_i32 s26, s26, 2
	s_and_b32 s0, s26, s43
	s_lshr_b32 s84, s0, 2
	s_lshl_b32 s1, s0, 7
	s_lshl_b64 s[26:27], s[84:85], 9
	s_and_b32 s1, s1, 0x100
	s_add_u32 s26, s80, s26
	s_addc_u32 s27, s81, s27
	s_add_u32 s26, s26, s1
	s_mov_b32 s1, s85
	s_addc_u32 s27, s27, 0
	s_lshl_b64 s[0:1], s[0:1], 7
	s_add_u32 s36, s76, s0
	s_addc_u32 vcc_lo, s77, s1
	s_add_i32 vcc_hi, 0, 0x10000
	s_cmp_eq_u32 s42, s25
	s_cselect_b32 s1, s22, s27
	s_cselect_b32 s0, s5, s26
	v_add_u32_e32 v2, vcc_hi, v183
	s_cselect_b32 s27, s24, vcc_lo
	s_cselect_b32 s26, s23, s36
	s_add_i32 s36, 0, 0x14000
	ds_read_b128 v[134:137], v2
	ds_read_b128 v[148:151], v2 offset:1024
	ds_read_b128 v[152:155], v2 offset:2048
	ds_read_b128 v[156:159], v2 offset:3072
	v_add_u32_e32 v2, s36, v183
	ds_read_b128 v[160:163], v2
	ds_read_b128 v[164:167], v2 offset:1024
	ds_read_b128 v[168:171], v2 offset:2048
	ds_read_b128 v[172:175], v2 offset:3072
	s_add_u32 s40, s40, s30
	s_addc_u32 s41, s41, s31
	v_lshl_add_u64 v[4:5], s[40:41], 0, v[144:145]
	v_lshl_add_u64 v[4:5], v[4:5], 0, s[86:87]
	s_add_i32 m0, s46, 0xc000
	ds_read_b128 v[176:179], v186
	ds_read_b128 v[188:191], v186 offset:1024
	ds_read_b128 v[192:195], v186 offset:2048
	ds_read_b128 v[196:199], v186 offset:3072
	ds_read_b128 v[200:203], v186 offset:4096
	ds_read_b128 v[214:217], v186 offset:5120
	ds_read_b128 v[218:221], v186 offset:6144
	ds_read_b128 v[222:225], v186 offset:7168
	global_load_lds_dwordx4 v[4:5], off
	v_lshl_add_u64 v[4:5], s[40:41], 0, v[140:141]
	v_lshl_add_u64 v[4:5], v[4:5], 0, s[86:87]
	s_add_i32 m0, s46, 0xe000
	s_nop 0
	global_load_lds_dwordx4 v[4:5], off
	s_waitcnt vmcnt(8)
	s_waitcnt lgkmcnt(0)
	s_setprio 1
	s_barrier
	v_mfma_f32_16x16x32_bf16 v[130:133], v[134:137], v[176:179], v[130:133]
	v_mfma_f32_16x16x32_bf16 v[126:129], v[152:155], v[176:179], v[126:129]
	v_mfma_f32_16x16x32_bf16 v[122:125], v[134:137], v[192:195], v[122:125]
	v_mfma_f32_16x16x32_bf16 v[118:121], v[152:155], v[192:195], v[118:121]
	v_mfma_f32_16x16x32_bf16 v[114:117], v[134:137], v[200:203], v[114:117]
	v_mfma_f32_16x16x32_bf16 v[110:113], v[152:155], v[200:203], v[110:113]
	v_mfma_f32_16x16x32_bf16 v[106:109], v[134:137], v[218:221], v[106:109]
	v_mfma_f32_16x16x32_bf16 v[102:105], v[152:155], v[218:221], v[102:105]
	v_mfma_f32_16x16x32_bf16 v[130:133], v[148:151], v[188:191], v[130:133]
	v_mfma_f32_16x16x32_bf16 v[126:129], v[156:159], v[188:191], v[126:129]
	v_mfma_f32_16x16x32_bf16 v[122:125], v[148:151], v[196:199], v[122:125]
	v_mfma_f32_16x16x32_bf16 v[118:121], v[156:159], v[196:199], v[118:121]
	v_mfma_f32_16x16x32_bf16 v[114:117], v[148:151], v[214:217], v[114:117]
	v_mfma_f32_16x16x32_bf16 v[110:113], v[156:159], v[214:217], v[110:113]
	v_mfma_f32_16x16x32_bf16 v[106:109], v[148:151], v[222:225], v[106:109]
	v_mfma_f32_16x16x32_bf16 v[102:105], v[156:159], v[222:225], v[102:105]
	v_mfma_f32_16x16x32_bf16 v[98:101], v[160:163], v[176:179], v[98:101]
	v_mfma_f32_16x16x32_bf16 v[94:97], v[168:171], v[176:179], v[94:97]
	v_mfma_f32_16x16x32_bf16 v[90:93], v[160:163], v[192:195], v[90:93]
	v_mfma_f32_16x16x32_bf16 v[86:89], v[168:171], v[192:195], v[86:89]
	v_mfma_f32_16x16x32_bf16 v[82:85], v[160:163], v[200:203], v[82:85]
	v_mfma_f32_16x16x32_bf16 v[78:81], v[168:171], v[200:203], v[78:81]
	v_mfma_f32_16x16x32_bf16 v[74:77], v[160:163], v[218:221], v[74:77]
	v_mfma_f32_16x16x32_bf16 v[70:73], v[168:171], v[218:221], v[70:73]
	v_mfma_f32_16x16x32_bf16 v[98:101], v[164:167], v[188:191], v[98:101]
	v_mfma_f32_16x16x32_bf16 v[94:97], v[172:175], v[188:191], v[94:97]
	v_mfma_f32_16x16x32_bf16 v[90:93], v[164:167], v[196:199], v[90:93]
	v_mfma_f32_16x16x32_bf16 v[86:89], v[172:175], v[196:199], v[86:89]
	v_mfma_f32_16x16x32_bf16 v[82:85], v[164:167], v[214:217], v[82:85]
	v_mfma_f32_16x16x32_bf16 v[78:81], v[172:175], v[214:217], v[78:81]
	v_mfma_f32_16x16x32_bf16 v[74:77], v[164:167], v[222:225], v[74:77]
	v_mfma_f32_16x16x32_bf16 v[70:73], v[172:175], v[222:225], v[70:73]
	s_barrier
	s_setprio 0
	s_add_i32 s40, vcc_hi, s44
	v_lshl_add_u64 v[180:181], s[26:27], 0, v[142:143]
	s_mov_b32 m0, s40
	ds_read_b128 v[176:179], v186 offset:16384
	ds_read_b128 v[188:191], v186 offset:17408
	ds_read_b128 v[192:195], v186 offset:18432
	ds_read_b128 v[196:199], v186 offset:19456
	ds_read_b128 v[200:203], v186 offset:20480
	ds_read_b128 v[214:217], v186 offset:21504
	ds_read_b128 v[218:221], v186 offset:22528
	ds_read_b128 v[222:225], v186 offset:23552
	global_load_lds_dwordx4 v142, s[26:27]
	s_add_i32 m0, s40, 0x2000
	v_lshl_add_u64 v[204:205], s[26:27], 0, v[138:139]
	s_add_u32 s26, s26, s30
	s_addc_u32 s27, s27, s31
	s_add_i32 s36, s36, s44
	global_load_lds_dwordx4 v[204:205], off
	v_lshl_add_u64 v[206:207], s[26:27], 0, v[142:143]
	s_mov_b32 m0, s36
	v_lshl_add_u64 v[208:209], s[26:27], 0, v[138:139]
	global_load_lds_dwordx4 v142, s[26:27]
	s_add_i32 m0, s36, 0x2000
	v_lshl_add_u64 v[226:227], s[0:1], 0, v[144:145]
	global_load_lds_dwordx4 v138, s[26:27]
	s_mov_b32 m0, s46
	v_lshl_add_u64 v[228:229], s[0:1], 0, v[140:141]
	global_load_lds_dwordx4 v144, s[0:1]
	s_mov_b32 m0, s47
	s_nop 0
	global_load_lds_dwordx4 v140, s[0:1]
	s_waitcnt vmcnt(8)
	s_waitcnt lgkmcnt(0)
	s_setprio 1
	s_barrier
; #define PG8_LDX(b) do { if constexpr (XR) { _Pragma("unroll") for (int k = 0; k < 2; ++k) Ax_[k] = *(const PG8_LAS bf16x8*)(lds + XR_OFF + (b) * 2048 + aoffx + k * 1024); } } while (0)
; #define PG8_MMAX() do { if constexpr (XR) { if (hasx) { __builtin_amdgcn_s_setprio(1); if (wr == 0) PG8_MMAX_(B0); else PG8_MMAX_(B1); __builtin_amdgcn_s_setprio(0); } } } while (0)
; #define PG8_WAIT_LOOP() do { if constexpr (XR) PG8_WAIT_V(9); else PG8_WAIT_V(8); } while (0)
; #define PG8_STAGE(bufoff, gbase, voff) do { _Pragma("unroll") for (int _i = 0; _i < 2; ++_i) \
;         __builtin_amdgcn_global_load_lds((const unsigned*)((const char*)(gbase) + (voff)[_i]), (PG8_LAS unsigned*)(lds + (bufoff) + ldsw + _i * 8192), 16, 0, 0); } while (0)
; #define PG8_LDA(dst, b, h) do { _Pragma("unroll") for (int m = 0; m < 4; ++m) _Pragma("unroll") for (int k = 0; k < 2; ++k) dst[m][k] = *(const PG8_LAS bf16x8*)(lds + PG8_SA(b, h) + aoff + m * 2048 + k * 1024); } while (0)
; #define PG8_LDB(dst, b, h) do { _Pragma("unroll") for (int n = 0; n < 2; ++n) _Pragma("unroll") for (int k = 0; k < 2; ++k) dst[n][k] = *(const PG8_LAS bf16x8*)(lds + PG8_SB(b, h) + boff + n * 2048 + k * 1024); } while (0)
; #define PG8_MMA(ai, bj, At, Bt) do { __builtin_amdgcn_s_setprio(1); _Pragma("unroll") for (int m = 0; m < 4; ++m) _Pragma("unroll") for (int n = 0; n < 2; ++n) _Pragma("unroll") for (int k = 0; k < 2; ++k) \
;         acc[ai][bj][m][n] = __builtin_amdgcn_mfma_f32_16x16x32_bf16(Bt[n][k], At[m][k], acc[ai][bj][m][n], 0, 0, 0); __builtin_amdgcn_s_setprio(0); } while (0)
; #define PG8_WAIT_L(n) asm volatile("s_waitcnt lgkmcnt(" #n ")" ::: "memory")
; #define PG8_BAR __builtin_amdgcn_s_barrier()
; #define PG8_SCHED __builtin_amdgcn_sched_barrier(0)
; template <class Epi, class Sched, bool ALIGN_EPI = false, bool SP2 = false, bool DRAIN = true, bool XR = false>
; __device__ __forceinline__ void gemm_phase(PG8_LAS unsigned char* lds, const Gemm g, const Sched& S, const Epi& E) {
;     ...
;             PG8_WAIT_LOOP(); PG8_WAIT_L(0); PG8_BAR; PG8_MMA(1, 0, At, B0); PG8_MMA(1, 1, At, B1); PG8_BAR; PG8_SCHED;
;             PG8_LDB(B0, 1, 0); PG8_LDB(B1, 1, 1); PG8_SCHED; PG8_LDA(At, 1, 0); PG8_LDX(1); PG8_STAGE(PG8_SA(0, 1), a2 + hstepA, voffA);
;             PG8_WAIT_LOOP(); PG8_WAIT_L(0); PG8_BAR; PG8_MMA(0, 0, At, B0); PG8_MMA(0, 1, At, B1); PG8_MMAX(); PG8_BAR; PG8_SCHED;
	v_mfma_f32_16x16x32_bf16 v[66:69], v[134:137], v[176:179], v[66:69]
	v_mfma_f32_16x16x32_bf16 v[62:65], v[152:155], v[176:179], v[62:65]
	v_mfma_f32_16x16x32_bf16 v[58:61], v[134:137], v[192:195], v[58:61]
	v_mfma_f32_16x16x32_bf16 v[54:57], v[152:155], v[192:195], v[54:57]
	v_mfma_f32_16x16x32_bf16 v[50:53], v[134:137], v[200:203], v[50:53]
	v_mfma_f32_16x16x32_bf16 v[46:49], v[152:155], v[200:203], v[46:49]
	v_mfma_f32_16x16x32_bf16 v[42:45], v[134:137], v[218:221], v[42:45]
	v_mfma_f32_16x16x32_bf16 v[38:41], v[152:155], v[218:221], v[38:41]
	v_mfma_f32_16x16x32_bf16 v[66:69], v[148:151], v[188:191], v[66:69]
	v_mfma_f32_16x16x32_bf16 v[62:65], v[156:159], v[188:191], v[62:65]
	v_mfma_f32_16x16x32_bf16 v[58:61], v[148:151], v[196:199], v[58:61]
	v_mfma_f32_16x16x32_bf16 v[54:57], v[156:159], v[196:199], v[54:57]
	v_mfma_f32_16x16x32_bf16 v[50:53], v[148:151], v[214:217], v[50:53]
	v_mfma_f32_16x16x32_bf16 v[46:49], v[156:159], v[214:217], v[46:49]
	v_mfma_f32_16x16x32_bf16 v[42:45], v[148:151], v[222:225], v[42:45]
	v_mfma_f32_16x16x32_bf16 v[38:41], v[156:159], v[222:225], v[38:41]
	v_mfma_f32_16x16x32_bf16 v[34:37], v[160:163], v[176:179], v[34:37]
	v_mfma_f32_16x16x32_bf16 v[30:33], v[168:171], v[176:179], v[30:33]
	v_mfma_f32_16x16x32_bf16 v[26:29], v[160:163], v[192:195], v[26:29]
	v_mfma_f32_16x16x32_bf16 v[22:25], v[168:171], v[192:195], v[22:25]
	v_mfma_f32_16x16x32_bf16 v[18:21], v[160:163], v[200:203], v[18:21]
	v_mfma_f32_16x16x32_bf16 v[14:17], v[168:171], v[200:203], v[14:17]
	v_mfma_f32_16x16x32_bf16 v[10:13], v[160:163], v[218:221], v[10:13]
	v_mfma_f32_16x16x32_bf16 v[4:7], v[168:171], v[218:221], v[6:9]
	v_mfma_f32_16x16x32_bf16 v[34:37], v[164:167], v[188:191], v[34:37]
	v_mfma_f32_16x16x32_bf16 v[30:33], v[172:175], v[188:191], v[30:33]
	v_mfma_f32_16x16x32_bf16 v[26:29], v[164:167], v[196:199], v[26:29]
	v_mfma_f32_16x16x32_bf16 v[22:25], v[172:175], v[196:199], v[22:25]
	v_mfma_f32_16x16x32_bf16 v[18:21], v[164:167], v[214:217], v[18:21]
	v_mfma_f32_16x16x32_bf16 v[14:17], v[172:175], v[214:217], v[14:17]
	v_mfma_f32_16x16x32_bf16 v[10:13], v[164:167], v[222:225], v[10:13]
	v_mfma_f32_16x16x32_bf16 v[4:7], v[172:175], v[222:225], v[4:7]
	s_barrier
	s_setprio 0
	s_add_i32 s26, 0, 0x18000
	v_add_u32_e32 v2, s26, v183
	s_add_i32 s27, 0, 0x1c000
	ds_read_b128 v[134:137], v2
	ds_read_b128 v[148:151], v2 offset:1024
	ds_read_b128 v[152:155], v2 offset:2048
	ds_read_b128 v[156:159], v2 offset:3072
	v_add_u32_e32 v2, s27, v183
	ds_read_b128 v[160:163], v2
	ds_read_b128 v[164:167], v2 offset:1024
	ds_read_b128 v[168:171], v2 offset:2048
	ds_read_b128 v[172:175], v2 offset:3072
	s_add_u32 s0, s0, s30
	s_addc_u32 s1, s1, s31
	s_mov_b32 m0, s48
	ds_read_b128 v[176:179], v186 offset:32768
	ds_read_b128 v[188:191], v186 offset:33792
	ds_read_b128 v[192:195], v186 offset:34816
	ds_read_b128 v[196:199], v186 offset:35840
	ds_read_b128 v[200:203], v186 offset:36864
	ds_read_b128 v[214:217], v186 offset:37888
	ds_read_b128 v[218:221], v186 offset:38912
	ds_read_b128 v[222:225], v186 offset:39936
	global_load_lds_dwordx4 v144, s[0:1]
	s_mov_b32 m0, s49
	s_nop 0
	global_load_lds_dwordx4 v140, s[0:1]
	s_waitcnt vmcnt(8)
	s_waitcnt lgkmcnt(0)
	s_setprio 1
	s_barrier
	v_mfma_f32_16x16x32_bf16 v[130:133], v[134:137], v[176:179], v[130:133]
	v_mfma_f32_16x16x32_bf16 v[126:129], v[152:155], v[176:179], v[126:129]
	v_mfma_f32_16x16x32_bf16 v[122:125], v[134:137], v[192:195], v[122:125]
	v_mfma_f32_16x16x32_bf16 v[118:121], v[152:155], v[192:195], v[118:121]
	v_mfma_f32_16x16x32_bf16 v[114:117], v[134:137], v[200:203], v[114:117]
	v_mfma_f32_16x16x32_bf16 v[110:113], v[152:155], v[200:203], v[110:113]
	v_mfma_f32_16x16x32_bf16 v[106:109], v[134:137], v[218:221], v[106:109]
	v_mfma_f32_16x16x32_bf16 v[102:105], v[152:155], v[218:221], v[102:105]
	v_mfma_f32_16x16x32_bf16 v[130:133], v[148:151], v[188:191], v[130:133]
	v_mfma_f32_16x16x32_bf16 v[126:129], v[156:159], v[188:191], v[126:129]
	v_mfma_f32_16x16x32_bf16 v[122:125], v[148:151], v[196:199], v[122:125]
	v_mfma_f32_16x16x32_bf16 v[118:121], v[156:159], v[196:199], v[118:121]
	v_mfma_f32_16x16x32_bf16 v[114:117], v[148:151], v[214:217], v[114:117]
	v_mfma_f32_16x16x32_bf16 v[110:113], v[156:159], v[214:217], v[110:113]
	v_mfma_f32_16x16x32_bf16 v[106:109], v[148:151], v[222:225], v[106:109]
	v_mfma_f32_16x16x32_bf16 v[102:105], v[156:159], v[222:225], v[102:105]
	v_mfma_f32_16x16x32_bf16 v[98:101], v[160:163], v[176:179], v[98:101]
	v_mfma_f32_16x16x32_bf16 v[94:97], v[168:171], v[176:179], v[94:97]
	v_mfma_f32_16x16x32_bf16 v[90:93], v[160:163], v[192:195], v[90:93]
	v_mfma_f32_16x16x32_bf16 v[86:89], v[168:171], v[192:195], v[86:89]
	v_mfma_f32_16x16x32_bf16 v[82:85], v[160:163], v[200:203], v[82:85]
	v_mfma_f32_16x16x32_bf16 v[78:81], v[168:171], v[200:203], v[78:81]
	v_mfma_f32_16x16x32_bf16 v[74:77], v[160:163], v[218:221], v[74:77]
	v_mfma_f32_16x16x32_bf16 v[70:73], v[168:171], v[218:221], v[70:73]
	v_mfma_f32_16x16x32_bf16 v[98:101], v[164:167], v[188:191], v[98:101]
	v_mfma_f32_16x16x32_bf16 v[94:97], v[172:175], v[188:191], v[94:97]
	v_mfma_f32_16x16x32_bf16 v[90:93], v[164:167], v[196:199], v[90:93]
	v_mfma_f32_16x16x32_bf16 v[86:89], v[172:175], v[196:199], v[86:89]
	v_mfma_f32_16x16x32_bf16 v[82:85], v[164:167], v[214:217], v[82:85]
	v_mfma_f32_16x16x32_bf16 v[78:81], v[172:175], v[214:217], v[78:81]
	v_mfma_f32_16x16x32_bf16 v[74:77], v[164:167], v[222:225], v[74:77]
	v_mfma_f32_16x16x32_bf16 v[70:73], v[172:175], v[222:225], v[70:73]
	s_barrier
; #define PG8_STAGEX(b, gbase) do { if constexpr (XR) { if (lane < 16) __builtin_amdgcn_global_load_lds((const unsigned*)((const char*)(gbase) + voffX), (PG8_LAS unsigned*)(lds + XR_OFF + (b) * 2048 + wid * 256), 16, 0, 0); } } while (0)
; #define PG8_WAIT_LOOP() do { if constexpr (XR) PG8_WAIT_V(9); else PG8_WAIT_V(8); } while (0)
; #define PG8_STAGE(bufoff, gbase, voff) do { _Pragma("unroll") for (int _i = 0; _i < 2; ++_i) \
;         __builtin_amdgcn_global_load_lds((const unsigned*)((const char*)(gbase) + (voff)[_i]), (PG8_LAS unsigned*)(lds + (bufoff) + ldsw + _i * 8192), 16, 0, 0); } while (0)
; #define PG8_LDA(dst, b, h) do { _Pragma("unroll") for (int m = 0; m < 4; ++m) _Pragma("unroll") for (int k = 0; k < 2; ++k) dst[m][k] = *(const PG8_LAS bf16x8*)(lds + PG8_SA(b, h) + aoff + m * 2048 + k * 1024); } while (0)
; #define PG8_MMA(ai, bj, At, Bt) do { __builtin_amdgcn_s_setprio(1); _Pragma("unroll") for (int m = 0; m < 4; ++m) _Pragma("unroll") for (int n = 0; n < 2; ++n) _Pragma("unroll") for (int k = 0; k < 2; ++k) \
;         acc[ai][bj][m][n] = __builtin_amdgcn_mfma_f32_16x16x32_bf16(Bt[n][k], At[m][k], acc[ai][bj][m][n], 0, 0, 0); __builtin_amdgcn_s_setprio(0); } while (0)
; #define PG8_WAIT_L(n) asm volatile("s_waitcnt lgkmcnt(" #n ")" ::: "memory")
; #define PG8_BAR __builtin_amdgcn_s_barrier()
; #define PG8_SCHED __builtin_amdgcn_sched_barrier(0)
; template <class Epi, class Sched, bool ALIGN_EPI = false, bool SP2 = false, bool DRAIN = true, bool XR = false>
; __device__ __forceinline__ void gemm_phase(PG8_LAS unsigned char* lds, const Gemm g, const Sched& S, const Epi& E) {
;     ...
;         for (int t = 0; t < nt; t += 2) {
;     ...
;             PG8_LDA(At, 1, 1); PG8_STAGE(PG8_SB(1, 0), b3, voffB); PG8_STAGE(PG8_SB(1, 1), b3 + hstep, voffB); PG8_STAGE(PG8_SA(1, 0), a3, voffA); PG8_STAGEX(1, x3);
;             PG8_WAIT_LOOP(); PG8_WAIT_L(0); PG8_BAR; PG8_MMA(1, 0, At, B0); PG8_MMA(1, 1, At, B1); PG8_BAR; PG8_SCHED;
	s_setprio 0
	s_add_i32 s0, s26, s44
	v_lshl_add_u64 v[8:9], v[180:181], 0, s[86:87]
	s_mov_b32 m0, s0
	ds_read_b128 v[176:179], v186 offset:49152
	ds_read_b128 v[188:191], v186 offset:50176
	ds_read_b128 v[192:195], v186 offset:51200
	ds_read_b128 v[196:199], v186 offset:52224
	ds_read_b128 v[200:203], v186 offset:53248
	ds_read_b128 v[214:217], v186 offset:54272
	ds_read_b128 v[218:221], v186 offset:55296
	ds_read_b128 v[222:225], v186 offset:56320
	global_load_lds_dwordx4 v[8:9], off
	v_lshl_add_u64 v[8:9], v[204:205], 0, s[86:87]
	s_add_i32 m0, s0, 0x2000
	s_add_i32 s0, s27, s44
	global_load_lds_dwordx4 v[8:9], off
	v_lshl_add_u64 v[8:9], v[206:207], 0, s[86:87]
	s_mov_b32 m0, s0
	s_nop 0
	global_load_lds_dwordx4 v[8:9], off
	v_lshl_add_u64 v[8:9], v[208:209], 0, s[86:87]
	s_add_i32 m0, s0, 0x2000
	s_nop 0
	global_load_lds_dwordx4 v[8:9], off
	v_lshl_add_u64 v[8:9], v[226:227], 0, s[86:87]
	s_mov_b32 m0, s67
	s_nop 0
	global_load_lds_dwordx4 v[8:9], off
	v_lshl_add_u64 v[8:9], v[228:229], 0, s[86:87]
	s_mov_b32 m0, s71
	s_nop 0
	global_load_lds_dwordx4 v[8:9], off
	s_waitcnt vmcnt(8)
	s_waitcnt lgkmcnt(0)
	s_setprio 1
	s_barrier
	v_mfma_f32_16x16x32_bf16 v[66:69], v[134:137], v[176:179], v[66:69]
	v_mfma_f32_16x16x32_bf16 v[62:65], v[152:155], v[176:179], v[62:65]
	v_mfma_f32_16x16x32_bf16 v[58:61], v[134:137], v[192:195], v[58:61]
	v_mfma_f32_16x16x32_bf16 v[54:57], v[152:155], v[192:195], v[54:57]
	v_mfma_f32_16x16x32_bf16 v[50:53], v[134:137], v[200:203], v[50:53]
	v_mfma_f32_16x16x32_bf16 v[46:49], v[152:155], v[200:203], v[46:49]
	v_mfma_f32_16x16x32_bf16 v[42:45], v[134:137], v[218:221], v[42:45]
	v_mfma_f32_16x16x32_bf16 v[38:41], v[152:155], v[218:221], v[38:41]
	v_mfma_f32_16x16x32_bf16 v[66:69], v[148:151], v[188:191], v[66:69]
	v_mfma_f32_16x16x32_bf16 v[62:65], v[156:159], v[188:191], v[62:65]
	v_mfma_f32_16x16x32_bf16 v[58:61], v[148:151], v[196:199], v[58:61]
	v_mfma_f32_16x16x32_bf16 v[54:57], v[156:159], v[196:199], v[54:57]
	v_mfma_f32_16x16x32_bf16 v[50:53], v[148:151], v[214:217], v[50:53]
	v_mfma_f32_16x16x32_bf16 v[46:49], v[156:159], v[214:217], v[46:49]
	v_mfma_f32_16x16x32_bf16 v[42:45], v[148:151], v[222:225], v[42:45]
	v_mfma_f32_16x16x32_bf16 v[38:41], v[156:159], v[222:225], v[38:41]
	v_mfma_f32_16x16x32_bf16 v[34:37], v[160:163], v[176:179], v[34:37]
	v_mfma_f32_16x16x32_bf16 v[30:33], v[168:171], v[176:179], v[30:33]
	v_mfma_f32_16x16x32_bf16 v[26:29], v[160:163], v[192:195], v[26:29]
	v_mfma_f32_16x16x32_bf16 v[22:25], v[168:171], v[192:195], v[22:25]
	v_mfma_f32_16x16x32_bf16 v[18:21], v[160:163], v[200:203], v[18:21]
	v_mfma_f32_16x16x32_bf16 v[14:17], v[168:171], v[200:203], v[14:17]
	v_mfma_f32_16x16x32_bf16 v[8:11], v[160:163], v[218:221], v[10:13]
	v_mfma_f32_16x16x32_bf16 v[4:7], v[168:171], v[218:221], v[4:7]
	v_mfma_f32_16x16x32_bf16 v[34:37], v[164:167], v[188:191], v[34:37]
	v_mfma_f32_16x16x32_bf16 v[30:33], v[172:175], v[188:191], v[30:33]
	v_mfma_f32_16x16x32_bf16 v[26:29], v[164:167], v[196:199], v[26:29]
	v_mfma_f32_16x16x32_bf16 v[22:25], v[172:175], v[196:199], v[22:25]
	v_mfma_f32_16x16x32_bf16 v[18:21], v[164:167], v[214:217], v[18:21]
	v_mfma_f32_16x16x32_bf16 v[14:17], v[172:175], v[214:217], v[14:17]
	v_mfma_f32_16x16x32_bf16 v[10:13], v[164:167], v[222:225], v[8:11]
	v_mfma_f32_16x16x32_bf16 v[6:9], v[172:175], v[222:225], v[4:7]
	s_barrier
	s_setprio 0
	s_add_i32 s25, s25, 2
	s_cmp_ge_i32 s25, s89
	s_cbranch_scc0 .LBB0_325

; #define PG8_STAGEX(b, gbase) do { if constexpr (XR) { if (lane < 16) __builtin_amdgcn_global_load_lds((const unsigned*)((const char*)(gbase) + voffX), (PG8_LAS unsigned*)(lds + XR_OFF + (b) * 2048 + wid * 256), 16, 0, 0); } } while (0)
; #define PG8_LDX(b) do { if constexpr (XR) { _Pragma("unroll") for (int k = 0; k < 2; ++k) Ax_[k] = *(const PG8_LAS bf16x8*)(lds + XR_OFF + (b) * 2048 + aoffx + k * 1024); } } while (0)
; #define PG8_MMAX() do { if constexpr (XR) { if (hasx) { __builtin_amdgcn_s_setprio(1); if (wr == 0) PG8_MMAX_(B0); else PG8_MMAX_(B1); __builtin_amdgcn_s_setprio(0); } } } while (0)
; #define PG8_WAIT_LOOP() do { if constexpr (XR) PG8_WAIT_V(9); else PG8_WAIT_V(8); } while (0)
; #define PG8_STAGE(bufoff, gbase, voff) do { _Pragma("unroll") for (int _i = 0; _i < 2; ++_i) \
;         __builtin_amdgcn_global_load_lds((const unsigned*)((const char*)(gbase) + (voff)[_i]), (PG8_LAS unsigned*)(lds + (bufoff) + ldsw + _i * 8192), 16, 0, 0); } while (0)
; #define PG8_WAIT_L(n) asm volatile("s_waitcnt lgkmcnt(" #n ")" ::: "memory")
; #define PG8_BAR __builtin_amdgcn_s_barrier()
; template <class Epi, class Sched, bool ALIGN_EPI = false, bool SP2 = false, bool DRAIN = true, bool XR = false>
; __device__ __forceinline__ void gemm_phase(PG8_LAS unsigned char* lds, const Gemm g, const Sched& S, const Epi& E) {
;     ...
;             const char* a1 = cA + PG8_KOA(t) + kstep;
;             const char* a2 = last ? nA + ka0 : cA + PG8_KOA(t + 2); const char* b2 = last ? nB + kb0 : cB + PG8_KOB(t + 2);
;             const char* x2 = XR ? (last ? nX + kx0 : cX + PG8_KOX(t + 2)) : nullptr; const char* x3 = XR ? x2 + kstep : nullptr;
;             const char* a3 = a2 + kstep; const char* b3 = b2 + kstep;
;             if (last && has_next) S.a_ready(nxt);
;             if constexpr (SP2) {
;             PG8_LDB(B0, 0, 0); PG8_LDB(B1, 0, 1); PG8_SCHED; PG8_LDA(At, 0, 0); PG8_LDX(0); PG8_STAGE(PG8_SA(1, 1), a1 + hstepA, voffA);
;             PG8_WAIT_LOOP(); PG8_WAIT_L(0); PG8_BAR; PG8_MMA(0, 0, At, B0); PG8_MMA(0, 1, At, B1); PG8_MMAX(); PG8_BAR; PG8_SCHED;
;             PG8_LDA(At, 0, 1); PG8_STAGE(PG8_SB(0, 0), b2, voffB); PG8_STAGE(PG8_SB(0, 1), b2 + hstep, voffB); PG8_STAGE(PG8_SA(0, 0), a2, voffA); PG8_STAGEX(0, x2);
;             PG8_WAIT_LOOP(); PG8_WAIT_L(0); PG8_BAR; PG8_MMA(1, 0, At, B0); PG8_MMA(1, 1, At, B1); PG8_BAR; PG8_SCHED;
.LBB0_1020:
	s_add_i32 s4, s72, -2
	s_and_b32 s73, s4, s61
	s_lshr_b32 s84, s73, 2
	s_lshl_b32 s36, s73, 7
	s_lshl_b64 s[4:5], s[84:85], 9
	s_and_b32 s36, s36, 0x100
	s_add_u32 s4, s44, s4
	s_addc_u32 s5, s45, s5
	s_add_u32 s73, s4, s36
	s_addc_u32 s77, s5, 0
	s_and_b32 s4, s72, s61
	s_lshr_b32 s84, s4, 2
	s_lshl_b32 s5, s4, 7
	s_lshl_b64 s[74:75], s[84:85], 9
	s_and_b32 s5, s5, 0x100
	s_add_u32 s36, s44, s74
	s_addc_u32 s74, s45, s75
	s_add_u32 s36, s36, s5
	s_mov_b32 s5, s85
	s_addc_u32 s74, s74, 0
	s_lshl_b64 s[4:5], s[4:5], 7
	s_add_u32 s76, s42, s4
	s_addc_u32 s75, s43, s5
	s_add_i32 s78, 0, 0x10000
	s_cmp_eq_u32 s60, s72
	s_cselect_b32 s5, s35, s74
	s_cselect_b32 s4, s34, s36
	s_cselect_b32 s75, s41, s75
	s_cselect_b32 s74, s40, s76
	s_add_i32 s36, 0, 0x14000
	v_add_u32_e32 v104, s78, v176
	v_add_u32_e32 v168, s36, v176
	ds_read_b128 v[84:87], v104
	ds_read_b128 v[88:91], v104 offset:1024
	ds_read_b128 v[96:99], v104 offset:2048
	ds_read_b128 v[104:107], v104 offset:3072
	ds_read_b128 v[148:151], v168
	ds_read_b128 v[152:155], v168 offset:1024
	ds_read_b128 v[156:159], v168 offset:2048
	ds_read_b128 v[168:171], v168 offset:3072
	s_add_u32 s76, s73, s18
	s_addc_u32 s77, s77, s19
	v_lshl_add_u64 v[204:205], s[76:77], 0, v[162:163]
	v_lshl_add_u64 v[204:205], v[204:205], 0, s[86:87]
	s_add_i32 m0, s54, 0xc000
	ds_read_b128 v[172:175], v178
	ds_read_b128 v[180:183], v178 offset:1024
	ds_read_b128 v[184:187], v178 offset:2048
	ds_read_b128 v[188:191], v178 offset:3072
	ds_read_b128 v[192:195], v178 offset:4096
	ds_read_b128 v[196:199], v178 offset:5120
	ds_read_b128 v[200:203], v178 offset:6144
	ds_read_b128 v[214:217], v178 offset:7168
	global_load_lds_dwordx4 v[204:205], off
	v_lshl_add_u64 v[204:205], s[76:77], 0, v[164:165]
	v_lshl_add_u64 v[204:205], v[204:205], 0, s[86:87]
	s_add_i32 m0, s54, 0xe000
	s_nop 0
	global_load_lds_dwordx4 v[204:205], off
	s_waitcnt vmcnt(8)
	s_waitcnt lgkmcnt(0)
	s_setprio 1
	s_barrier
	v_mfma_f32_16x16x32_bf16 v[144:147], v[84:87], v[172:175], v[144:147]
	v_mfma_f32_16x16x32_bf16 v[140:143], v[96:99], v[172:175], v[140:143]
	v_mfma_f32_16x16x32_bf16 v[128:131], v[84:87], v[184:187], v[128:131]
	v_mfma_f32_16x16x32_bf16 v[124:127], v[96:99], v[184:187], v[124:127]
	v_mfma_f32_16x16x32_bf16 v[112:115], v[84:87], v[192:195], v[112:115]
	v_mfma_f32_16x16x32_bf16 v[108:111], v[96:99], v[192:195], v[108:111]
	v_mfma_f32_16x16x32_bf16 v[80:83], v[84:87], v[200:203], v[80:83]
	v_mfma_f32_16x16x32_bf16 v[76:79], v[96:99], v[200:203], v[76:79]
	v_mfma_f32_16x16x32_bf16 v[144:147], v[88:91], v[180:183], v[144:147]
	v_mfma_f32_16x16x32_bf16 v[140:143], v[104:107], v[180:183], v[140:143]
	v_mfma_f32_16x16x32_bf16 v[128:131], v[88:91], v[188:191], v[128:131]
	v_mfma_f32_16x16x32_bf16 v[124:127], v[104:107], v[188:191], v[124:127]
	v_mfma_f32_16x16x32_bf16 v[112:115], v[88:91], v[196:199], v[112:115]
	v_mfma_f32_16x16x32_bf16 v[108:111], v[104:107], v[196:199], v[108:111]
	v_mfma_f32_16x16x32_bf16 v[80:83], v[88:91], v[214:217], v[80:83]
	v_mfma_f32_16x16x32_bf16 v[76:79], v[104:107], v[214:217], v[76:79]
	v_mfma_f32_16x16x32_bf16 v[136:139], v[148:151], v[172:175], v[136:139]
	v_mfma_f32_16x16x32_bf16 v[132:135], v[156:159], v[172:175], v[132:135]
	v_mfma_f32_16x16x32_bf16 v[120:123], v[148:151], v[184:187], v[120:123]
	v_mfma_f32_16x16x32_bf16 v[116:119], v[156:159], v[184:187], v[116:119]
	v_mfma_f32_16x16x32_bf16 v[100:103], v[148:151], v[192:195], v[100:103]
	v_mfma_f32_16x16x32_bf16 v[92:95], v[156:159], v[192:195], v[92:95]
	v_mfma_f32_16x16x32_bf16 v[72:75], v[148:151], v[200:203], v[72:75]
	v_mfma_f32_16x16x32_bf16 v[68:71], v[156:159], v[200:203], v[68:71]
	v_mfma_f32_16x16x32_bf16 v[136:139], v[152:155], v[180:183], v[136:139]
	v_mfma_f32_16x16x32_bf16 v[132:135], v[168:171], v[180:183], v[132:135]
	v_mfma_f32_16x16x32_bf16 v[120:123], v[152:155], v[188:191], v[120:123]
	v_mfma_f32_16x16x32_bf16 v[116:119], v[168:171], v[188:191], v[116:119]
	v_mfma_f32_16x16x32_bf16 v[100:103], v[152:155], v[196:199], v[100:103]
	v_mfma_f32_16x16x32_bf16 v[92:95], v[168:171], v[196:199], v[92:95]
	v_mfma_f32_16x16x32_bf16 v[72:75], v[152:155], v[214:217], v[72:75]
	v_mfma_f32_16x16x32_bf16 v[68:71], v[168:171], v[214:217], v[68:71]
	s_barrier
	s_setprio 0
	s_add_i32 s73, s78, s51
	v_lshl_add_u64 v[204:205], s[74:75], 0, v[2:3]
	s_mov_b32 m0, s73
	ds_read_b128 v[172:175], v178 offset:16384
	ds_read_b128 v[180:183], v178 offset:17408
	ds_read_b128 v[184:187], v178 offset:18432
	ds_read_b128 v[188:191], v178 offset:19456
	ds_read_b128 v[192:195], v178 offset:20480
	ds_read_b128 v[196:199], v178 offset:21504
	ds_read_b128 v[200:203], v178 offset:22528
	ds_read_b128 v[214:217], v178 offset:23552
	global_load_lds_dwordx4 v2, s[74:75]
	s_add_i32 m0, s73, 0x2000
	v_lshl_add_u64 v[206:207], s[74:75], 0, v[166:167]
	s_add_u32 s74, s74, s18
	s_addc_u32 s75, s75, s19
	s_add_i32 s36, s36, s51
	global_load_lds_dwordx4 v[206:207], off
	v_lshl_add_u64 v[208:209], s[74:75], 0, v[2:3]
	s_mov_b32 m0, s36
	v_lshl_add_u64 v[212:213], s[74:75], 0, v[166:167]
	global_load_lds_dwordx4 v2, s[74:75]
	s_add_i32 m0, s36, 0x2000
	v_lshl_add_u64 v[218:219], s[4:5], 0, v[162:163]
	global_load_lds_dwordx4 v166, s[74:75]
	s_mov_b32 m0, s54
	v_lshl_add_u64 v[220:221], s[4:5], 0, v[164:165]
	global_load_lds_dwordx4 v162, s[4:5]
	s_mov_b32 m0, s55
	s_nop 0
	global_load_lds_dwordx4 v164, s[4:5]
	s_waitcnt vmcnt(8)
	s_waitcnt lgkmcnt(0)
	s_setprio 1
	s_barrier
; #define PG8_LDX(b) do { if constexpr (XR) { _Pragma("unroll") for (int k = 0; k < 2; ++k) Ax_[k] = *(const PG8_LAS bf16x8*)(lds + XR_OFF + (b) * 2048 + aoffx + k * 1024); } } while (0)
; #define PG8_MMAX() do { if constexpr (XR) { if (hasx) { __builtin_amdgcn_s_setprio(1); if (wr == 0) PG8_MMAX_(B0); else PG8_MMAX_(B1); __builtin_amdgcn_s_setprio(0); } } } while (0)
; #define PG8_WAIT_LOOP() do { if constexpr (XR) PG8_WAIT_V(9); else PG8_WAIT_V(8); } while (0)
; #define PG8_STAGE(bufoff, gbase, voff) do { _Pragma("unroll") for (int _i = 0; _i < 2; ++_i) \
;         __builtin_amdgcn_global_load_lds((const unsigned*)((const char*)(gbase) + (voff)[_i]), (PG8_LAS unsigned*)(lds + (bufoff) + ldsw + _i * 8192), 16, 0, 0); } while (0)
; #define PG8_LDA(dst, b, h) do { _Pragma("unroll") for (int m = 0; m < 4; ++m) _Pragma("unroll") for (int k = 0; k < 2; ++k) dst[m][k] = *(const PG8_LAS bf16x8*)(lds + PG8_SA(b, h) + aoff + m * 2048 + k * 1024); } while (0)
; #define PG8_LDB(dst, b, h) do { _Pragma("unroll") for (int n = 0; n < 2; ++n) _Pragma("unroll") for (int k = 0; k < 2; ++k) dst[n][k] = *(const PG8_LAS bf16x8*)(lds + PG8_SB(b, h) + boff + n * 2048 + k * 1024); } while (0)
; #define PG8_MMA(ai, bj, At, Bt) do { __builtin_amdgcn_s_setprio(1); _Pragma("unroll") for (int m = 0; m < 4; ++m) _Pragma("unroll") for (int n = 0; n < 2; ++n) _Pragma("unroll") for (int k = 0; k < 2; ++k) \
;         acc[ai][bj][m][n] = __builtin_amdgcn_mfma_f32_16x16x32_bf16(Bt[n][k], At[m][k], acc[ai][bj][m][n], 0, 0, 0); __builtin_amdgcn_s_setprio(0); } while (0)
; #define PG8_WAIT_L(n) asm volatile("s_waitcnt lgkmcnt(" #n ")" ::: "memory")
; #define PG8_BAR __builtin_amdgcn_s_barrier()
; #define PG8_SCHED __builtin_amdgcn_sched_barrier(0)
; template <class Epi, class Sched, bool ALIGN_EPI = false, bool SP2 = false, bool DRAIN = true, bool XR = false>
; __device__ __forceinline__ void gemm_phase(PG8_LAS unsigned char* lds, const Gemm g, const Sched& S, const Epi& E) {
;     ...
;             PG8_WAIT_LOOP(); PG8_WAIT_L(0); PG8_BAR; PG8_MMA(1, 0, At, B0); PG8_MMA(1, 1, At, B1); PG8_BAR; PG8_SCHED;
;             PG8_LDB(B0, 1, 0); PG8_LDB(B1, 1, 1); PG8_SCHED; PG8_LDA(At, 1, 0); PG8_LDX(1); PG8_STAGE(PG8_SA(0, 1), a2 + hstepA, voffA);
;             PG8_WAIT_LOOP(); PG8_WAIT_L(0); PG8_BAR; PG8_MMA(0, 0, At, B0); PG8_MMA(0, 1, At, B1); PG8_MMAX(); PG8_BAR; PG8_SCHED;
	v_mfma_f32_16x16x32_bf16 v[64:67], v[84:87], v[172:175], v[64:67]
	v_mfma_f32_16x16x32_bf16 v[60:63], v[96:99], v[172:175], v[60:63]
	v_mfma_f32_16x16x32_bf16 v[48:51], v[84:87], v[184:187], v[48:51]
	v_mfma_f32_16x16x32_bf16 v[44:47], v[96:99], v[184:187], v[44:47]
	v_mfma_f32_16x16x32_bf16 v[32:35], v[84:87], v[192:195], v[32:35]
	v_mfma_f32_16x16x32_bf16 v[28:31], v[96:99], v[192:195], v[28:31]
	v_mfma_f32_16x16x32_bf16 v[16:19], v[84:87], v[200:203], v[16:19]
	v_mfma_f32_16x16x32_bf16 v[12:15], v[96:99], v[200:203], v[12:15]
	v_mfma_f32_16x16x32_bf16 v[64:67], v[88:91], v[180:183], v[64:67]
	v_mfma_f32_16x16x32_bf16 v[60:63], v[104:107], v[180:183], v[60:63]
	v_mfma_f32_16x16x32_bf16 v[48:51], v[88:91], v[188:191], v[48:51]
	v_mfma_f32_16x16x32_bf16 v[44:47], v[104:107], v[188:191], v[44:47]
	v_mfma_f32_16x16x32_bf16 v[32:35], v[88:91], v[196:199], v[32:35]
	v_mfma_f32_16x16x32_bf16 v[28:31], v[104:107], v[196:199], v[28:31]
	v_mfma_f32_16x16x32_bf16 v[16:19], v[88:91], v[214:217], v[16:19]
	v_mfma_f32_16x16x32_bf16 v[12:15], v[104:107], v[214:217], v[12:15]
	v_mfma_f32_16x16x32_bf16 v[56:59], v[148:151], v[172:175], v[56:59]
	v_mfma_f32_16x16x32_bf16 v[52:55], v[156:159], v[172:175], v[52:55]
	v_mfma_f32_16x16x32_bf16 v[40:43], v[148:151], v[184:187], v[40:43]
	v_mfma_f32_16x16x32_bf16 v[36:39], v[156:159], v[184:187], v[36:39]
	v_mfma_f32_16x16x32_bf16 v[24:27], v[148:151], v[192:195], v[24:27]
	v_mfma_f32_16x16x32_bf16 v[20:23], v[156:159], v[192:195], v[20:23]
	v_mfma_f32_16x16x32_bf16 v[8:11], v[148:151], v[200:203], v[8:11]
	v_mfma_f32_16x16x32_bf16 v[4:7], v[156:159], v[200:203], v[4:7]
	v_mfma_f32_16x16x32_bf16 v[56:59], v[152:155], v[180:183], v[56:59]
	v_mfma_f32_16x16x32_bf16 v[52:55], v[168:171], v[180:183], v[52:55]
	v_mfma_f32_16x16x32_bf16 v[40:43], v[152:155], v[188:191], v[40:43]
	v_mfma_f32_16x16x32_bf16 v[36:39], v[168:171], v[188:191], v[36:39]
	v_mfma_f32_16x16x32_bf16 v[24:27], v[152:155], v[196:199], v[24:27]
	v_mfma_f32_16x16x32_bf16 v[20:23], v[168:171], v[196:199], v[20:23]
	v_mfma_f32_16x16x32_bf16 v[8:11], v[152:155], v[214:217], v[8:11]
	v_mfma_f32_16x16x32_bf16 v[4:7], v[168:171], v[214:217], v[4:7]
	s_barrier
	s_setprio 0
	s_add_i32 s36, 0, 0x18000
	s_add_i32 s73, 0, 0x1c000
	v_add_u32_e32 v104, s36, v176
	v_add_u32_e32 v168, s73, v176
	ds_read_b128 v[84:87], v104
	ds_read_b128 v[88:91], v104 offset:1024
	ds_read_b128 v[96:99], v104 offset:2048
	ds_read_b128 v[104:107], v104 offset:3072
	ds_read_b128 v[148:151], v168
	ds_read_b128 v[152:155], v168 offset:1024
	ds_read_b128 v[156:159], v168 offset:2048
	ds_read_b128 v[168:171], v168 offset:3072
	s_add_u32 s4, s4, s18
	s_addc_u32 s5, s5, s19
	s_mov_b32 m0, s56
	ds_read_b128 v[172:175], v178 offset:32768
	ds_read_b128 v[180:183], v178 offset:33792
	ds_read_b128 v[184:187], v178 offset:34816
	ds_read_b128 v[188:191], v178 offset:35840
	ds_read_b128 v[192:195], v178 offset:36864
	ds_read_b128 v[196:199], v178 offset:37888
	ds_read_b128 v[200:203], v178 offset:38912
	ds_read_b128 v[214:217], v178 offset:39936
	global_load_lds_dwordx4 v162, s[4:5]
	s_mov_b32 m0, s57
	s_nop 0
	global_load_lds_dwordx4 v164, s[4:5]
	s_waitcnt vmcnt(8)
	s_waitcnt lgkmcnt(0)
	s_setprio 1
	s_barrier
	v_mfma_f32_16x16x32_bf16 v[144:147], v[84:87], v[172:175], v[144:147]
	v_mfma_f32_16x16x32_bf16 v[140:143], v[96:99], v[172:175], v[140:143]
	v_mfma_f32_16x16x32_bf16 v[128:131], v[84:87], v[184:187], v[128:131]
	v_mfma_f32_16x16x32_bf16 v[124:127], v[96:99], v[184:187], v[124:127]
	v_mfma_f32_16x16x32_bf16 v[112:115], v[84:87], v[192:195], v[112:115]
	v_mfma_f32_16x16x32_bf16 v[108:111], v[96:99], v[192:195], v[108:111]
	v_mfma_f32_16x16x32_bf16 v[80:83], v[84:87], v[200:203], v[80:83]
	v_mfma_f32_16x16x32_bf16 v[76:79], v[96:99], v[200:203], v[76:79]
	v_mfma_f32_16x16x32_bf16 v[144:147], v[88:91], v[180:183], v[144:147]
	v_mfma_f32_16x16x32_bf16 v[140:143], v[104:107], v[180:183], v[140:143]
	v_mfma_f32_16x16x32_bf16 v[128:131], v[88:91], v[188:191], v[128:131]
	v_mfma_f32_16x16x32_bf16 v[124:127], v[104:107], v[188:191], v[124:127]
	v_mfma_f32_16x16x32_bf16 v[112:115], v[88:91], v[196:199], v[112:115]
	v_mfma_f32_16x16x32_bf16 v[108:111], v[104:107], v[196:199], v[108:111]
	v_mfma_f32_16x16x32_bf16 v[80:83], v[88:91], v[214:217], v[80:83]
	v_mfma_f32_16x16x32_bf16 v[76:79], v[104:107], v[214:217], v[76:79]
	v_mfma_f32_16x16x32_bf16 v[136:139], v[148:151], v[172:175], v[136:139]
	v_mfma_f32_16x16x32_bf16 v[132:135], v[156:159], v[172:175], v[132:135]
	v_mfma_f32_16x16x32_bf16 v[120:123], v[148:151], v[184:187], v[120:123]
	v_mfma_f32_16x16x32_bf16 v[116:119], v[156:159], v[184:187], v[116:119]
	v_mfma_f32_16x16x32_bf16 v[100:103], v[148:151], v[192:195], v[100:103]
	v_mfma_f32_16x16x32_bf16 v[92:95], v[156:159], v[192:195], v[92:95]
	v_mfma_f32_16x16x32_bf16 v[72:75], v[148:151], v[200:203], v[72:75]
	v_mfma_f32_16x16x32_bf16 v[68:71], v[156:159], v[200:203], v[68:71]
	v_mfma_f32_16x16x32_bf16 v[136:139], v[152:155], v[180:183], v[136:139]
	v_mfma_f32_16x16x32_bf16 v[132:135], v[168:171], v[180:183], v[132:135]
	v_mfma_f32_16x16x32_bf16 v[120:123], v[152:155], v[188:191], v[120:123]
	v_mfma_f32_16x16x32_bf16 v[116:119], v[168:171], v[188:191], v[116:119]
	v_mfma_f32_16x16x32_bf16 v[100:103], v[152:155], v[196:199], v[100:103]
	v_mfma_f32_16x16x32_bf16 v[92:95], v[168:171], v[196:199], v[92:95]
	v_mfma_f32_16x16x32_bf16 v[72:75], v[152:155], v[214:217], v[72:75]
	v_mfma_f32_16x16x32_bf16 v[68:71], v[168:171], v[214:217], v[68:71]
	s_barrier
; #define PG8_STAGEX(b, gbase) do { if constexpr (XR) { if (lane < 16) __builtin_amdgcn_global_load_lds((const unsigned*)((const char*)(gbase) + voffX), (PG8_LAS unsigned*)(lds + XR_OFF + (b) * 2048 + wid * 256), 16, 0, 0); } } while (0)
; #define PG8_WAIT_LOOP() do { if constexpr (XR) PG8_WAIT_V(9); else PG8_WAIT_V(8); } while (0)
; #define PG8_STAGE(bufoff, gbase, voff) do { _Pragma("unroll") for (int _i = 0; _i < 2; ++_i) \
;         __builtin_amdgcn_global_load_lds((const unsigned*)((const char*)(gbase) + (voff)[_i]), (PG8_LAS unsigned*)(lds + (bufoff) + ldsw + _i * 8192), 16, 0, 0); } while (0)
; #define PG8_LDA(dst, b, h) do { _Pragma("unroll") for (int m = 0; m < 4; ++m) _Pragma("unroll") for (int k = 0; k < 2; ++k) dst[m][k] = *(const PG8_LAS bf16x8*)(lds + PG8_SA(b, h) + aoff + m * 2048 + k * 1024); } while (0)
; #define PG8_MMA(ai, bj, At, Bt) do { __builtin_amdgcn_s_setprio(1); _Pragma("unroll") for (int m = 0; m < 4; ++m) _Pragma("unroll") for (int n = 0; n < 2; ++n) _Pragma("unroll") for (int k = 0; k < 2; ++k) \
;         acc[ai][bj][m][n] = __builtin_amdgcn_mfma_f32_16x16x32_bf16(Bt[n][k], At[m][k], acc[ai][bj][m][n], 0, 0, 0); __builtin_amdgcn_s_setprio(0); } while (0)
; #define PG8_WAIT_L(n) asm volatile("s_waitcnt lgkmcnt(" #n ")" ::: "memory")
; #define PG8_BAR __builtin_amdgcn_s_barrier()
; #define PG8_SCHED __builtin_amdgcn_sched_barrier(0)
; template <class Epi, class Sched, bool ALIGN_EPI = false, bool SP2 = false, bool DRAIN = true, bool XR = false>
; __device__ __forceinline__ void gemm_phase(PG8_LAS unsigned char* lds, const Gemm g, const Sched& S, const Epi& E) {
;     ...
;         for (int t = 0; t < nt; t += 2) {
;     ...
;             PG8_LDA(At, 1, 1); PG8_STAGE(PG8_SB(1, 0), b3, voffB); PG8_STAGE(PG8_SB(1, 1), b3 + hstep, voffB); PG8_STAGE(PG8_SA(1, 0), a3, voffA); PG8_STAGEX(1, x3);
;             PG8_WAIT_LOOP(); PG8_WAIT_L(0); PG8_BAR; PG8_MMA(1, 0, At, B0); PG8_MMA(1, 1, At, B1); PG8_BAR; PG8_SCHED;
	s_setprio 0
	s_add_i32 s4, s36, s51
	v_lshl_add_u64 v[204:205], v[204:205], 0, s[86:87]
	s_mov_b32 m0, s4
	ds_read_b128 v[172:175], v178 offset:49152
	ds_read_b128 v[180:183], v178 offset:50176
	ds_read_b128 v[184:187], v178 offset:51200
	ds_read_b128 v[188:191], v178 offset:52224
	ds_read_b128 v[192:195], v178 offset:53248
	ds_read_b128 v[196:199], v178 offset:54272
	ds_read_b128 v[200:203], v178 offset:55296
	ds_read_b128 v[214:217], v178 offset:56320
	global_load_lds_dwordx4 v[204:205], off
	v_lshl_add_u64 v[204:205], v[206:207], 0, s[86:87]
	s_add_i32 m0, s4, 0x2000
	s_add_i32 s4, s73, s51
	global_load_lds_dwordx4 v[204:205], off
	v_lshl_add_u64 v[204:205], v[208:209], 0, s[86:87]
	s_mov_b32 m0, s4
	s_nop 0
	global_load_lds_dwordx4 v[204:205], off
	v_lshl_add_u64 v[204:205], v[212:213], 0, s[86:87]
	s_add_i32 m0, s4, 0x2000
	s_nop 0
	global_load_lds_dwordx4 v[204:205], off
	v_lshl_add_u64 v[204:205], v[218:219], 0, s[86:87]
	s_mov_b32 m0, s62
	s_nop 0
	global_load_lds_dwordx4 v[204:205], off
	v_lshl_add_u64 v[204:205], v[220:221], 0, s[86:87]
	s_mov_b32 m0, s63
	s_nop 0
	global_load_lds_dwordx4 v[204:205], off
	s_waitcnt vmcnt(8)
	s_waitcnt lgkmcnt(0)
	s_setprio 1
	s_barrier
	v_mfma_f32_16x16x32_bf16 v[64:67], v[84:87], v[172:175], v[64:67]
	v_mfma_f32_16x16x32_bf16 v[60:63], v[96:99], v[172:175], v[60:63]
	v_mfma_f32_16x16x32_bf16 v[48:51], v[84:87], v[184:187], v[48:51]
	v_mfma_f32_16x16x32_bf16 v[44:47], v[96:99], v[184:187], v[44:47]
	v_mfma_f32_16x16x32_bf16 v[32:35], v[84:87], v[192:195], v[32:35]
	v_mfma_f32_16x16x32_bf16 v[28:31], v[96:99], v[192:195], v[28:31]
	v_mfma_f32_16x16x32_bf16 v[16:19], v[84:87], v[200:203], v[16:19]
	v_mfma_f32_16x16x32_bf16 v[12:15], v[96:99], v[200:203], v[12:15]
	v_mfma_f32_16x16x32_bf16 v[64:67], v[88:91], v[180:183], v[64:67]
	v_mfma_f32_16x16x32_bf16 v[60:63], v[104:107], v[180:183], v[60:63]
	v_mfma_f32_16x16x32_bf16 v[48:51], v[88:91], v[188:191], v[48:51]
	v_mfma_f32_16x16x32_bf16 v[44:47], v[104:107], v[188:191], v[44:47]
	v_mfma_f32_16x16x32_bf16 v[32:35], v[88:91], v[196:199], v[32:35]
	v_mfma_f32_16x16x32_bf16 v[28:31], v[104:107], v[196:199], v[28:31]
	v_mfma_f32_16x16x32_bf16 v[16:19], v[88:91], v[214:217], v[16:19]
	v_mfma_f32_16x16x32_bf16 v[12:15], v[104:107], v[214:217], v[12:15]
	v_mfma_f32_16x16x32_bf16 v[56:59], v[148:151], v[172:175], v[56:59]
	v_mfma_f32_16x16x32_bf16 v[52:55], v[156:159], v[172:175], v[52:55]
	v_mfma_f32_16x16x32_bf16 v[40:43], v[148:151], v[184:187], v[40:43]
	v_mfma_f32_16x16x32_bf16 v[36:39], v[156:159], v[184:187], v[36:39]
	v_mfma_f32_16x16x32_bf16 v[24:27], v[148:151], v[192:195], v[24:27]
	v_mfma_f32_16x16x32_bf16 v[20:23], v[156:159], v[192:195], v[20:23]
	v_mfma_f32_16x16x32_bf16 v[8:11], v[148:151], v[200:203], v[8:11]
	v_mfma_f32_16x16x32_bf16 v[4:7], v[156:159], v[200:203], v[4:7]
	v_mfma_f32_16x16x32_bf16 v[56:59], v[152:155], v[180:183], v[56:59]
	v_mfma_f32_16x16x32_bf16 v[52:55], v[168:171], v[180:183], v[52:55]
	v_mfma_f32_16x16x32_bf16 v[40:43], v[152:155], v[188:191], v[40:43]
	v_mfma_f32_16x16x32_bf16 v[36:39], v[168:171], v[188:191], v[36:39]
	v_mfma_f32_16x16x32_bf16 v[24:27], v[152:155], v[196:199], v[24:27]
	v_mfma_f32_16x16x32_bf16 v[20:23], v[168:171], v[196:199], v[20:23]
	v_mfma_f32_16x16x32_bf16 v[8:11], v[152:155], v[214:217], v[8:11]
	v_mfma_f32_16x16x32_bf16 v[4:7], v[168:171], v[214:217], v[4:7]
	s_barrier
	s_setprio 0
	s_add_i32 s4, s72, 2
	s_cmp_ge_i32 s72, s60
	s_mov_b32 s72, s4
	s_cbranch_scc0 .LBB0_1020

; #define PG8_LAS __attribute__((address_space(3)))
;     template <class Sched> __device__ __forceinline__ void prehook(const Sched& S, const Unit& u0) const { rtab_hook(S, u0, pre, ssq, (PG8_LAS float*)rtab); }
;     __device__ __forceinline__ bool next(int i, Unit& u) const { if (i >= nr) return false; int j = nr - 1 - i + rot; if (j >= nr) j -= nr; const bool ok = StaticOrder::next(j, u); u.ui = i; return ok; }
;     __device__ __forceinline__ bool next(int i, Unit& u) const { if (c >= nM || i >= 2) return false; u.pm = c; u.pn = i; u.ui = i; return true; }
; #define PG8_STAGEX(b, gbase) do { if constexpr (XR) { if (lane < 16) __builtin_amdgcn_global_load_lds((const unsigned*)((const char*)(gbase) + voffX), (PG8_LAS unsigned*)(lds + XR_OFF + (b) * 2048 + wid * 256), 16, 0, 0); } } while (0)
; #define PG8_STAGE(bufoff, gbase, voff) do { _Pragma("unroll") for (int _i = 0; _i < 2; ++_i) \
;         __builtin_amdgcn_global_load_lds((const unsigned*)((const char*)(gbase) + (voff)[_i]), (PG8_LAS unsigned*)(lds + (bufoff) + ldsw + _i * 8192), 16, 0, 0); } while (0)
;     template <class Sched> __device__ __forceinline__ void prehook(const Sched& S, const Unit& u0) const { rtab_hook(S, u0, pre, ssq_in, (PG8_LAS float*)rtab); }
; template <class Sched> __device__ __forceinline__ void rtab_hook(const Sched& S, const Unit& u0, const RtPre& pre, const float* ssq, PG8_LAS float* rt) {
;     int t_ = threadIdx.x; asm volatile("" : "+v"(t_));
;     if (t_ < 256) { const float r0 = rtpre_rinv(pre, 1.0f / 1024.0f); Unit u_;
;         for (int i_ = 0; i_ < 8 && S.next(i_, u_); ++i_) { float r = r0; if (u_.pm != u0.pm) r = rinv16(ssq, u_.pm * 256 + t_, 1.0f / 1024.0f); rt[i_ * 256 + t_] = r; } }
; template <class Epi, class Sched, bool ALIGN_EPI = false, bool SP2 = false, bool DRAIN = true, bool XR = false>
; __device__ __forceinline__ void gemm_phase(PG8_LAS unsigned char* lds, const Gemm g, const Sched& S, const Epi& E) {
;     ...
;         PG8_STAGE(PG8_SB(0, 0), cB + kb0, voffB); PG8_STAGE(PG8_SB(0, 1), cB + kb0 + hstep, voffB); PG8_STAGE(PG8_SA(0, 0), cA + ka0, voffA); PG8_STAGEX(0, cX + kx0); PG8_STAGE(PG8_SA(0, 1), cA + ka0 + hstepA, voffA);
;         if constexpr (Epi::PREHOOK) E.prehook(S, cur);
.LBB0_1169:
	s_or_b64 exec, exec, s[26:27]
	s_add_u32 s26, s18, s10
	v_mov_b32_e32 v215, v3
	s_addc_u32 s27, s19, s11
	s_add_i32 s71, s64, 0x4000
	v_mov_b32_e32 v219, v3
	s_mov_b32 m0, s71
	s_add_i32 s72, s64, 0x6000
	global_load_lds_dwordx4 v214, s[26:27]
	v_lshl_add_u64 v[4:5], s[26:27], 0, v[218:219]
	s_mov_b32 m0, s72
	s_movk_i32 s26, 0x100
	global_load_lds_dwordx4 v[4:5], off
	v_mov_b32_e32 v4, v0
	s_nop 0
	v_cmp_gt_i32_e32 vcc, s26, v4
	s_and_saveexec_b64 s[26:27], vcc
	s_cbranch_execz .LBB0_1198
	s_ashr_i32 s28, s52, 31
	s_lshr_b32 s28, s28, 29
	s_add_i32 s30, s52, s28
	s_and_b32 s28, s30, -8
	s_sub_i32 s35, s52, s28
	s_cmp_gt_i32 s35, -1
	s_mov_b64 s[28:29], -1
	s_cbranch_scc0 .LBB0_1172
	s_lshl_b32 s31, s35, 5
	s_mov_b64 s[28:29], 0

; #define PG8_STAGEX(b, gbase) do { if constexpr (XR) { if (lane < 16) __builtin_amdgcn_global_load_lds((const unsigned*)((const char*)(gbase) + voffX), (PG8_LAS unsigned*)(lds + XR_OFF + (b) * 2048 + wid * 256), 16, 0, 0); } } while (0)
; #define PG8_LDX(b) do { if constexpr (XR) { _Pragma("unroll") for (int k = 0; k < 2; ++k) Ax_[k] = *(const PG8_LAS bf16x8*)(lds + XR_OFF + (b) * 2048 + aoffx + k * 1024); } } while (0)
; #define PG8_MMAX() do { if constexpr (XR) { if (hasx) { __builtin_amdgcn_s_setprio(1); if (wr == 0) PG8_MMAX_(B0); else PG8_MMAX_(B1); __builtin_amdgcn_s_setprio(0); } } } while (0)
; #define PG8_WAIT_LOOP() do { if constexpr (XR) PG8_WAIT_V(9); else PG8_WAIT_V(8); } while (0)
; #define PG8_STAGE(bufoff, gbase, voff) do { _Pragma("unroll") for (int _i = 0; _i < 2; ++_i) \
;         __builtin_amdgcn_global_load_lds((const unsigned*)((const char*)(gbase) + (voff)[_i]), (PG8_LAS unsigned*)(lds + (bufoff) + ldsw + _i * 8192), 16, 0, 0); } while (0)
; #define PG8_LDA(dst, b, h) do { _Pragma("unroll") for (int m = 0; m < 4; ++m) _Pragma("unroll") for (int k = 0; k < 2; ++k) dst[m][k] = *(const PG8_LAS bf16x8*)(lds + PG8_SA(b, h) + aoff + m * 2048 + k * 1024); } while (0)
; template <class Epi, class Sched, bool ALIGN_EPI = false, bool SP2 = false, bool DRAIN = true, bool XR = false>
; __device__ __forceinline__ void gemm_phase(PG8_LAS unsigned char* lds, const Gemm g, const Sched& S, const Epi& E) {
;     ...
;             const bool last = (t == nt - 2);
;             const char* a1 = cA + PG8_KOA(t) + kstep;
;             const char* a2 = last ? nA + ka0 : cA + PG8_KOA(t + 2); const char* b2 = last ? nB + kb0 : cB + PG8_KOB(t + 2);
;             const char* x2 = XR ? (last ? nX + kx0 : cX + PG8_KOX(t + 2)) : nullptr; const char* x3 = XR ? x2 + kstep : nullptr;
;             const char* a3 = a2 + kstep; const char* b3 = b2 + kstep;
;             if (last && has_next) S.a_ready(nxt);
;             if constexpr (SP2) {
;             PG8_LDB(B0, 0, 0); PG8_LDB(B1, 0, 1); PG8_SCHED; PG8_LDA(At, 0, 0); PG8_LDX(0); PG8_STAGE(PG8_SA(1, 1), a1 + hstepA, voffA);
;             PG8_WAIT_LOOP(); PG8_WAIT_L(0); PG8_BAR; PG8_MMA(0, 0, At, B0); PG8_MMA(0, 1, At, B1); PG8_MMAX(); PG8_BAR; PG8_SCHED;
;             PG8_LDA(At, 0, 1); PG8_STAGE(PG8_SB(0, 0), b2, voffB); PG8_STAGE(PG8_SB(0, 1), b2 + hstep, voffB); PG8_STAGE(PG8_SA(0, 0), a2, voffA); PG8_STAGEX(0, x2);
.LBB0_1226:
	s_barrier
	s_add_i32 s89, s50, 2
	s_and_b32 s48, s89, s82
	s_lshr_b32 s84, s48, 2
	s_lshl_b32 s36, s48, 7
	s_lshl_b64 vcc, s[84:85], 9
	s_and_b32 s36, s36, 0x100
	s_add_u32 s49, s18, vcc_lo
	s_addc_u32 s51, s19, vcc_hi
	s_add_u32 s36, s49, s36
	s_mov_b32 s49, s85
	s_addc_u32 s51, s51, 0
	s_lshl_b64 s[48:49], s[48:49], 7
	s_add_u32 vcc_lo, s14, s48
	s_addc_u32 vcc_hi, s15, s49
	s_add_u32 s58, s16, s48
	s_addc_u32 s59, s17, s49
	s_cmp_eq_u32 s37, s50
	s_cselect_b32 s49, s43, s51
	s_cselect_b32 s48, s42, s36
	s_cselect_b32 s51, s97, s59
	s_cselect_b32 s50, s90, s58
	s_cselect_b32 vcc_hi, s45, vcc_hi
	s_cselect_b32 vcc_lo, s44, vcc_lo
	s_mov_b32 m0, s65
	v_lshl_add_u64 v[224:225], vcc, 0, v[216:217]
	v_lshl_add_u64 v[226:227], vcc, 0, v[220:221]
	s_add_u32 vcc_lo, vcc_lo, s10
	ds_read_b128 v[198:201], v251 offset:16384
	ds_read_b128 v[202:205], v251 offset:17408
	ds_read_b128 v[190:193], v251 offset:18432
	ds_read_b128 v[194:197], v251 offset:19456
	ds_read_b128 v[182:185], v251 offset:20480
	ds_read_b128 v[186:189], v251 offset:21504
	ds_read_b128 v[174:177], v251 offset:22528
	ds_read_b128 v[178:181], v251 offset:23552
	global_load_lds_dwordx4 v[224:225], off
	s_mov_b32 m0, s67
	s_addc_u32 vcc_hi, vcc_hi, s11
	global_load_lds_dwordx4 v[226:227], off
	v_lshl_add_u64 v[228:229], vcc, 0, v[216:217]
	s_mov_b32 m0, s68
	v_lshl_add_u64 v[230:231], vcc, 0, v[220:221]
	global_load_lds_dwordx4 v216, vcc
	s_mov_b32 m0, s69
	v_lshl_add_u64 v[232:233], s[48:49], 0, v[214:215]
	global_load_lds_dwordx4 v220, vcc
	s_mov_b32 m0, s64
	v_lshl_add_u64 v[234:235], s[48:49], 0, v[218:219]
	global_load_lds_dwordx4 v214, s[48:49]
	s_mov_b32 m0, s70
	v_lshl_add_u64 v[4:5], s[50:51], 0, v[222:223]
	global_load_lds_dwordx4 v218, s[48:49]
	s_and_saveexec_b64 s[50:51], s[2:3]
	s_cbranch_execz .LBB0_1228
	s_add_i32 s36, s57, 0
	s_add_i32 m0, s36, 0x22400
	s_nop 0
	global_load_lds_dwordx4 v[4:5], off
; #define PG8_LDX(b) do { if constexpr (XR) { _Pragma("unroll") for (int k = 0; k < 2; ++k) Ax_[k] = *(const PG8_LAS bf16x8*)(lds + XR_OFF + (b) * 2048 + aoffx + k * 1024); } } while (0)
; #define PG8_MMAX() do { if constexpr (XR) { if (hasx) { __builtin_amdgcn_s_setprio(1); if (wr == 0) PG8_MMAX_(B0); else PG8_MMAX_(B1); __builtin_amdgcn_s_setprio(0); } } } while (0)
; #define PG8_WAIT_LOOP() do { if constexpr (XR) PG8_WAIT_V(9); else PG8_WAIT_V(8); } while (0)
; #define PG8_STAGE(bufoff, gbase, voff) do { _Pragma("unroll") for (int _i = 0; _i < 2; ++_i) \
;         __builtin_amdgcn_global_load_lds((const unsigned*)((const char*)(gbase) + (voff)[_i]), (PG8_LAS unsigned*)(lds + (bufoff) + ldsw + _i * 8192), 16, 0, 0); } while (0)
; #define PG8_LDA(dst, b, h) do { _Pragma("unroll") for (int m = 0; m < 4; ++m) _Pragma("unroll") for (int k = 0; k < 2; ++k) dst[m][k] = *(const PG8_LAS bf16x8*)(lds + PG8_SA(b, h) + aoff + m * 2048 + k * 1024); } while (0)
; #define PG8_LDB(dst, b, h) do { _Pragma("unroll") for (int n = 0; n < 2; ++n) _Pragma("unroll") for (int k = 0; k < 2; ++k) dst[n][k] = *(const PG8_LAS bf16x8*)(lds + PG8_SB(b, h) + boff + n * 2048 + k * 1024); } while (0)
; #define PG8_MMA(ai, bj, At, Bt) do { __builtin_amdgcn_s_setprio(1); _Pragma("unroll") for (int m = 0; m < 4; ++m) _Pragma("unroll") for (int n = 0; n < 2; ++n) _Pragma("unroll") for (int k = 0; k < 2; ++k) \
;         acc[ai][bj][m][n] = __builtin_amdgcn_mfma_f32_16x16x32_bf16(Bt[n][k], At[m][k], acc[ai][bj][m][n], 0, 0, 0); __builtin_amdgcn_s_setprio(0); } while (0)
; #define PG8_WAIT_L(n) asm volatile("s_waitcnt lgkmcnt(" #n ")" ::: "memory")
; #define PG8_BAR __builtin_amdgcn_s_barrier()
; #define PG8_SCHED __builtin_amdgcn_sched_barrier(0)
; template <class Epi, class Sched, bool ALIGN_EPI = false, bool SP2 = false, bool DRAIN = true, bool XR = false>
; __device__ __forceinline__ void gemm_phase(PG8_LAS unsigned char* lds, const Gemm g, const Sched& S, const Epi& E) {
;     ...
;             PG8_WAIT_LOOP(); PG8_WAIT_L(0); PG8_BAR; PG8_MMA(1, 0, At, B0); PG8_MMA(1, 1, At, B1); PG8_BAR; PG8_SCHED;
;             PG8_LDB(B0, 1, 0); PG8_LDB(B1, 1, 1); PG8_SCHED; PG8_LDA(At, 1, 0); PG8_LDX(1); PG8_STAGE(PG8_SA(0, 1), a2 + hstepA, voffA);
;             PG8_WAIT_LOOP(); PG8_WAIT_L(0); PG8_BAR; PG8_MMA(0, 0, At, B0); PG8_MMA(0, 1, At, B1); PG8_MMAX(); PG8_BAR; PG8_SCHED;
.LBB0_1228:
	s_or_b64 exec, exec, s[50:51]
	s_waitcnt vmcnt(9)
	s_waitcnt lgkmcnt(0)
	s_setprio 1
	s_barrier
	v_mfma_f32_16x16x32_bf16 v[74:77], v[158:161], v[198:201], v[74:77]
	v_mfma_f32_16x16x32_bf16 v[70:73], v[166:169], v[198:201], v[70:73]
	v_mfma_f32_16x16x32_bf16 v[66:69], v[158:161], v[190:193], v[66:69]
	v_mfma_f32_16x16x32_bf16 v[62:65], v[166:169], v[190:193], v[62:65]
	v_mfma_f32_16x16x32_bf16 v[58:61], v[158:161], v[182:185], v[58:61]
	v_mfma_f32_16x16x32_bf16 v[54:57], v[166:169], v[182:185], v[54:57]
	v_mfma_f32_16x16x32_bf16 v[50:53], v[158:161], v[174:177], v[50:53]
	v_mfma_f32_16x16x32_bf16 v[46:49], v[166:169], v[174:177], v[46:49]
	v_mfma_f32_16x16x32_bf16 v[74:77], v[162:165], v[202:205], v[74:77]
	v_mfma_f32_16x16x32_bf16 v[70:73], v[170:173], v[202:205], v[70:73]
	v_mfma_f32_16x16x32_bf16 v[66:69], v[162:165], v[194:197], v[66:69]
	v_mfma_f32_16x16x32_bf16 v[62:65], v[170:173], v[194:197], v[62:65]
	v_mfma_f32_16x16x32_bf16 v[58:61], v[162:165], v[186:189], v[58:61]
	v_mfma_f32_16x16x32_bf16 v[54:57], v[170:173], v[186:189], v[54:57]
	v_mfma_f32_16x16x32_bf16 v[50:53], v[162:165], v[178:181], v[50:53]
	v_mfma_f32_16x16x32_bf16 v[46:49], v[170:173], v[178:181], v[46:49]
	v_mfma_f32_16x16x32_bf16 v[42:45], v[142:145], v[198:201], v[42:45]
	v_mfma_f32_16x16x32_bf16 v[38:41], v[150:153], v[198:201], v[38:41]
	v_mfma_f32_16x16x32_bf16 v[34:37], v[142:145], v[190:193], v[34:37]
	v_mfma_f32_16x16x32_bf16 v[30:33], v[150:153], v[190:193], v[30:33]
	v_mfma_f32_16x16x32_bf16 v[26:29], v[142:145], v[182:185], v[26:29]
	v_mfma_f32_16x16x32_bf16 v[22:25], v[150:153], v[182:185], v[22:25]
	v_mfma_f32_16x16x32_bf16 v[18:21], v[142:145], v[174:177], v[18:21]
	v_mfma_f32_16x16x32_bf16 v[14:17], v[150:153], v[174:177], v[14:17]
	v_mfma_f32_16x16x32_bf16 v[42:45], v[146:149], v[202:205], v[42:45]
	v_mfma_f32_16x16x32_bf16 v[38:41], v[154:157], v[202:205], v[38:41]
	v_mfma_f32_16x16x32_bf16 v[34:37], v[146:149], v[194:197], v[34:37]
	v_mfma_f32_16x16x32_bf16 v[30:33], v[154:157], v[194:197], v[30:33]
	v_mfma_f32_16x16x32_bf16 v[26:29], v[146:149], v[186:189], v[26:29]
	v_mfma_f32_16x16x32_bf16 v[22:25], v[154:157], v[186:189], v[22:25]
	v_mfma_f32_16x16x32_bf16 v[18:21], v[146:149], v[178:181], v[18:21]
	v_mfma_f32_16x16x32_bf16 v[14:17], v[154:157], v[178:181], v[14:17]
	s_barrier
	s_setprio 0
	v_add_u32_e32 v142, 0x18000, v250
	v_add_u32_e32 v154, 0x1c000, v250
	ds_read_b128 v[158:161], v142
	ds_read_b128 v[162:165], v142 offset:1024
	ds_read_b128 v[166:169], v142 offset:2048
	ds_read_b128 v[170:173], v142 offset:3072
	ds_read_b128 v[142:145], v154
	ds_read_b128 v[146:149], v154 offset:1024
	ds_read_b128 v[150:153], v154 offset:2048
	ds_read_b128 v[154:157], v154 offset:3072
	s_add_u32 s48, s48, s10
	s_addc_u32 s49, s49, s11
	s_mov_b32 m0, s71
	v_add_u32_e32 v178, 0x22c00, v240
	ds_read_b128 v[182:185], v251 offset:32768
	ds_read_b128 v[186:189], v251 offset:33792
	ds_read_b128 v[190:193], v251 offset:34816
	ds_read_b128 v[194:197], v251 offset:35840
	ds_read_b128 v[198:201], v251 offset:36864
	ds_read_b128 v[202:205], v251 offset:37888
	ds_read_b128 v[242:245], v251 offset:38912
	ds_read_b128 v[206:209], v251 offset:39936
	ds_read_b128 v[174:177], v178
	ds_read_b128 v[178:181], v178 offset:1024
	global_load_lds_dwordx4 v214, s[48:49]
	s_mov_b32 m0, s72
	s_nop 0
	global_load_lds_dwordx4 v218, s[48:49]
	s_waitcnt vmcnt(9)
	s_waitcnt lgkmcnt(0)
	s_setprio 1
	s_barrier
	v_mfma_f32_16x16x32_bf16 v[138:141], v[158:161], v[182:185], v[138:141]
	v_mfma_f32_16x16x32_bf16 v[134:137], v[166:169], v[182:185], v[134:137]
	v_mfma_f32_16x16x32_bf16 v[130:133], v[158:161], v[190:193], v[130:133]
	v_mfma_f32_16x16x32_bf16 v[126:129], v[166:169], v[190:193], v[126:129]
	v_mfma_f32_16x16x32_bf16 v[122:125], v[158:161], v[198:201], v[122:125]
	v_mfma_f32_16x16x32_bf16 v[118:121], v[166:169], v[198:201], v[118:121]
	v_mfma_f32_16x16x32_bf16 v[114:117], v[158:161], v[242:245], v[114:117]
	v_mfma_f32_16x16x32_bf16 v[110:113], v[166:169], v[242:245], v[110:113]
	v_mfma_f32_16x16x32_bf16 v[138:141], v[162:165], v[186:189], v[138:141]
	v_mfma_f32_16x16x32_bf16 v[134:137], v[170:173], v[186:189], v[134:137]
	v_mfma_f32_16x16x32_bf16 v[130:133], v[162:165], v[194:197], v[130:133]
	v_mfma_f32_16x16x32_bf16 v[126:129], v[170:173], v[194:197], v[126:129]
	v_mfma_f32_16x16x32_bf16 v[122:125], v[162:165], v[202:205], v[122:125]
	v_mfma_f32_16x16x32_bf16 v[118:121], v[170:173], v[202:205], v[118:121]
	v_mfma_f32_16x16x32_bf16 v[114:117], v[162:165], v[206:209], v[114:117]
	v_mfma_f32_16x16x32_bf16 v[110:113], v[170:173], v[206:209], v[110:113]
	v_mfma_f32_16x16x32_bf16 v[106:109], v[142:145], v[182:185], v[106:109]
	v_mfma_f32_16x16x32_bf16 v[102:105], v[150:153], v[182:185], v[102:105]
	v_mfma_f32_16x16x32_bf16 v[98:101], v[142:145], v[190:193], v[98:101]
	v_mfma_f32_16x16x32_bf16 v[94:97], v[150:153], v[190:193], v[94:97]
	v_mfma_f32_16x16x32_bf16 v[90:93], v[142:145], v[198:201], v[90:93]
	v_mfma_f32_16x16x32_bf16 v[86:89], v[150:153], v[198:201], v[86:89]
	v_mfma_f32_16x16x32_bf16 v[82:85], v[142:145], v[242:245], v[82:85]
	v_mfma_f32_16x16x32_bf16 v[78:81], v[150:153], v[242:245], v[78:81]
	v_mfma_f32_16x16x32_bf16 v[106:109], v[146:149], v[186:189], v[106:109]
	v_mfma_f32_16x16x32_bf16 v[102:105], v[154:157], v[186:189], v[102:105]
	v_mfma_f32_16x16x32_bf16 v[98:101], v[146:149], v[194:197], v[98:101]
	v_mfma_f32_16x16x32_bf16 v[94:97], v[154:157], v[194:197], v[94:97]
	v_mfma_f32_16x16x32_bf16 v[90:93], v[146:149], v[202:205], v[90:93]
	v_mfma_f32_16x16x32_bf16 v[86:89], v[154:157], v[202:205], v[86:89]
	v_mfma_f32_16x16x32_bf16 v[82:85], v[146:149], v[206:209], v[82:85]
	v_mfma_f32_16x16x32_bf16 v[78:81], v[154:157], v[206:209], v[78:81]
	s_setprio 0
	s_and_b64 vcc, exec, s[8:9]
	s_cbranch_vccnz .LBB0_1234
	s_setprio 1
	s_and_b64 vcc, exec, s[6:7]
	s_mov_b64 s[6:7], -1
	s_cbranch_vccnz .LBB0_1231
	v_mfma_f32_16x16x32_bf16 v[10:13], v[142:145], v[174:177], v[10:13]
	s_mov_b64 s[6:7], 0
	v_mfma_f32_16x16x32_bf16 v[6:9], v[150:153], v[174:177], v[6:9]
	v_mfma_f32_16x16x32_bf16 v[10:13], v[146:149], v[178:181], v[10:13]
	v_mfma_f32_16x16x32_bf16 v[6:9], v[154:157], v[178:181], v[6:9]

;     template <class Sched> __device__ __forceinline__ void prehook(const Sched& S, const Unit& u0) const { rtab_hook(S, u0, pre, ssq, (PG8_LAS float*)rtab); }
; #define PG8_STAGEX(b, gbase) do { if constexpr (XR) { if (lane < 16) __builtin_amdgcn_global_load_lds((const unsigned*)((const char*)(gbase) + voffX), (PG8_LAS unsigned*)(lds + XR_OFF + (b) * 2048 + wid * 256), 16, 0, 0); } } while (0)
; #define PG8_STAGE(bufoff, gbase, voff) do { _Pragma("unroll") for (int _i = 0; _i < 2; ++_i) \
;         __builtin_amdgcn_global_load_lds((const unsigned*)((const char*)(gbase) + (voff)[_i]), (PG8_LAS unsigned*)(lds + (bufoff) + ldsw + _i * 8192), 16, 0, 0); } while (0)
; #define PG8_BAR __builtin_amdgcn_s_barrier()
;     template <class Sched> __device__ __forceinline__ void prehook(const Sched& S, const Unit& u0) const { rtab_hook(S, u0, pre, ssq_in, (PG8_LAS float*)rtab); }
; template <class Epi, class Sched, bool ALIGN_EPI = false, bool SP2 = false, bool DRAIN = true, bool XR = false>
; __device__ __forceinline__ void gemm_phase(PG8_LAS unsigned char* lds, const Gemm g, const Sched& S, const Epi& E) {
;     ...
;         PG8_STAGE(PG8_SB(0, 0), cB + kb0, voffB); PG8_STAGE(PG8_SB(0, 1), cB + kb0 + hstep, voffB); PG8_STAGE(PG8_SA(0, 0), cA + ka0, voffA); PG8_STAGEX(0, cX + kx0); PG8_STAGE(PG8_SA(0, 1), cA + ka0 + hstepA, voffA);
;         if constexpr (Epi::PREHOOK) E.prehook(S, cur);
;         if (wr == 1) PG8_BAR;
.LBB0_1338:
	s_or_b64 exec, exec, s[6:7]
	s_ashr_i32 s6, s8, 8
	s_add_u32 s20, s56, s28
	v_mov_b32_e32 v221, v3
	s_addc_u32 s21, s57, s29
	s_add_i32 s19, s13, 0x4000
	v_mov_b32_e32 v217, v3
	s_mov_b32 m0, s19
	s_add_i32 s22, s13, 0x6000
	global_load_lds_dwordx4 v220, s[20:21]
	s_mov_b32 m0, s22
	s_cmp_eq_u32 s6, 1
	global_load_lds_dwordx4 v216, s[20:21]
	s_cselect_b64 s[34:35], -1, 0
	s_cmp_lg_u32 s6, 1
	s_cbranch_scc1 .LBB0_1340
	s_barrier

; #define PG8_STAGEX(b, gbase) do { if constexpr (XR) { if (lane < 16) __builtin_amdgcn_global_load_lds((const unsigned*)((const char*)(gbase) + voffX), (PG8_LAS unsigned*)(lds + XR_OFF + (b) * 2048 + wid * 256), 16, 0, 0); } } while (0)
; #define PG8_LDX(b) do { if constexpr (XR) { _Pragma("unroll") for (int k = 0; k < 2; ++k) Ax_[k] = *(const PG8_LAS bf16x8*)(lds + XR_OFF + (b) * 2048 + aoffx + k * 1024); } } while (0)
; #define PG8_MMAX() do { if constexpr (XR) { if (hasx) { __builtin_amdgcn_s_setprio(1); if (wr == 0) PG8_MMAX_(B0); else PG8_MMAX_(B1); __builtin_amdgcn_s_setprio(0); } } } while (0)
; #define PG8_WAIT_LOOP() do { if constexpr (XR) PG8_WAIT_V(9); else PG8_WAIT_V(8); } while (0)
; #define PG8_STAGE(bufoff, gbase, voff) do { _Pragma("unroll") for (int _i = 0; _i < 2; ++_i) \
;         __builtin_amdgcn_global_load_lds((const unsigned*)((const char*)(gbase) + (voff)[_i]), (PG8_LAS unsigned*)(lds + (bufoff) + ldsw + _i * 8192), 16, 0, 0); } while (0)
; #define PG8_LDA(dst, b, h) do { _Pragma("unroll") for (int m = 0; m < 4; ++m) _Pragma("unroll") for (int k = 0; k < 2; ++k) dst[m][k] = *(const PG8_LAS bf16x8*)(lds + PG8_SA(b, h) + aoff + m * 2048 + k * 1024); } while (0)
; #define PG8_BAR __builtin_amdgcn_s_barrier()
; template <class Epi, class Sched, bool ALIGN_EPI = false, bool SP2 = false, bool DRAIN = true, bool XR = false>
; __device__ __forceinline__ void gemm_phase(PG8_LAS unsigned char* lds, const Gemm g, const Sched& S, const Epi& E) {
;     ...
;             const char* a1 = cA + PG8_KOA(t) + kstep;
;             const char* a2 = last ? nA + ka0 : cA + PG8_KOA(t + 2); const char* b2 = last ? nB + kb0 : cB + PG8_KOB(t + 2);
;             const char* x2 = XR ? (last ? nX + kx0 : cX + PG8_KOX(t + 2)) : nullptr; const char* x3 = XR ? x2 + kstep : nullptr;
;             const char* a3 = a2 + kstep; const char* b3 = b2 + kstep;
;             if (last && has_next) S.a_ready(nxt);
;             if constexpr (SP2) {
;             PG8_LDB(B0, 0, 0); PG8_LDB(B1, 0, 1); PG8_SCHED; PG8_LDA(At, 0, 0); PG8_LDX(0); PG8_STAGE(PG8_SA(1, 1), a1 + hstepA, voffA);
;             PG8_WAIT_LOOP(); PG8_WAIT_L(0); PG8_BAR; PG8_MMA(0, 0, At, B0); PG8_MMA(0, 1, At, B1); PG8_MMAX(); PG8_BAR; PG8_SCHED;
;             PG8_LDA(At, 0, 1); PG8_STAGE(PG8_SB(0, 0), b2, voffB); PG8_STAGE(PG8_SB(0, 1), b2 + hstep, voffB); PG8_STAGE(PG8_SA(0, 0), a2, voffA); PG8_STAGEX(0, x2);
.LBB0_1365:
	s_barrier
	s_and_b32 s8, s90, s73
	s_lshr_b32 s84, s8, 2
	s_lshl_b32 s9, s8, 7
	s_lshl_b64 s[20:21], s[84:85], 9
	s_and_b32 s9, s9, 0x100
	s_add_u32 s20, s56, s20
	s_addc_u32 s21, s57, s21
	s_add_u32 s20, s20, s9
	s_mov_b32 s9, s85
	s_addc_u32 s21, s21, 0
	s_lshl_b64 s[8:9], s[8:9], 7
	s_add_u32 s36, s54, s8
	s_addc_u32 s62, s55, s9
	s_add_u32 s8, s58, s8
	s_addc_u32 s9, s59, s9
	s_cmp_eq_u32 s65, s90
	s_cselect_b32 s61, s49, s21
	s_cselect_b32 s60, s48, s20
	s_cselect_b32 s9, s88, s9
	s_cselect_b32 s8, s89, s8
	s_cselect_b32 s21, s51, s62
	s_cselect_b32 s20, s50, s36
	s_mov_b32 m0, s14
	v_lshl_add_u64 v[224:225], s[20:21], 0, v[218:219]
	v_lshl_add_u64 v[226:227], s[20:21], 0, v[214:215]
	s_add_u32 s20, s20, s28
	ds_read_b128 v[198:201], v249 offset:16384
	ds_read_b128 v[202:205], v249 offset:17408
	ds_read_b128 v[190:193], v249 offset:18432
	ds_read_b128 v[194:197], v249 offset:19456
	ds_read_b128 v[182:185], v249 offset:20480
	ds_read_b128 v[186:189], v249 offset:21504
	ds_read_b128 v[174:177], v249 offset:22528
	ds_read_b128 v[178:181], v249 offset:23552
	global_load_lds_dwordx4 v[224:225], off
	s_mov_b32 m0, s15
	s_addc_u32 s21, s21, s29
	global_load_lds_dwordx4 v[226:227], off
	v_lshl_add_u64 v[228:229], s[20:21], 0, v[218:219]
	s_mov_b32 m0, s16
	v_lshl_add_u64 v[230:231], s[20:21], 0, v[214:215]
	global_load_lds_dwordx4 v218, s[20:21]
	s_mov_b32 m0, s17
	v_lshl_add_u64 v[232:233], s[60:61], 0, v[220:221]
	global_load_lds_dwordx4 v214, s[20:21]
	s_mov_b32 m0, s13
	v_lshl_add_u64 v[234:235], s[60:61], 0, v[216:217]
	global_load_lds_dwordx4 v220, s[60:61]
	s_mov_b32 m0, s18
	v_lshl_add_u64 v[4:5], s[8:9], 0, v[222:223]
	global_load_lds_dwordx4 v216, s[60:61]
	s_and_saveexec_b64 s[62:63], s[0:1]
	s_cbranch_execz .LBB0_1367
	s_add_i32 s8, s12, 0
	s_add_i32 m0, s8, 0x22400
	s_nop 0
	global_load_lds_dwordx4 v[4:5], off
; #define PG8_LDX(b) do { if constexpr (XR) { _Pragma("unroll") for (int k = 0; k < 2; ++k) Ax_[k] = *(const PG8_LAS bf16x8*)(lds + XR_OFF + (b) * 2048 + aoffx + k * 1024); } } while (0)
; #define PG8_MMAX() do { if constexpr (XR) { if (hasx) { __builtin_amdgcn_s_setprio(1); if (wr == 0) PG8_MMAX_(B0); else PG8_MMAX_(B1); __builtin_amdgcn_s_setprio(0); } } } while (0)
; #define PG8_WAIT_LOOP() do { if constexpr (XR) PG8_WAIT_V(9); else PG8_WAIT_V(8); } while (0)
; #define PG8_STAGE(bufoff, gbase, voff) do { _Pragma("unroll") for (int _i = 0; _i < 2; ++_i) \
;         __builtin_amdgcn_global_load_lds((const unsigned*)((const char*)(gbase) + (voff)[_i]), (PG8_LAS unsigned*)(lds + (bufoff) + ldsw + _i * 8192), 16, 0, 0); } while (0)
; #define PG8_LDA(dst, b, h) do { _Pragma("unroll") for (int m = 0; m < 4; ++m) _Pragma("unroll") for (int k = 0; k < 2; ++k) dst[m][k] = *(const PG8_LAS bf16x8*)(lds + PG8_SA(b, h) + aoff + m * 2048 + k * 1024); } while (0)
; #define PG8_LDB(dst, b, h) do { _Pragma("unroll") for (int n = 0; n < 2; ++n) _Pragma("unroll") for (int k = 0; k < 2; ++k) dst[n][k] = *(const PG8_LAS bf16x8*)(lds + PG8_SB(b, h) + boff + n * 2048 + k * 1024); } while (0)
; #define PG8_MMA(ai, bj, At, Bt) do { __builtin_amdgcn_s_setprio(1); _Pragma("unroll") for (int m = 0; m < 4; ++m) _Pragma("unroll") for (int n = 0; n < 2; ++n) _Pragma("unroll") for (int k = 0; k < 2; ++k) \
;         acc[ai][bj][m][n] = __builtin_amdgcn_mfma_f32_16x16x32_bf16(Bt[n][k], At[m][k], acc[ai][bj][m][n], 0, 0, 0); __builtin_amdgcn_s_setprio(0); } while (0)
; #define PG8_WAIT_L(n) asm volatile("s_waitcnt lgkmcnt(" #n ")" ::: "memory")
; #define PG8_BAR __builtin_amdgcn_s_barrier()
; #define PG8_SCHED __builtin_amdgcn_sched_barrier(0)
; template <class Epi, class Sched, bool ALIGN_EPI = false, bool SP2 = false, bool DRAIN = true, bool XR = false>
; __device__ __forceinline__ void gemm_phase(PG8_LAS unsigned char* lds, const Gemm g, const Sched& S, const Epi& E) {
;     ...
;             PG8_WAIT_LOOP(); PG8_WAIT_L(0); PG8_BAR; PG8_MMA(1, 0, At, B0); PG8_MMA(1, 1, At, B1); PG8_BAR; PG8_SCHED;
;             PG8_LDB(B0, 1, 0); PG8_LDB(B1, 1, 1); PG8_SCHED; PG8_LDA(At, 1, 0); PG8_LDX(1); PG8_STAGE(PG8_SA(0, 1), a2 + hstepA, voffA);
;             PG8_WAIT_LOOP(); PG8_WAIT_L(0); PG8_BAR; PG8_MMA(0, 0, At, B0); PG8_MMA(0, 1, At, B1); PG8_MMAX(); PG8_BAR; PG8_SCHED;
.LBB0_1367:
	s_or_b64 exec, exec, s[62:63]
	s_waitcnt vmcnt(9)
	s_waitcnt lgkmcnt(0)
	s_setprio 1
	s_barrier
	v_mfma_f32_16x16x32_bf16 v[74:77], v[158:161], v[198:201], v[74:77]
	v_mfma_f32_16x16x32_bf16 v[70:73], v[166:169], v[198:201], v[70:73]
	v_mfma_f32_16x16x32_bf16 v[58:61], v[158:161], v[190:193], v[58:61]
	v_mfma_f32_16x16x32_bf16 v[54:57], v[166:169], v[190:193], v[54:57]
	v_mfma_f32_16x16x32_bf16 v[42:45], v[158:161], v[182:185], v[42:45]
	v_mfma_f32_16x16x32_bf16 v[38:41], v[166:169], v[182:185], v[38:41]
	v_mfma_f32_16x16x32_bf16 v[26:29], v[158:161], v[174:177], v[26:29]
	v_mfma_f32_16x16x32_bf16 v[22:25], v[166:169], v[174:177], v[22:25]
	v_mfma_f32_16x16x32_bf16 v[74:77], v[162:165], v[202:205], v[74:77]
	v_mfma_f32_16x16x32_bf16 v[70:73], v[170:173], v[202:205], v[70:73]
	v_mfma_f32_16x16x32_bf16 v[58:61], v[162:165], v[194:197], v[58:61]
	v_mfma_f32_16x16x32_bf16 v[54:57], v[170:173], v[194:197], v[54:57]
	v_mfma_f32_16x16x32_bf16 v[42:45], v[162:165], v[186:189], v[42:45]
	v_mfma_f32_16x16x32_bf16 v[38:41], v[170:173], v[186:189], v[38:41]
	v_mfma_f32_16x16x32_bf16 v[26:29], v[162:165], v[178:181], v[26:29]
	v_mfma_f32_16x16x32_bf16 v[22:25], v[170:173], v[178:181], v[22:25]
	v_mfma_f32_16x16x32_bf16 v[66:69], v[142:145], v[198:201], v[66:69]
	v_mfma_f32_16x16x32_bf16 v[62:65], v[150:153], v[198:201], v[62:65]
	v_mfma_f32_16x16x32_bf16 v[50:53], v[142:145], v[190:193], v[50:53]
	v_mfma_f32_16x16x32_bf16 v[46:49], v[150:153], v[190:193], v[46:49]
	v_mfma_f32_16x16x32_bf16 v[34:37], v[142:145], v[182:185], v[34:37]
	v_mfma_f32_16x16x32_bf16 v[30:33], v[150:153], v[182:185], v[30:33]
	v_mfma_f32_16x16x32_bf16 v[18:21], v[142:145], v[174:177], v[18:21]
	v_mfma_f32_16x16x32_bf16 v[14:17], v[150:153], v[174:177], v[14:17]
	v_mfma_f32_16x16x32_bf16 v[66:69], v[146:149], v[202:205], v[66:69]
	v_mfma_f32_16x16x32_bf16 v[62:65], v[154:157], v[202:205], v[62:65]
	v_mfma_f32_16x16x32_bf16 v[50:53], v[146:149], v[194:197], v[50:53]
	v_mfma_f32_16x16x32_bf16 v[46:49], v[154:157], v[194:197], v[46:49]
	v_mfma_f32_16x16x32_bf16 v[34:37], v[146:149], v[186:189], v[34:37]
	v_mfma_f32_16x16x32_bf16 v[30:33], v[154:157], v[186:189], v[30:33]
	v_mfma_f32_16x16x32_bf16 v[18:21], v[146:149], v[178:181], v[18:21]
	v_mfma_f32_16x16x32_bf16 v[14:17], v[154:157], v[178:181], v[14:17]
	s_barrier
	s_setprio 0
	v_add_u32_e32 v2, 0x18000, v248
	ds_read_b128 v[158:161], v2
	ds_read_b128 v[162:165], v2 offset:1024
	ds_read_b128 v[166:169], v2 offset:2048
	ds_read_b128 v[170:173], v2 offset:3072
	v_add_u32_e32 v2, 0x1c000, v248
	ds_read_b128 v[142:145], v2
	ds_read_b128 v[146:149], v2 offset:1024
	ds_read_b128 v[150:153], v2 offset:2048
	ds_read_b128 v[154:157], v2 offset:3072
	s_add_u32 s8, s60, s28
	s_addc_u32 s9, s61, s29
	s_mov_b32 m0, s19
	v_add_u32_e32 v2, 0x22c00, v250
	ds_read_b128 v[182:185], v249 offset:32768
	ds_read_b128 v[186:189], v249 offset:33792
	ds_read_b128 v[190:193], v249 offset:34816
	ds_read_b128 v[194:197], v249 offset:35840
	ds_read_b128 v[198:201], v249 offset:36864
	ds_read_b128 v[202:205], v249 offset:37888
	ds_read_b128 v[206:209], v249 offset:38912
	ds_read_b128 v[242:245], v249 offset:39936
	ds_read_b128 v[174:177], v2
	ds_read_b128 v[178:181], v2 offset:1024
	global_load_lds_dwordx4 v220, s[8:9]
	s_mov_b32 m0, s22
	s_nop 0
	global_load_lds_dwordx4 v216, s[8:9]
	s_waitcnt vmcnt(9)
	s_waitcnt lgkmcnt(0)
	s_setprio 1
	s_barrier
	v_mfma_f32_16x16x32_bf16 v[138:141], v[158:161], v[182:185], v[138:141]
	v_mfma_f32_16x16x32_bf16 v[134:137], v[166:169], v[182:185], v[134:137]
	v_mfma_f32_16x16x32_bf16 v[122:125], v[158:161], v[190:193], v[122:125]
	v_mfma_f32_16x16x32_bf16 v[118:121], v[166:169], v[190:193], v[118:121]
	v_mfma_f32_16x16x32_bf16 v[106:109], v[158:161], v[198:201], v[106:109]
	v_mfma_f32_16x16x32_bf16 v[102:105], v[166:169], v[198:201], v[102:105]
	v_mfma_f32_16x16x32_bf16 v[90:93], v[158:161], v[206:209], v[90:93]
	v_mfma_f32_16x16x32_bf16 v[86:89], v[166:169], v[206:209], v[86:89]
	v_mfma_f32_16x16x32_bf16 v[138:141], v[162:165], v[186:189], v[138:141]
	v_mfma_f32_16x16x32_bf16 v[134:137], v[170:173], v[186:189], v[134:137]
	v_mfma_f32_16x16x32_bf16 v[122:125], v[162:165], v[194:197], v[122:125]
	v_mfma_f32_16x16x32_bf16 v[118:121], v[170:173], v[194:197], v[118:121]
	v_mfma_f32_16x16x32_bf16 v[106:109], v[162:165], v[202:205], v[106:109]
	v_mfma_f32_16x16x32_bf16 v[102:105], v[170:173], v[202:205], v[102:105]
	v_mfma_f32_16x16x32_bf16 v[90:93], v[162:165], v[242:245], v[90:93]
	v_mfma_f32_16x16x32_bf16 v[86:89], v[170:173], v[242:245], v[86:89]
	v_mfma_f32_16x16x32_bf16 v[130:133], v[142:145], v[182:185], v[130:133]
	v_mfma_f32_16x16x32_bf16 v[126:129], v[150:153], v[182:185], v[126:129]
	v_mfma_f32_16x16x32_bf16 v[114:117], v[142:145], v[190:193], v[114:117]
	v_mfma_f32_16x16x32_bf16 v[110:113], v[150:153], v[190:193], v[110:113]
	v_mfma_f32_16x16x32_bf16 v[98:101], v[142:145], v[198:201], v[98:101]
	v_mfma_f32_16x16x32_bf16 v[94:97], v[150:153], v[198:201], v[94:97]
	v_mfma_f32_16x16x32_bf16 v[82:85], v[142:145], v[206:209], v[82:85]
	v_mfma_f32_16x16x32_bf16 v[78:81], v[150:153], v[206:209], v[78:81]
	v_mfma_f32_16x16x32_bf16 v[130:133], v[146:149], v[186:189], v[130:133]
	v_mfma_f32_16x16x32_bf16 v[126:129], v[154:157], v[186:189], v[126:129]
	v_mfma_f32_16x16x32_bf16 v[114:117], v[146:149], v[194:197], v[114:117]
	v_mfma_f32_16x16x32_bf16 v[110:113], v[154:157], v[194:197], v[110:113]
	v_mfma_f32_16x16x32_bf16 v[98:101], v[146:149], v[202:205], v[98:101]
	v_mfma_f32_16x16x32_bf16 v[94:97], v[154:157], v[202:205], v[94:97]
	v_mfma_f32_16x16x32_bf16 v[82:85], v[146:149], v[242:245], v[82:85]
	v_mfma_f32_16x16x32_bf16 v[78:81], v[154:157], v[242:245], v[78:81]
	s_setprio 0
	s_and_b64 vcc, exec, s[6:7]
	s_cbranch_vccnz .LBB0_1373
	s_setprio 1
	s_and_b64 vcc, exec, s[4:5]
	s_mov_b64 s[4:5], -1
	s_cbranch_vccnz .LBB0_1370
	v_mfma_f32_16x16x32_bf16 v[10:13], v[142:145], v[174:177], v[10:13]
	s_mov_b64 s[4:5], 0
	v_mfma_f32_16x16x32_bf16 v[6:9], v[150:153], v[174:177], v[6:9]
	v_mfma_f32_16x16x32_bf16 v[10:13], v[146:149], v[178:181], v[10:13]
	v_mfma_f32_16x16x32_bf16 v[6:9], v[154:157], v[178:181], v[6:9]

; #define PG8_LAS __attribute__((address_space(3)))
;     template <class Sched> __device__ __forceinline__ void prehook(const Sched& S, const Unit& u0) const { rtab_hook(S, u0, pre, ssq, (PG8_LAS float*)rtab); }
;     __device__ __forceinline__ bool next(int i, Unit& u) const { if (i >= nr) return false; int j = nr - 1 - i + rot; if (j >= nr) j -= nr; const bool ok = StaticOrder::next(j, u); u.ui = i; return ok; }
;     __device__ __forceinline__ bool next(int i, Unit& u) const { if (c >= nM || i >= 2) return false; u.pm = c; u.pn = i; u.ui = i; return true; }
; #define PG8_STAGEX(b, gbase) do { if constexpr (XR) { if (lane < 16) __builtin_amdgcn_global_load_lds((const unsigned*)((const char*)(gbase) + voffX), (PG8_LAS unsigned*)(lds + XR_OFF + (b) * 2048 + wid * 256), 16, 0, 0); } } while (0)
; #define PG8_STAGE(bufoff, gbase, voff) do { _Pragma("unroll") for (int _i = 0; _i < 2; ++_i) \
;         __builtin_amdgcn_global_load_lds((const unsigned*)((const char*)(gbase) + (voff)[_i]), (PG8_LAS unsigned*)(lds + (bufoff) + ldsw + _i * 8192), 16, 0, 0); } while (0)
;     template <class Sched> __device__ __forceinline__ void prehook(const Sched& S, const Unit& u0) const { rtab_hook(S, u0, pre, ssq_in, (PG8_LAS float*)rtab); }
; template <class Sched> __device__ __forceinline__ void rtab_hook(const Sched& S, const Unit& u0, const RtPre& pre, const float* ssq, PG8_LAS float* rt) {
;     int t_ = threadIdx.x; asm volatile("" : "+v"(t_));
;     if (t_ < 256) { const float r0 = rtpre_rinv(pre, 1.0f / 1024.0f); Unit u_;
;         for (int i_ = 0; i_ < 8 && S.next(i_, u_); ++i_) { float r = r0; if (u_.pm != u0.pm) r = rinv16(ssq, u_.pm * 256 + t_, 1.0f / 1024.0f); rt[i_ * 256 + t_] = r; } }
; template <class Epi, class Sched, bool ALIGN_EPI = false, bool SP2 = false, bool DRAIN = true, bool XR = false>
; __device__ __forceinline__ void gemm_phase(PG8_LAS unsigned char* lds, const Gemm g, const Sched& S, const Epi& E) {
;     ...
;         PG8_STAGE(PG8_SB(0, 0), cB + kb0, voffB); PG8_STAGE(PG8_SB(0, 1), cB + kb0 + hstep, voffB); PG8_STAGE(PG8_SA(0, 0), cA + ka0, voffA); PG8_STAGEX(0, cX + kx0); PG8_STAGE(PG8_SA(0, 1), cA + ka0 + hstepA, voffA);
;         if constexpr (Epi::PREHOOK) E.prehook(S, cur);
.LBB0_1411:
	s_or_b64 exec, exec, s[44:45]
	s_add_u32 s8, s48, s28
	v_mov_b32_e32 v205, v3
	s_addc_u32 s9, s49, s29
	s_add_i32 s12, s90, 0x4000
	v_mov_b32_e32 v217, v3
	s_mov_b32 m0, s12
	s_add_i32 s13, s90, 0x6000
	global_load_lds_dwordx4 v204, s[8:9]
	v_lshl_add_u64 v[22:23], s[8:9], 0, v[216:217]
	s_mov_b32 m0, s13
	v_mov_b32_e32 v21, v0
	global_load_lds_dwordx4 v216, s[8:9]
	s_movk_i32 s5, 0x100
	s_nop 0
	v_cmp_gt_i32_e32 vcc, s5, v21
	s_and_saveexec_b64 s[44:45], vcc
	s_cbranch_execz .LBB0_1477
	s_cmp_lt_i32 s82, 1
	s_cbranch_scc1 .LBB0_1477
	s_add_i32 s5, s15, s82
	s_add_i32 s8, s5, -1
	s_cmp_ge_i32 s8, s82
	s_cselect_b32 s9, s82, 0
	s_sub_i32 s8, s8, s9
	s_mul_hi_i32 s9, s8, s67
	s_mul_i32 s8, s8, s67
	s_add_u32 s50, s8, s68
	s_addc_u32 s51, s9, s79
	v_mov_b64_e32 v[22:23], 0x3ff
	v_cmp_gt_i64_e32 vcc, s[50:51], v[22:23]
	s_cbranch_vccnz .LBB0_1477
	s_ashr_i32 s8, s50, 31
	s_lshr_b32 s8, s8, 29
	s_add_i32 s9, s50, s8
	s_and_b32 s8, s9, -8
	s_sub_i32 s18, s50, s8
	s_cmp_gt_i32 s18, -1
	s_mov_b64 s[50:51], -1
	s_cbranch_scc0 .LBB0_1416
	s_lshl_b32 s8, s18, 7
	s_mov_b64 s[50:51], 0

; #define PG8_STAGEX(b, gbase) do { if constexpr (XR) { if (lane < 16) __builtin_amdgcn_global_load_lds((const unsigned*)((const char*)(gbase) + voffX), (PG8_LAS unsigned*)(lds + XR_OFF + (b) * 2048 + wid * 256), 16, 0, 0); } } while (0)
; #define PG8_LDX(b) do { if constexpr (XR) { _Pragma("unroll") for (int k = 0; k < 2; ++k) Ax_[k] = *(const PG8_LAS bf16x8*)(lds + XR_OFF + (b) * 2048 + aoffx + k * 1024); } } while (0)
; #define PG8_MMAX() do { if constexpr (XR) { if (hasx) { __builtin_amdgcn_s_setprio(1); if (wr == 0) PG8_MMAX_(B0); else PG8_MMAX_(B1); __builtin_amdgcn_s_setprio(0); } } } while (0)
; #define PG8_WAIT_LOOP() do { if constexpr (XR) PG8_WAIT_V(9); else PG8_WAIT_V(8); } while (0)
; #define PG8_STAGE(bufoff, gbase, voff) do { _Pragma("unroll") for (int _i = 0; _i < 2; ++_i) \
;         __builtin_amdgcn_global_load_lds((const unsigned*)((const char*)(gbase) + (voff)[_i]), (PG8_LAS unsigned*)(lds + (bufoff) + ldsw + _i * 8192), 16, 0, 0); } while (0)
; #define PG8_LDA(dst, b, h) do { _Pragma("unroll") for (int m = 0; m < 4; ++m) _Pragma("unroll") for (int k = 0; k < 2; ++k) dst[m][k] = *(const PG8_LAS bf16x8*)(lds + PG8_SA(b, h) + aoff + m * 2048 + k * 1024); } while (0)
; #define PG8_BAR __builtin_amdgcn_s_barrier()
; template <class Epi, class Sched, bool ALIGN_EPI = false, bool SP2 = false, bool DRAIN = true, bool XR = false>
; __device__ __forceinline__ void gemm_phase(PG8_LAS unsigned char* lds, const Gemm g, const Sched& S, const Epi& E) {
;     ...
;             const char* a1 = cA + PG8_KOA(t) + kstep;
;             const char* a2 = last ? nA + ka0 : cA + PG8_KOA(t + 2); const char* b2 = last ? nB + kb0 : cB + PG8_KOB(t + 2);
;             const char* x2 = XR ? (last ? nX + kx0 : cX + PG8_KOX(t + 2)) : nullptr; const char* x3 = XR ? x2 + kstep : nullptr;
;             const char* a3 = a2 + kstep; const char* b3 = b2 + kstep;
;             if (last && has_next) S.a_ready(nxt);
;             if constexpr (SP2) {
;             PG8_LDB(B0, 0, 0); PG8_LDB(B1, 0, 1); PG8_SCHED; PG8_LDA(At, 0, 0); PG8_LDX(0); PG8_STAGE(PG8_SA(1, 1), a1 + hstepA, voffA);
;             PG8_WAIT_LOOP(); PG8_WAIT_L(0); PG8_BAR; PG8_MMA(0, 0, At, B0); PG8_MMA(0, 1, At, B1); PG8_MMAX(); PG8_BAR; PG8_SCHED;
;             PG8_LDA(At, 0, 1); PG8_STAGE(PG8_SB(0, 0), b2, voffB); PG8_STAGE(PG8_SB(0, 1), b2 + hstep, voffB); PG8_STAGE(PG8_SA(0, 0), a2, voffA); PG8_STAGEX(0, x2);
.LBB0_1507:
	s_barrier
	s_add_i32 s64, s64, 2
	s_and_b32 s62, s64, s97
	s_lshr_b32 s84, s62, 2
	s_lshl_b32 s36, s62, 7
	s_lshl_b64 s[64:65], s[84:85], 9
	s_and_b32 s36, s36, 0x100
	s_add_u32 s63, s40, s64
	s_addc_u32 s64, s41, s65
	s_add_u32 s36, s63, s36
	s_mov_b32 s63, s85
	s_addc_u32 s64, s64, 0
	s_lshl_b64 s[62:63], s[62:63], 7
	s_add_u32 vcc_lo, s34, s62
	s_addc_u32 vcc_hi, s35, s63
	s_add_u32 s81, s42, s62
	s_addc_u32 s65, s43, s63
	s_cmp_eq_u32 s91, s70
	s_cselect_b32 s63, s8, s64
	s_cselect_b32 s62, s78, s36
	s_cselect_b32 s65, s69, s65
	s_cselect_b32 s64, s21, s81
	s_cselect_b32 vcc_hi, s20, vcc_hi
	s_cselect_b32 vcc_lo, s9, vcc_lo
	s_mov_b32 m0, s16
	v_lshl_add_u64 v[224:225], vcc, 0, v[214:215]
	v_lshl_add_u64 v[226:227], vcc, 0, v[218:219]
	s_add_u32 vcc_lo, vcc_lo, s28
	ds_read_b128 v[196:199], v249 offset:16384
	ds_read_b128 v[200:203], v249 offset:17408
	ds_read_b128 v[188:191], v249 offset:18432
	ds_read_b128 v[192:195], v249 offset:19456
	ds_read_b128 v[180:183], v249 offset:20480
	ds_read_b128 v[184:187], v249 offset:21504
	ds_read_b128 v[172:175], v249 offset:22528
	ds_read_b128 v[176:179], v249 offset:23552
	global_load_lds_dwordx4 v[224:225], off
	s_mov_b32 m0, s17
	s_addc_u32 vcc_hi, vcc_hi, s29
	global_load_lds_dwordx4 v[226:227], off
	v_lshl_add_u64 v[228:229], vcc, 0, v[214:215]
	s_mov_b32 m0, s93
	v_lshl_add_u64 v[230:231], vcc, 0, v[218:219]
	global_load_lds_dwordx4 v214, vcc
	s_mov_b32 m0, s24
	v_lshl_add_u64 v[232:233], s[62:63], 0, v[204:205]
	global_load_lds_dwordx4 v218, vcc
	s_mov_b32 m0, s90
	v_lshl_add_u64 v[234:235], s[62:63], 0, v[216:217]
	global_load_lds_dwordx4 v204, s[62:63]
	s_mov_b32 m0, s25
	v_lshl_add_u64 v[222:223], s[64:65], 0, v[220:221]
	global_load_lds_dwordx4 v216, s[62:63]
	s_and_saveexec_b64 s[64:65], s[2:3]
	s_cbranch_execz .LBB0_1509
	s_add_i32 s36, s26, 0
	s_add_i32 m0, s36, 0x22400
	s_nop 0
	global_load_lds_dwordx4 v[222:223], off
; #define PG8_LDX(b) do { if constexpr (XR) { _Pragma("unroll") for (int k = 0; k < 2; ++k) Ax_[k] = *(const PG8_LAS bf16x8*)(lds + XR_OFF + (b) * 2048 + aoffx + k * 1024); } } while (0)
; #define PG8_MMAX() do { if constexpr (XR) { if (hasx) { __builtin_amdgcn_s_setprio(1); if (wr == 0) PG8_MMAX_(B0); else PG8_MMAX_(B1); __builtin_amdgcn_s_setprio(0); } } } while (0)
; #define PG8_WAIT_LOOP() do { if constexpr (XR) PG8_WAIT_V(9); else PG8_WAIT_V(8); } while (0)
; #define PG8_STAGE(bufoff, gbase, voff) do { _Pragma("unroll") for (int _i = 0; _i < 2; ++_i) \
;         __builtin_amdgcn_global_load_lds((const unsigned*)((const char*)(gbase) + (voff)[_i]), (PG8_LAS unsigned*)(lds + (bufoff) + ldsw + _i * 8192), 16, 0, 0); } while (0)
; #define PG8_LDA(dst, b, h) do { _Pragma("unroll") for (int m = 0; m < 4; ++m) _Pragma("unroll") for (int k = 0; k < 2; ++k) dst[m][k] = *(const PG8_LAS bf16x8*)(lds + PG8_SA(b, h) + aoff + m * 2048 + k * 1024); } while (0)
; #define PG8_LDB(dst, b, h) do { _Pragma("unroll") for (int n = 0; n < 2; ++n) _Pragma("unroll") for (int k = 0; k < 2; ++k) dst[n][k] = *(const PG8_LAS bf16x8*)(lds + PG8_SB(b, h) + boff + n * 2048 + k * 1024); } while (0)
; #define PG8_MMA(ai, bj, At, Bt) do { __builtin_amdgcn_s_setprio(1); _Pragma("unroll") for (int m = 0; m < 4; ++m) _Pragma("unroll") for (int n = 0; n < 2; ++n) _Pragma("unroll") for (int k = 0; k < 2; ++k) \
;         acc[ai][bj][m][n] = __builtin_amdgcn_mfma_f32_16x16x32_bf16(Bt[n][k], At[m][k], acc[ai][bj][m][n], 0, 0, 0); __builtin_amdgcn_s_setprio(0); } while (0)
; #define PG8_WAIT_L(n) asm volatile("s_waitcnt lgkmcnt(" #n ")" ::: "memory")
; #define PG8_BAR __builtin_amdgcn_s_barrier()
; #define PG8_SCHED __builtin_amdgcn_sched_barrier(0)
; template <class Epi, class Sched, bool ALIGN_EPI = false, bool SP2 = false, bool DRAIN = true, bool XR = false>
; __device__ __forceinline__ void gemm_phase(PG8_LAS unsigned char* lds, const Gemm g, const Sched& S, const Epi& E) {
;     ...
;             PG8_WAIT_LOOP(); PG8_WAIT_L(0); PG8_BAR; PG8_MMA(1, 0, At, B0); PG8_MMA(1, 1, At, B1); PG8_BAR; PG8_SCHED;
;             PG8_LDB(B0, 1, 0); PG8_LDB(B1, 1, 1); PG8_SCHED; PG8_LDA(At, 1, 0); PG8_LDX(1); PG8_STAGE(PG8_SA(0, 1), a2 + hstepA, voffA);
;             PG8_WAIT_LOOP(); PG8_WAIT_L(0); PG8_BAR; PG8_MMA(0, 0, At, B0); PG8_MMA(0, 1, At, B1); PG8_MMAX(); PG8_BAR; PG8_SCHED;
.LBB0_1509:
	s_or_b64 exec, exec, s[64:65]
	s_waitcnt vmcnt(9)
	s_waitcnt lgkmcnt(0)
	s_setprio 1
	s_barrier
	v_mfma_f32_16x16x32_bf16 v[72:75], v[156:159], v[196:199], v[72:75]
	v_mfma_f32_16x16x32_bf16 v[68:71], v[164:167], v[196:199], v[68:71]
	v_mfma_f32_16x16x32_bf16 v[64:67], v[156:159], v[188:191], v[64:67]
	v_mfma_f32_16x16x32_bf16 v[60:63], v[164:167], v[188:191], v[60:63]
	v_mfma_f32_16x16x32_bf16 v[56:59], v[156:159], v[180:183], v[56:59]
	v_mfma_f32_16x16x32_bf16 v[52:55], v[164:167], v[180:183], v[52:55]
	v_mfma_f32_16x16x32_bf16 v[48:51], v[156:159], v[172:175], v[48:51]
	v_mfma_f32_16x16x32_bf16 v[44:47], v[164:167], v[172:175], v[44:47]
	v_mfma_f32_16x16x32_bf16 v[72:75], v[160:163], v[200:203], v[72:75]
	v_mfma_f32_16x16x32_bf16 v[68:71], v[168:171], v[200:203], v[68:71]
	v_mfma_f32_16x16x32_bf16 v[64:67], v[160:163], v[192:195], v[64:67]
	v_mfma_f32_16x16x32_bf16 v[60:63], v[168:171], v[192:195], v[60:63]
	v_mfma_f32_16x16x32_bf16 v[56:59], v[160:163], v[184:187], v[56:59]
	v_mfma_f32_16x16x32_bf16 v[52:55], v[168:171], v[184:187], v[52:55]
	v_mfma_f32_16x16x32_bf16 v[48:51], v[160:163], v[176:179], v[48:51]
	v_mfma_f32_16x16x32_bf16 v[44:47], v[168:171], v[176:179], v[44:47]
	v_mfma_f32_16x16x32_bf16 v[40:43], v[140:143], v[196:199], v[40:43]
	v_mfma_f32_16x16x32_bf16 v[36:39], v[148:151], v[196:199], v[36:39]
	v_mfma_f32_16x16x32_bf16 v[32:35], v[140:143], v[188:191], v[32:35]
	v_mfma_f32_16x16x32_bf16 v[28:31], v[148:151], v[188:191], v[28:31]
	v_mfma_f32_16x16x32_bf16 v[24:27], v[140:143], v[180:183], v[24:27]
	v_mfma_f32_16x16x32_bf16 v[20:23], v[148:151], v[180:183], v[20:23]
	v_mfma_f32_16x16x32_bf16 v[16:19], v[140:143], v[172:175], v[16:19]
	v_mfma_f32_16x16x32_bf16 v[12:15], v[148:151], v[172:175], v[12:15]
	v_mfma_f32_16x16x32_bf16 v[40:43], v[144:147], v[200:203], v[40:43]
	v_mfma_f32_16x16x32_bf16 v[36:39], v[152:155], v[200:203], v[36:39]
	v_mfma_f32_16x16x32_bf16 v[32:35], v[144:147], v[192:195], v[32:35]
	v_mfma_f32_16x16x32_bf16 v[28:31], v[152:155], v[192:195], v[28:31]
	v_mfma_f32_16x16x32_bf16 v[24:27], v[144:147], v[184:187], v[24:27]
	v_mfma_f32_16x16x32_bf16 v[20:23], v[152:155], v[184:187], v[20:23]
	v_mfma_f32_16x16x32_bf16 v[16:19], v[144:147], v[176:179], v[16:19]
	v_mfma_f32_16x16x32_bf16 v[12:15], v[152:155], v[176:179], v[12:15]
	s_barrier
	s_setprio 0
	v_add_u32_e32 v140, 0x18000, v248
	v_add_u32_e32 v152, 0x1c000, v248
	ds_read_b128 v[156:159], v140
	ds_read_b128 v[160:163], v140 offset:1024
	ds_read_b128 v[164:167], v140 offset:2048
	ds_read_b128 v[168:171], v140 offset:3072
	ds_read_b128 v[140:143], v152
	ds_read_b128 v[144:147], v152 offset:1024
	ds_read_b128 v[148:151], v152 offset:2048
	ds_read_b128 v[152:155], v152 offset:3072
	s_add_u32 s62, s62, s28
	s_addc_u32 s63, s63, s29
	s_mov_b32 m0, s12
	v_add_u32_e32 v176, 0x22c00, v250
	ds_read_b128 v[180:183], v249 offset:32768
	ds_read_b128 v[184:187], v249 offset:33792
	ds_read_b128 v[188:191], v249 offset:34816
	ds_read_b128 v[192:195], v249 offset:35840
	ds_read_b128 v[196:199], v249 offset:36864
	ds_read_b128 v[200:203], v249 offset:37888
	ds_read_b128 v[206:209], v249 offset:38912
	ds_read_b128 v[242:245], v249 offset:39936
	ds_read_b128 v[172:175], v176
	ds_read_b128 v[176:179], v176 offset:1024
	global_load_lds_dwordx4 v204, s[62:63]
	s_mov_b32 m0, s13
	s_nop 0
	global_load_lds_dwordx4 v216, s[62:63]
	s_waitcnt vmcnt(9)
	s_waitcnt lgkmcnt(0)
	s_setprio 1
	s_barrier
	v_mfma_f32_16x16x32_bf16 v[136:139], v[156:159], v[180:183], v[136:139]
	v_mfma_f32_16x16x32_bf16 v[132:135], v[164:167], v[180:183], v[132:135]
	v_mfma_f32_16x16x32_bf16 v[128:131], v[156:159], v[188:191], v[128:131]
	v_mfma_f32_16x16x32_bf16 v[124:127], v[164:167], v[188:191], v[124:127]
	v_mfma_f32_16x16x32_bf16 v[120:123], v[156:159], v[196:199], v[120:123]
	v_mfma_f32_16x16x32_bf16 v[116:119], v[164:167], v[196:199], v[116:119]
	v_mfma_f32_16x16x32_bf16 v[112:115], v[156:159], v[206:209], v[112:115]
	v_mfma_f32_16x16x32_bf16 v[108:111], v[164:167], v[206:209], v[108:111]
	v_mfma_f32_16x16x32_bf16 v[136:139], v[160:163], v[184:187], v[136:139]
	v_mfma_f32_16x16x32_bf16 v[132:135], v[168:171], v[184:187], v[132:135]
	v_mfma_f32_16x16x32_bf16 v[128:131], v[160:163], v[192:195], v[128:131]
	v_mfma_f32_16x16x32_bf16 v[124:127], v[168:171], v[192:195], v[124:127]
	v_mfma_f32_16x16x32_bf16 v[120:123], v[160:163], v[200:203], v[120:123]
	v_mfma_f32_16x16x32_bf16 v[116:119], v[168:171], v[200:203], v[116:119]
	v_mfma_f32_16x16x32_bf16 v[112:115], v[160:163], v[242:245], v[112:115]
	v_mfma_f32_16x16x32_bf16 v[108:111], v[168:171], v[242:245], v[108:111]
	v_mfma_f32_16x16x32_bf16 v[104:107], v[140:143], v[180:183], v[104:107]
	v_mfma_f32_16x16x32_bf16 v[100:103], v[148:151], v[180:183], v[100:103]
	v_mfma_f32_16x16x32_bf16 v[96:99], v[140:143], v[188:191], v[96:99]
	v_mfma_f32_16x16x32_bf16 v[92:95], v[148:151], v[188:191], v[92:95]
	v_mfma_f32_16x16x32_bf16 v[88:91], v[140:143], v[196:199], v[88:91]
	v_mfma_f32_16x16x32_bf16 v[84:87], v[148:151], v[196:199], v[84:87]
	v_mfma_f32_16x16x32_bf16 v[80:83], v[140:143], v[206:209], v[80:83]
	v_mfma_f32_16x16x32_bf16 v[76:79], v[148:151], v[206:209], v[76:79]
	v_mfma_f32_16x16x32_bf16 v[104:107], v[144:147], v[184:187], v[104:107]
	v_mfma_f32_16x16x32_bf16 v[100:103], v[152:155], v[184:187], v[100:103]
	v_mfma_f32_16x16x32_bf16 v[96:99], v[144:147], v[192:195], v[96:99]
	v_mfma_f32_16x16x32_bf16 v[92:95], v[152:155], v[192:195], v[92:95]
	v_mfma_f32_16x16x32_bf16 v[88:91], v[144:147], v[200:203], v[88:91]
	v_mfma_f32_16x16x32_bf16 v[84:87], v[152:155], v[200:203], v[84:87]
	v_mfma_f32_16x16x32_bf16 v[80:83], v[144:147], v[242:245], v[80:83]
	v_mfma_f32_16x16x32_bf16 v[76:79], v[152:155], v[242:245], v[76:79]
	s_setprio 0
	s_and_b64 vcc, exec, s[6:7]
	s_cbranch_vccnz .LBB0_1515
	s_setprio 1
	s_and_b64 vcc, exec, s[4:5]
	s_mov_b64 s[4:5], -1
	s_cbranch_vccnz .LBB0_1512
	v_mfma_f32_16x16x32_bf16 v[8:11], v[140:143], v[172:175], v[8:11]
	s_mov_b64 s[4:5], 0
	v_mfma_f32_16x16x32_bf16 v[4:7], v[148:151], v[172:175], v[4:7]
	v_mfma_f32_16x16x32_bf16 v[8:11], v[144:147], v[176:179], v[8:11]
	v_mfma_f32_16x16x32_bf16 v[4:7], v[152:155], v[176:179], v[4:7]

;     template <class Sched> __device__ __forceinline__ void prehook(const Sched& S, const Unit& u0) const { rtab_hook(S, u0, pre, ssq, (PG8_LAS float*)rtab); }
; #define PG8_STAGEX(b, gbase) do { if constexpr (XR) { if (lane < 16) __builtin_amdgcn_global_load_lds((const unsigned*)((const char*)(gbase) + voffX), (PG8_LAS unsigned*)(lds + XR_OFF + (b) * 2048 + wid * 256), 16, 0, 0); } } while (0)
; #define PG8_STAGE(bufoff, gbase, voff) do { _Pragma("unroll") for (int _i = 0; _i < 2; ++_i) \
;         __builtin_amdgcn_global_load_lds((const unsigned*)((const char*)(gbase) + (voff)[_i]), (PG8_LAS unsigned*)(lds + (bufoff) + ldsw + _i * 8192), 16, 0, 0); } while (0)
; #define PG8_BAR __builtin_amdgcn_s_barrier()
;     template <class Sched> __device__ __forceinline__ void prehook(const Sched& S, const Unit& u0) const { rtab_hook(S, u0, pre, ssq_in, (PG8_LAS float*)rtab); }
; template <class Epi, class Sched, bool ALIGN_EPI = false, bool SP2 = false, bool DRAIN = true, bool XR = false>
; __device__ __forceinline__ void gemm_phase(PG8_LAS unsigned char* lds, const Gemm g, const Sched& S, const Epi& E) {
;     ...
;         PG8_STAGE(PG8_SB(0, 0), cB + kb0, voffB); PG8_STAGE(PG8_SB(0, 1), cB + kb0 + hstep, voffB); PG8_STAGE(PG8_SA(0, 0), cA + ka0, voffA); PG8_STAGEX(0, cX + kx0); PG8_STAGE(PG8_SA(0, 1), cA + ka0 + hstepA, voffA);
;         if constexpr (Epi::PREHOOK) E.prehook(S, cur);
;         if (wr == 1) PG8_BAR;
.LBB0_1630:
	s_or_b64 exec, exec, s[12:13]
	s_ashr_i32 s71, s24, 8
	s_add_u32 s12, s16, 0x10000
	v_mov_b32_e32 v215, v3
	s_addc_u32 s13, s17, 0
	s_add_i32 s72, s63, 0x4000
	v_mov_b32_e32 v219, v3
	s_mov_b32 m0, s72
	s_add_i32 s73, s63, 0x6000
	global_load_lds_dwordx4 v214, s[12:13]
	s_mov_b32 m0, s73
	s_cmp_eq_u32 s71, 1
	global_load_lds_dwordx4 v218, s[12:13]
	s_cselect_b64 s[12:13], -1, 0
	v_writelane_b32 v253, s12, 33
	s_cmp_lg_u32 s71, 1
	s_nop 0
	v_writelane_b32 v253, s13, 34
	s_cbranch_scc1 .LBB0_1632
	s_barrier

; #define PG8_LDX(b) do { if constexpr (XR) { _Pragma("unroll") for (int k = 0; k < 2; ++k) Ax_[k] = *(const PG8_LAS bf16x8*)(lds + XR_OFF + (b) * 2048 + aoffx + k * 1024); } } while (0)
; #define PG8_MMAX() do { if constexpr (XR) { if (hasx) { __builtin_amdgcn_s_setprio(1); if (wr == 0) PG8_MMAX_(B0); else PG8_MMAX_(B1); __builtin_amdgcn_s_setprio(0); } } } while (0)
; #define PG8_WAIT_LOOP() do { if constexpr (XR) PG8_WAIT_V(9); else PG8_WAIT_V(8); } while (0)
; #define PG8_STAGE(bufoff, gbase, voff) do { _Pragma("unroll") for (int _i = 0; _i < 2; ++_i) \
;         __builtin_amdgcn_global_load_lds((const unsigned*)((const char*)(gbase) + (voff)[_i]), (PG8_LAS unsigned*)(lds + (bufoff) + ldsw + _i * 8192), 16, 0, 0); } while (0)
; #define PG8_LDA(dst, b, h) do { _Pragma("unroll") for (int m = 0; m < 4; ++m) _Pragma("unroll") for (int k = 0; k < 2; ++k) dst[m][k] = *(const PG8_LAS bf16x8*)(lds + PG8_SA(b, h) + aoff + m * 2048 + k * 1024); } while (0)
; #define PG8_LDB(dst, b, h) do { _Pragma("unroll") for (int n = 0; n < 2; ++n) _Pragma("unroll") for (int k = 0; k < 2; ++k) dst[n][k] = *(const PG8_LAS bf16x8*)(lds + PG8_SB(b, h) + boff + n * 2048 + k * 1024); } while (0)
; #define PG8_MMA(ai, bj, At, Bt) do { __builtin_amdgcn_s_setprio(1); _Pragma("unroll") for (int m = 0; m < 4; ++m) _Pragma("unroll") for (int n = 0; n < 2; ++n) _Pragma("unroll") for (int k = 0; k < 2; ++k) \
;         acc[ai][bj][m][n] = __builtin_amdgcn_mfma_f32_16x16x32_bf16(Bt[n][k], At[m][k], acc[ai][bj][m][n], 0, 0, 0); __builtin_amdgcn_s_setprio(0); } while (0)
; #define PG8_WAIT_L(n) asm volatile("s_waitcnt lgkmcnt(" #n ")" ::: "memory")
; #define PG8_BAR __builtin_amdgcn_s_barrier()
; #define PG8_SCHED __builtin_amdgcn_sched_barrier(0)
; template <class Epi, class Sched, bool ALIGN_EPI = false, bool SP2 = false, bool DRAIN = true, bool XR = false>
; __device__ __forceinline__ void gemm_phase(PG8_LAS unsigned char* lds, const Gemm g, const Sched& S, const Epi& E) {
;     ...
;             PG8_LDB(B0, 0, 0); PG8_LDB(B1, 0, 1); PG8_SCHED; PG8_LDA(At, 0, 0); PG8_LDX(0); PG8_STAGE(PG8_SA(1, 1), a1 + hstepA, voffA);
;             PG8_WAIT_LOOP(); PG8_WAIT_L(0); PG8_BAR; PG8_MMA(0, 0, At, B0); PG8_MMA(0, 1, At, B1); PG8_MMAX(); PG8_BAR; PG8_SCHED;
.LBB0_1652:
	v_add_u32_e32 v2, 0x10000, v248
	s_add_i32 s46, s54, s89
	ds_read_b128 v[158:161], v2
	ds_read_b128 v[162:165], v2 offset:1024
	ds_read_b128 v[166:169], v2 offset:2048
	ds_read_b128 v[170:173], v2 offset:3072
	v_add_u32_e32 v2, 0x14000, v248
	s_and_b32 s6, s46, s59
	ds_read_b128 v[142:145], v2
	ds_read_b128 v[146:149], v2 offset:1024
	ds_read_b128 v[150:153], v2 offset:2048
	ds_read_b128 v[154:157], v2 offset:3072
	s_lshr_b32 s84, s6, 2
	s_lshl_b32 s6, s6, 7
	s_lshl_b64 s[0:1], s[84:85], 17
	s_and_b32 s6, s6, 0x100
	s_add_u32 s0, s40, s0
	s_addc_u32 s1, s41, s1
	s_add_u32 s0, s0, s6
	s_addc_u32 s1, s1, 0
	s_add_u32 s0, s0, 0x10080
	s_addc_u32 s1, s1, 0
	v_add_u32_e32 v2, 0x22400, v250
	s_add_i32 m0, s63, 0xc000
	ds_read_b128 v[182:185], v249
	ds_read_b128 v[186:189], v249 offset:1024
	ds_read_b128 v[190:193], v249 offset:2048
	ds_read_b128 v[194:197], v249 offset:3072
	ds_read_b128 v[198:201], v249 offset:4096
	ds_read_b128 v[202:205], v249 offset:5120
	ds_read_b128 v[206:209], v249 offset:6144
	ds_read_b128 v[224:227], v249 offset:7168
	ds_read_b128 v[174:177], v2
	ds_read_b128 v[178:181], v2 offset:1024
	global_load_lds_dwordx4 v214, s[0:1]
	s_add_i32 m0, s63, 0xe000
	s_nop 0
	global_load_lds_dwordx4 v218, s[0:1]
	s_waitcnt vmcnt(9)
	s_waitcnt lgkmcnt(0)
	s_setprio 1
	s_barrier
	v_mfma_f32_16x16x32_bf16 v[138:141], v[158:161], v[182:185], v[138:141]
	v_mfma_f32_16x16x32_bf16 v[134:137], v[166:169], v[182:185], v[134:137]
	v_mfma_f32_16x16x32_bf16 v[122:125], v[158:161], v[190:193], v[122:125]
	v_mfma_f32_16x16x32_bf16 v[118:121], v[166:169], v[190:193], v[118:121]
	v_mfma_f32_16x16x32_bf16 v[106:109], v[158:161], v[198:201], v[106:109]
	v_mfma_f32_16x16x32_bf16 v[102:105], v[166:169], v[198:201], v[102:105]
	v_mfma_f32_16x16x32_bf16 v[90:93], v[158:161], v[206:209], v[90:93]
	v_mfma_f32_16x16x32_bf16 v[86:89], v[166:169], v[206:209], v[86:89]
	v_mfma_f32_16x16x32_bf16 v[138:141], v[162:165], v[186:189], v[138:141]
	v_mfma_f32_16x16x32_bf16 v[134:137], v[170:173], v[186:189], v[134:137]
	v_mfma_f32_16x16x32_bf16 v[122:125], v[162:165], v[194:197], v[122:125]
	v_mfma_f32_16x16x32_bf16 v[118:121], v[170:173], v[194:197], v[118:121]
	v_mfma_f32_16x16x32_bf16 v[106:109], v[162:165], v[202:205], v[106:109]
	v_mfma_f32_16x16x32_bf16 v[102:105], v[170:173], v[202:205], v[102:105]
	v_mfma_f32_16x16x32_bf16 v[90:93], v[162:165], v[224:227], v[90:93]
	v_mfma_f32_16x16x32_bf16 v[86:89], v[170:173], v[224:227], v[86:89]
	v_mfma_f32_16x16x32_bf16 v[130:133], v[142:145], v[182:185], v[130:133]
	v_mfma_f32_16x16x32_bf16 v[126:129], v[150:153], v[182:185], v[126:129]
	v_mfma_f32_16x16x32_bf16 v[114:117], v[142:145], v[190:193], v[114:117]
	v_mfma_f32_16x16x32_bf16 v[110:113], v[150:153], v[190:193], v[110:113]
	v_mfma_f32_16x16x32_bf16 v[98:101], v[142:145], v[198:201], v[98:101]
	v_mfma_f32_16x16x32_bf16 v[94:97], v[150:153], v[198:201], v[94:97]
	v_mfma_f32_16x16x32_bf16 v[82:85], v[142:145], v[206:209], v[82:85]
	v_mfma_f32_16x16x32_bf16 v[78:81], v[150:153], v[206:209], v[78:81]
	v_mfma_f32_16x16x32_bf16 v[130:133], v[146:149], v[186:189], v[130:133]
	v_mfma_f32_16x16x32_bf16 v[126:129], v[154:157], v[186:189], v[126:129]
	v_mfma_f32_16x16x32_bf16 v[114:117], v[146:149], v[194:197], v[114:117]
	v_mfma_f32_16x16x32_bf16 v[110:113], v[154:157], v[194:197], v[110:113]
	v_mfma_f32_16x16x32_bf16 v[98:101], v[146:149], v[202:205], v[98:101]
	v_mfma_f32_16x16x32_bf16 v[94:97], v[154:157], v[202:205], v[94:97]
	v_mfma_f32_16x16x32_bf16 v[82:85], v[146:149], v[224:227], v[82:85]
	v_mfma_f32_16x16x32_bf16 v[78:81], v[154:157], v[224:227], v[78:81]
	s_setprio 0
	v_cndmask_b32_e64 v2, 0, 1, s[30:31]
	v_cmp_ne_u32_e64 s[6:7], 1, v2
	v_cndmask_b32_e64 v2, 0, 1, s[22:23]
	s_andn2_b64 vcc, exec, s[30:31]
	v_cmp_ne_u32_e64 s[0:1], 1, v2
	s_cbranch_vccnz .LBB0_1658
	s_setprio 1
	s_and_b64 vcc, exec, s[0:1]
	s_mov_b64 s[44:45], -1
	s_cbranch_vccnz .LBB0_1655
	v_mfma_f32_16x16x32_bf16 v[10:13], v[142:145], v[174:177], v[10:13]
	s_mov_b64 s[44:45], 0
	v_mfma_f32_16x16x32_bf16 v[6:9], v[150:153], v[174:177], v[6:9]
	v_mfma_f32_16x16x32_bf16 v[10:13], v[146:149], v[178:181], v[10:13]
	v_mfma_f32_16x16x32_bf16 v[6:9], v[154:157], v[178:181], v[6:9]

; #define PG8_STAGEX(b, gbase) do { if constexpr (XR) { if (lane < 16) __builtin_amdgcn_global_load_lds((const unsigned*)((const char*)(gbase) + voffX), (PG8_LAS unsigned*)(lds + XR_OFF + (b) * 2048 + wid * 256), 16, 0, 0); } } while (0)
; #define PG8_LDX(b) do { if constexpr (XR) { _Pragma("unroll") for (int k = 0; k < 2; ++k) Ax_[k] = *(const PG8_LAS bf16x8*)(lds + XR_OFF + (b) * 2048 + aoffx + k * 1024); } } while (0)
; #define PG8_MMAX() do { if constexpr (XR) { if (hasx) { __builtin_amdgcn_s_setprio(1); if (wr == 0) PG8_MMAX_(B0); else PG8_MMAX_(B1); __builtin_amdgcn_s_setprio(0); } } } while (0)
; #define PG8_WAIT_LOOP() do { if constexpr (XR) PG8_WAIT_V(9); else PG8_WAIT_V(8); } while (0)
; #define PG8_STAGE(bufoff, gbase, voff) do { _Pragma("unroll") for (int _i = 0; _i < 2; ++_i) \
;         __builtin_amdgcn_global_load_lds((const unsigned*)((const char*)(gbase) + (voff)[_i]), (PG8_LAS unsigned*)(lds + (bufoff) + ldsw + _i * 8192), 16, 0, 0); } while (0)
; #define PG8_LDA(dst, b, h) do { _Pragma("unroll") for (int m = 0; m < 4; ++m) _Pragma("unroll") for (int k = 0; k < 2; ++k) dst[m][k] = *(const PG8_LAS bf16x8*)(lds + PG8_SA(b, h) + aoff + m * 2048 + k * 1024); } while (0)
; #define PG8_BAR __builtin_amdgcn_s_barrier()
; template <class Epi, class Sched, bool ALIGN_EPI = false, bool SP2 = false, bool DRAIN = true, bool XR = false>
; __device__ __forceinline__ void gemm_phase(PG8_LAS unsigned char* lds, const Gemm g, const Sched& S, const Epi& E) {
;     ...
;             const char* a1 = cA + PG8_KOA(t) + kstep;
;             const char* a2 = last ? nA + ka0 : cA + PG8_KOA(t + 2); const char* b2 = last ? nB + kb0 : cB + PG8_KOB(t + 2);
;             const char* x2 = XR ? (last ? nX + kx0 : cX + PG8_KOX(t + 2)) : nullptr; const char* x3 = XR ? x2 + kstep : nullptr;
;             const char* a3 = a2 + kstep; const char* b3 = b2 + kstep;
;             if (last && has_next) S.a_ready(nxt);
;             if constexpr (SP2) {
;             PG8_LDB(B0, 0, 0); PG8_LDB(B1, 0, 1); PG8_SCHED; PG8_LDA(At, 0, 0); PG8_LDX(0); PG8_STAGE(PG8_SA(1, 1), a1 + hstepA, voffA);
;             PG8_WAIT_LOOP(); PG8_WAIT_L(0); PG8_BAR; PG8_MMA(0, 0, At, B0); PG8_MMA(0, 1, At, B1); PG8_MMAX(); PG8_BAR; PG8_SCHED;
;             PG8_LDA(At, 0, 1); PG8_STAGE(PG8_SB(0, 0), b2, voffB); PG8_STAGE(PG8_SB(0, 1), b2 + hstep, voffB); PG8_STAGE(PG8_SA(0, 0), a2, voffA); PG8_STAGEX(0, x2);
.LBB0_1658:
	s_barrier
	s_add_i32 s46, s46, 2
	s_and_b32 s44, s46, s59
	s_lshr_b32 s84, s44, 2
	s_lshl_b32 s36, s44, 7
	s_lshl_b64 s[46:47], s[84:85], 17
	s_and_b32 s36, s36, 0x100
	s_add_u32 s45, s40, s46
	s_addc_u32 s46, s41, s47
	s_add_u32 s36, s45, s36
	s_mov_b32 s45, s85
	s_addc_u32 s46, s46, 0
	s_lshl_b64 s[44:45], s[44:45], 7
	s_add_u32 vcc_lo, s34, s44
	s_addc_u32 vcc_hi, s35, s45
	s_add_u32 s12, s42, s44
	s_addc_u32 s13, s43, s45
	s_cmp_eq_u32 s82, s89
	s_cselect_b32 s45, s39, s46
	s_cselect_b32 s44, s93, s36
	s_cselect_b32 s47, s90, s13
	s_cselect_b32 s46, s97, s12
	s_cselect_b32 vcc_hi, s96, vcc_hi
	s_cselect_b32 vcc_lo, s50, vcc_lo
	s_mov_b32 m0, s64
	v_lshl_add_u64 v[224:225], vcc, 0, v[216:217]
	v_lshl_add_u64 v[226:227], vcc, 0, v[220:221]
	s_add_u32 vcc_lo, vcc_lo, s8
	ds_read_b128 v[198:201], v249 offset:16384
	ds_read_b128 v[202:205], v249 offset:17408
	ds_read_b128 v[190:193], v249 offset:18432
	ds_read_b128 v[194:197], v249 offset:19456
	ds_read_b128 v[182:185], v249 offset:20480
	ds_read_b128 v[186:189], v249 offset:21504
	ds_read_b128 v[174:177], v249 offset:22528
	ds_read_b128 v[178:181], v249 offset:23552
	global_load_lds_dwordx4 v[224:225], off
	s_mov_b32 m0, s65
	s_addc_u32 vcc_hi, vcc_hi, s9
	global_load_lds_dwordx4 v[226:227], off
	v_lshl_add_u64 v[228:229], vcc, 0, v[216:217]
	s_mov_b32 m0, s67
	v_lshl_add_u64 v[230:231], vcc, 0, v[220:221]
	global_load_lds_dwordx4 v216, vcc
	s_mov_b32 m0, s68
	v_lshl_add_u64 v[232:233], s[44:45], 0, v[214:215]
	global_load_lds_dwordx4 v220, vcc
	s_mov_b32 m0, s63
	v_lshl_add_u64 v[234:235], s[44:45], 0, v[218:219]
	global_load_lds_dwordx4 v214, s[44:45]
	s_mov_b32 m0, s69
	v_lshl_add_u64 v[4:5], s[46:47], 0, v[222:223]
	global_load_lds_dwordx4 v218, s[44:45]
	s_and_saveexec_b64 s[46:47], s[2:3]
	s_cbranch_execz .LBB0_1660
	s_add_i32 s12, s60, 0
	s_add_i32 m0, s12, 0x22400
	s_nop 0
	global_load_lds_dwordx4 v[4:5], off
; #define PG8_LDX(b) do { if constexpr (XR) { _Pragma("unroll") for (int k = 0; k < 2; ++k) Ax_[k] = *(const PG8_LAS bf16x8*)(lds + XR_OFF + (b) * 2048 + aoffx + k * 1024); } } while (0)
; #define PG8_MMAX() do { if constexpr (XR) { if (hasx) { __builtin_amdgcn_s_setprio(1); if (wr == 0) PG8_MMAX_(B0); else PG8_MMAX_(B1); __builtin_amdgcn_s_setprio(0); } } } while (0)
; #define PG8_WAIT_LOOP() do { if constexpr (XR) PG8_WAIT_V(9); else PG8_WAIT_V(8); } while (0)
; #define PG8_STAGE(bufoff, gbase, voff) do { _Pragma("unroll") for (int _i = 0; _i < 2; ++_i) \
;         __builtin_amdgcn_global_load_lds((const unsigned*)((const char*)(gbase) + (voff)[_i]), (PG8_LAS unsigned*)(lds + (bufoff) + ldsw + _i * 8192), 16, 0, 0); } while (0)
; #define PG8_LDA(dst, b, h) do { _Pragma("unroll") for (int m = 0; m < 4; ++m) _Pragma("unroll") for (int k = 0; k < 2; ++k) dst[m][k] = *(const PG8_LAS bf16x8*)(lds + PG8_SA(b, h) + aoff + m * 2048 + k * 1024); } while (0)
; #define PG8_LDB(dst, b, h) do { _Pragma("unroll") for (int n = 0; n < 2; ++n) _Pragma("unroll") for (int k = 0; k < 2; ++k) dst[n][k] = *(const PG8_LAS bf16x8*)(lds + PG8_SB(b, h) + boff + n * 2048 + k * 1024); } while (0)
; #define PG8_MMA(ai, bj, At, Bt) do { __builtin_amdgcn_s_setprio(1); _Pragma("unroll") for (int m = 0; m < 4; ++m) _Pragma("unroll") for (int n = 0; n < 2; ++n) _Pragma("unroll") for (int k = 0; k < 2; ++k) \
;         acc[ai][bj][m][n] = __builtin_amdgcn_mfma_f32_16x16x32_bf16(Bt[n][k], At[m][k], acc[ai][bj][m][n], 0, 0, 0); __builtin_amdgcn_s_setprio(0); } while (0)
; #define PG8_WAIT_L(n) asm volatile("s_waitcnt lgkmcnt(" #n ")" ::: "memory")
; #define PG8_BAR __builtin_amdgcn_s_barrier()
; #define PG8_SCHED __builtin_amdgcn_sched_barrier(0)
; template <class Epi, class Sched, bool ALIGN_EPI = false, bool SP2 = false, bool DRAIN = true, bool XR = false>
; __device__ __forceinline__ void gemm_phase(PG8_LAS unsigned char* lds, const Gemm g, const Sched& S, const Epi& E) {
;     ...
;             PG8_WAIT_LOOP(); PG8_WAIT_L(0); PG8_BAR; PG8_MMA(1, 0, At, B0); PG8_MMA(1, 1, At, B1); PG8_BAR; PG8_SCHED;
;             PG8_LDB(B0, 1, 0); PG8_LDB(B1, 1, 1); PG8_SCHED; PG8_LDA(At, 1, 0); PG8_LDX(1); PG8_STAGE(PG8_SA(0, 1), a2 + hstepA, voffA);
;             PG8_WAIT_LOOP(); PG8_WAIT_L(0); PG8_BAR; PG8_MMA(0, 0, At, B0); PG8_MMA(0, 1, At, B1); PG8_MMAX(); PG8_BAR; PG8_SCHED;
.LBB0_1660:
	s_or_b64 exec, exec, s[46:47]
	s_waitcnt vmcnt(9)
	s_waitcnt lgkmcnt(0)
	s_setprio 1
	s_barrier
	v_mfma_f32_16x16x32_bf16 v[74:77], v[158:161], v[198:201], v[74:77]
	v_mfma_f32_16x16x32_bf16 v[70:73], v[166:169], v[198:201], v[70:73]
	v_mfma_f32_16x16x32_bf16 v[58:61], v[158:161], v[190:193], v[58:61]
	v_mfma_f32_16x16x32_bf16 v[54:57], v[166:169], v[190:193], v[54:57]
	v_mfma_f32_16x16x32_bf16 v[42:45], v[158:161], v[182:185], v[42:45]
	v_mfma_f32_16x16x32_bf16 v[38:41], v[166:169], v[182:185], v[38:41]
	v_mfma_f32_16x16x32_bf16 v[26:29], v[158:161], v[174:177], v[26:29]
	v_mfma_f32_16x16x32_bf16 v[22:25], v[166:169], v[174:177], v[22:25]
	v_mfma_f32_16x16x32_bf16 v[74:77], v[162:165], v[202:205], v[74:77]
	v_mfma_f32_16x16x32_bf16 v[70:73], v[170:173], v[202:205], v[70:73]
	v_mfma_f32_16x16x32_bf16 v[58:61], v[162:165], v[194:197], v[58:61]
	v_mfma_f32_16x16x32_bf16 v[54:57], v[170:173], v[194:197], v[54:57]
	v_mfma_f32_16x16x32_bf16 v[42:45], v[162:165], v[186:189], v[42:45]
	v_mfma_f32_16x16x32_bf16 v[38:41], v[170:173], v[186:189], v[38:41]
	v_mfma_f32_16x16x32_bf16 v[26:29], v[162:165], v[178:181], v[26:29]
	v_mfma_f32_16x16x32_bf16 v[22:25], v[170:173], v[178:181], v[22:25]
	v_mfma_f32_16x16x32_bf16 v[66:69], v[142:145], v[198:201], v[66:69]
	v_mfma_f32_16x16x32_bf16 v[62:65], v[150:153], v[198:201], v[62:65]
	v_mfma_f32_16x16x32_bf16 v[50:53], v[142:145], v[190:193], v[50:53]
	v_mfma_f32_16x16x32_bf16 v[46:49], v[150:153], v[190:193], v[46:49]
	v_mfma_f32_16x16x32_bf16 v[34:37], v[142:145], v[182:185], v[34:37]
	v_mfma_f32_16x16x32_bf16 v[30:33], v[150:153], v[182:185], v[30:33]
	v_mfma_f32_16x16x32_bf16 v[18:21], v[142:145], v[174:177], v[18:21]
	v_mfma_f32_16x16x32_bf16 v[14:17], v[150:153], v[174:177], v[14:17]
	v_mfma_f32_16x16x32_bf16 v[66:69], v[146:149], v[202:205], v[66:69]
	v_mfma_f32_16x16x32_bf16 v[62:65], v[154:157], v[202:205], v[62:65]
	v_mfma_f32_16x16x32_bf16 v[50:53], v[146:149], v[194:197], v[50:53]
	v_mfma_f32_16x16x32_bf16 v[46:49], v[154:157], v[194:197], v[46:49]
	v_mfma_f32_16x16x32_bf16 v[34:37], v[146:149], v[186:189], v[34:37]
	v_mfma_f32_16x16x32_bf16 v[30:33], v[154:157], v[186:189], v[30:33]
	v_mfma_f32_16x16x32_bf16 v[18:21], v[146:149], v[178:181], v[18:21]
	v_mfma_f32_16x16x32_bf16 v[14:17], v[154:157], v[178:181], v[14:17]
	s_barrier
	s_setprio 0
	v_add_u32_e32 v2, 0x18000, v248
	ds_read_b128 v[158:161], v2
	ds_read_b128 v[162:165], v2 offset:1024
	ds_read_b128 v[166:169], v2 offset:2048
	ds_read_b128 v[170:173], v2 offset:3072
	v_add_u32_e32 v2, 0x1c000, v248
	ds_read_b128 v[142:145], v2
	ds_read_b128 v[146:149], v2 offset:1024
	ds_read_b128 v[150:153], v2 offset:2048
	ds_read_b128 v[154:157], v2 offset:3072
	s_add_u32 s44, s44, 0x10000
	s_addc_u32 s45, s45, 0
	s_mov_b32 m0, s72
	v_add_u32_e32 v2, 0x22c00, v250
	ds_read_b128 v[182:185], v249 offset:32768
	ds_read_b128 v[186:189], v249 offset:33792
	ds_read_b128 v[190:193], v249 offset:34816
	ds_read_b128 v[194:197], v249 offset:35840
	ds_read_b128 v[198:201], v249 offset:36864
	ds_read_b128 v[202:205], v249 offset:37888
	ds_read_b128 v[206:209], v249 offset:38912
	ds_read_b128 v[240:243], v249 offset:39936
	ds_read_b128 v[174:177], v2
	ds_read_b128 v[178:181], v2 offset:1024
	global_load_lds_dwordx4 v214, s[44:45]
	s_mov_b32 m0, s73
	s_nop 0
	global_load_lds_dwordx4 v218, s[44:45]
	s_waitcnt vmcnt(9)
	s_waitcnt lgkmcnt(0)
	s_setprio 1
	s_barrier
	v_mfma_f32_16x16x32_bf16 v[138:141], v[158:161], v[182:185], v[138:141]
	v_mfma_f32_16x16x32_bf16 v[134:137], v[166:169], v[182:185], v[134:137]
	v_mfma_f32_16x16x32_bf16 v[122:125], v[158:161], v[190:193], v[122:125]
	v_mfma_f32_16x16x32_bf16 v[118:121], v[166:169], v[190:193], v[118:121]
	v_mfma_f32_16x16x32_bf16 v[106:109], v[158:161], v[198:201], v[106:109]
	v_mfma_f32_16x16x32_bf16 v[102:105], v[166:169], v[198:201], v[102:105]
	v_mfma_f32_16x16x32_bf16 v[90:93], v[158:161], v[206:209], v[90:93]
	v_mfma_f32_16x16x32_bf16 v[86:89], v[166:169], v[206:209], v[86:89]
	v_mfma_f32_16x16x32_bf16 v[138:141], v[162:165], v[186:189], v[138:141]
	v_mfma_f32_16x16x32_bf16 v[134:137], v[170:173], v[186:189], v[134:137]
	v_mfma_f32_16x16x32_bf16 v[122:125], v[162:165], v[194:197], v[122:125]
	v_mfma_f32_16x16x32_bf16 v[118:121], v[170:173], v[194:197], v[118:121]
	v_mfma_f32_16x16x32_bf16 v[106:109], v[162:165], v[202:205], v[106:109]
	v_mfma_f32_16x16x32_bf16 v[102:105], v[170:173], v[202:205], v[102:105]
	v_mfma_f32_16x16x32_bf16 v[90:93], v[162:165], v[240:243], v[90:93]
	v_mfma_f32_16x16x32_bf16 v[86:89], v[170:173], v[240:243], v[86:89]
	v_mfma_f32_16x16x32_bf16 v[130:133], v[142:145], v[182:185], v[130:133]
	v_mfma_f32_16x16x32_bf16 v[126:129], v[150:153], v[182:185], v[126:129]
	v_mfma_f32_16x16x32_bf16 v[114:117], v[142:145], v[190:193], v[114:117]
	v_mfma_f32_16x16x32_bf16 v[110:113], v[150:153], v[190:193], v[110:113]
	v_mfma_f32_16x16x32_bf16 v[98:101], v[142:145], v[198:201], v[98:101]
	v_mfma_f32_16x16x32_bf16 v[94:97], v[150:153], v[198:201], v[94:97]
	v_mfma_f32_16x16x32_bf16 v[82:85], v[142:145], v[206:209], v[82:85]
	v_mfma_f32_16x16x32_bf16 v[78:81], v[150:153], v[206:209], v[78:81]
	v_mfma_f32_16x16x32_bf16 v[130:133], v[146:149], v[186:189], v[130:133]
	v_mfma_f32_16x16x32_bf16 v[126:129], v[154:157], v[186:189], v[126:129]
	v_mfma_f32_16x16x32_bf16 v[114:117], v[146:149], v[194:197], v[114:117]
	v_mfma_f32_16x16x32_bf16 v[110:113], v[154:157], v[194:197], v[110:113]
	v_mfma_f32_16x16x32_bf16 v[98:101], v[146:149], v[202:205], v[98:101]
	v_mfma_f32_16x16x32_bf16 v[94:97], v[154:157], v[202:205], v[94:97]
	v_mfma_f32_16x16x32_bf16 v[82:85], v[146:149], v[240:243], v[82:85]
	v_mfma_f32_16x16x32_bf16 v[78:81], v[154:157], v[240:243], v[78:81]
	s_setprio 0
	s_and_b64 vcc, exec, s[6:7]
	s_cbranch_vccnz .LBB0_1666
	s_setprio 1
	s_and_b64 vcc, exec, s[0:1]
	s_mov_b64 s[0:1], -1
	s_cbranch_vccnz .LBB0_1663
	v_mfma_f32_16x16x32_bf16 v[10:13], v[142:145], v[174:177], v[10:13]
	s_mov_b64 s[0:1], 0
	v_mfma_f32_16x16x32_bf16 v[6:9], v[150:153], v[174:177], v[6:9]
	v_mfma_f32_16x16x32_bf16 v[10:13], v[146:149], v[178:181], v[10:13]
	v_mfma_f32_16x16x32_bf16 v[6:9], v[154:157], v[178:181], v[6:9]

; #define PG8_LAS __attribute__((address_space(3)))
;     template <class Sched> __device__ __forceinline__ void prehook(const Sched& S, const Unit& u0) const { rtab_hook(S, u0, pre, ssq, (PG8_LAS float*)rtab); }
;     __device__ __forceinline__ bool next(int i, Unit& u) const { if (i >= nr) return false; int j = nr - 1 - i + rot; if (j >= nr) j -= nr; const bool ok = StaticOrder::next(j, u); u.ui = i; return ok; }
;     __device__ __forceinline__ bool next(int i, Unit& u) const { if (c >= nM || i >= 2) return false; u.pm = c; u.pn = i; u.ui = i; return true; }
; #define PG8_STAGEX(b, gbase) do { if constexpr (XR) { if (lane < 16) __builtin_amdgcn_global_load_lds((const unsigned*)((const char*)(gbase) + voffX), (PG8_LAS unsigned*)(lds + XR_OFF + (b) * 2048 + wid * 256), 16, 0, 0); } } while (0)
; #define PG8_STAGE(bufoff, gbase, voff) do { _Pragma("unroll") for (int _i = 0; _i < 2; ++_i) \
;         __builtin_amdgcn_global_load_lds((const unsigned*)((const char*)(gbase) + (voff)[_i]), (PG8_LAS unsigned*)(lds + (bufoff) + ldsw + _i * 8192), 16, 0, 0); } while (0)
;     template <class Sched> __device__ __forceinline__ void prehook(const Sched& S, const Unit& u0) const { rtab_hook(S, u0, pre, ssq_in, (PG8_LAS float*)rtab); }
; template <class Sched> __device__ __forceinline__ void rtab_hook(const Sched& S, const Unit& u0, const RtPre& pre, const float* ssq, PG8_LAS float* rt) {
;     int t_ = threadIdx.x; asm volatile("" : "+v"(t_));
;     if (t_ < 256) { const float r0 = rtpre_rinv(pre, 1.0f / 1024.0f); Unit u_;
;         for (int i_ = 0; i_ < 8 && S.next(i_, u_); ++i_) { float r = r0; if (u_.pm != u0.pm) r = rinv16(ssq, u_.pm * 256 + t_, 1.0f / 1024.0f); rt[i_ * 256 + t_] = r; } }
; template <class Epi, class Sched, bool ALIGN_EPI = false, bool SP2 = false, bool DRAIN = true, bool XR = false>
; __device__ __forceinline__ void gemm_phase(PG8_LAS unsigned char* lds, const Gemm g, const Sched& S, const Epi& E) {
;     ...
;         PG8_STAGE(PG8_SB(0, 0), cB + kb0, voffB); PG8_STAGE(PG8_SB(0, 1), cB + kb0 + hstep, voffB); PG8_STAGE(PG8_SA(0, 0), cA + ka0, voffA); PG8_STAGEX(0, cX + kx0); PG8_STAGE(PG8_SA(0, 1), cA + ka0 + hstepA, voffA);
;         if constexpr (Epi::PREHOOK) E.prehook(S, cur);
.LBB0_1777:
	s_or_b64 exec, exec, s[34:35]
	s_ashr_i32 s34, s65, 31
	v_writelane_b32 v253, s34, 41
	s_add_u32 s34, s8, s18
	v_mov_b32_e32 v215, v3
	s_addc_u32 s35, s9, s19
	s_add_i32 s79, s72, 0x4000
	v_mov_b32_e32 v219, v3
	s_mov_b32 m0, s79
	s_add_i32 s80, s72, 0x6000
	global_load_lds_dwordx4 v214, s[34:35]
	v_lshl_add_u64 v[22:23], s[34:35], 0, v[218:219]
	s_mov_b32 m0, s80
	s_movk_i32 s34, 0x100
	global_load_lds_dwordx4 v[22:23], off
	v_mov_b32_e32 v22, v0
	s_nop 0
	v_cmp_gt_i32_e32 vcc, s34, v22
	s_and_saveexec_b64 s[34:35], vcc
	s_cbranch_execz .LBB0_1834
	v_readlane_b32 s37, v253, 41
	s_lshr_b32 s40, s37, 29
	s_add_i32 s42, s65, s40
	s_and_b32 s40, s42, -8
	s_sub_i32 s45, s65, s40
	s_cmp_gt_i32 s45, -1
	s_mov_b64 s[40:41], -1
	s_cbranch_scc0 .LBB0_1780
	s_lshl_b32 s43, s45, 5
	s_mov_b64 s[40:41], 0

; #define PG8_STAGEX(b, gbase) do { if constexpr (XR) { if (lane < 16) __builtin_amdgcn_global_load_lds((const unsigned*)((const char*)(gbase) + voffX), (PG8_LAS unsigned*)(lds + XR_OFF + (b) * 2048 + wid * 256), 16, 0, 0); } } while (0)
; #define PG8_LDX(b) do { if constexpr (XR) { _Pragma("unroll") for (int k = 0; k < 2; ++k) Ax_[k] = *(const PG8_LAS bf16x8*)(lds + XR_OFF + (b) * 2048 + aoffx + k * 1024); } } while (0)
; #define PG8_MMAX() do { if constexpr (XR) { if (hasx) { __builtin_amdgcn_s_setprio(1); if (wr == 0) PG8_MMAX_(B0); else PG8_MMAX_(B1); __builtin_amdgcn_s_setprio(0); } } } while (0)
; #define PG8_WAIT_LOOP() do { if constexpr (XR) PG8_WAIT_V(9); else PG8_WAIT_V(8); } while (0)
; #define PG8_STAGE(bufoff, gbase, voff) do { _Pragma("unroll") for (int _i = 0; _i < 2; ++_i) \
;         __builtin_amdgcn_global_load_lds((const unsigned*)((const char*)(gbase) + (voff)[_i]), (PG8_LAS unsigned*)(lds + (bufoff) + ldsw + _i * 8192), 16, 0, 0); } while (0)
; #define PG8_LDA(dst, b, h) do { _Pragma("unroll") for (int m = 0; m < 4; ++m) _Pragma("unroll") for (int k = 0; k < 2; ++k) dst[m][k] = *(const PG8_LAS bf16x8*)(lds + PG8_SA(b, h) + aoff + m * 2048 + k * 1024); } while (0)
; #define PG8_BAR __builtin_amdgcn_s_barrier()
; template <class Epi, class Sched, bool ALIGN_EPI = false, bool SP2 = false, bool DRAIN = true, bool XR = false>
; __device__ __forceinline__ void gemm_phase(PG8_LAS unsigned char* lds, const Gemm g, const Sched& S, const Epi& E) {
;     ...
;             const char* a1 = cA + PG8_KOA(t) + kstep;
;             const char* a2 = last ? nA + ka0 : cA + PG8_KOA(t + 2); const char* b2 = last ? nB + kb0 : cB + PG8_KOB(t + 2);
;             const char* x2 = XR ? (last ? nX + kx0 : cX + PG8_KOX(t + 2)) : nullptr; const char* x3 = XR ? x2 + kstep : nullptr;
;             const char* a3 = a2 + kstep; const char* b3 = b2 + kstep;
;             if (last && has_next) S.a_ready(nxt);
;             if constexpr (SP2) {
;             PG8_LDB(B0, 0, 0); PG8_LDB(B1, 0, 1); PG8_SCHED; PG8_LDA(At, 0, 0); PG8_LDX(0); PG8_STAGE(PG8_SA(1, 1), a1 + hstepA, voffA);
;             PG8_WAIT_LOOP(); PG8_WAIT_L(0); PG8_BAR; PG8_MMA(0, 0, At, B0); PG8_MMA(0, 1, At, B1); PG8_MMAX(); PG8_BAR; PG8_SCHED;
;             PG8_LDA(At, 0, 1); PG8_STAGE(PG8_SB(0, 0), b2, voffB); PG8_STAGE(PG8_SB(0, 1), b2 + hstep, voffB); PG8_STAGE(PG8_SA(0, 0), a2, voffA); PG8_STAGEX(0, x2);
.LBB0_1862:
	s_barrier
	s_add_i32 s56, s56, 2
	s_and_b32 s54, s56, s67
	s_lshr_b32 s84, s54, 2
	s_lshl_b32 s36, s54, 7
	s_lshl_b64 s[56:57], s[84:85], 9
	s_and_b32 s36, s36, 0x100
	s_add_u32 s55, s24, s56
	s_addc_u32 s56, s25, s57
	s_add_u32 s36, s55, s36
	s_mov_b32 s55, s85
	s_addc_u32 s56, s56, 0
	s_lshl_b64 s[54:55], s[54:55], 7
	s_add_u32 vcc_lo, s22, s54
	s_addc_u32 vcc_hi, s23, s55
	s_add_u32 s70, s28, s54
	s_addc_u32 s57, s29, s55
	s_cmp_eq_u32 s63, s45
	s_cselect_b32 s55, s59, s56
	s_cselect_b32 s54, s58, s36
	s_cselect_b32 s57, s44, s57
	s_cselect_b32 s56, s43, s70
	s_cselect_b32 vcc_hi, s42, vcc_hi
	s_cselect_b32 vcc_lo, s78, vcc_lo
	s_mov_b32 m0, s73
	v_lshl_add_u64 v[224:225], vcc, 0, v[216:217]
	v_lshl_add_u64 v[226:227], vcc, 0, v[220:221]
	s_add_u32 vcc_lo, vcc_lo, s18
	ds_read_b128 v[198:201], v238 offset:16384
	ds_read_b128 v[202:205], v238 offset:17408
	ds_read_b128 v[190:193], v238 offset:18432
	ds_read_b128 v[194:197], v238 offset:19456
	ds_read_b128 v[182:185], v238 offset:20480
	ds_read_b128 v[186:189], v238 offset:21504
	ds_read_b128 v[174:177], v238 offset:22528
	ds_read_b128 v[178:181], v238 offset:23552
	global_load_lds_dwordx4 v[224:225], off
	s_mov_b32 m0, s74
	s_addc_u32 vcc_hi, vcc_hi, s19
	global_load_lds_dwordx4 v[226:227], off
	v_lshl_add_u64 v[228:229], vcc, 0, v[216:217]
	s_mov_b32 m0, s75
	v_lshl_add_u64 v[230:231], vcc, 0, v[220:221]
	global_load_lds_dwordx4 v216, vcc
	s_mov_b32 m0, s76
	v_lshl_add_u64 v[232:233], s[54:55], 0, v[214:215]
	global_load_lds_dwordx4 v220, vcc
	s_mov_b32 m0, s72
	v_lshl_add_u64 v[234:235], s[54:55], 0, v[218:219]
	global_load_lds_dwordx4 v214, s[54:55]
	s_mov_b32 m0, s77
	v_lshl_add_u64 v[4:5], s[56:57], 0, v[222:223]
	global_load_lds_dwordx4 v218, s[54:55]
	s_and_saveexec_b64 s[56:57], s[2:3]
	s_cbranch_execz .LBB0_1864
	s_add_i32 s36, s68, 0
	s_add_i32 m0, s36, 0x22400
	s_nop 0
	global_load_lds_dwordx4 v[4:5], off
; #define PG8_LDX(b) do { if constexpr (XR) { _Pragma("unroll") for (int k = 0; k < 2; ++k) Ax_[k] = *(const PG8_LAS bf16x8*)(lds + XR_OFF + (b) * 2048 + aoffx + k * 1024); } } while (0)
; #define PG8_MMAX() do { if constexpr (XR) { if (hasx) { __builtin_amdgcn_s_setprio(1); if (wr == 0) PG8_MMAX_(B0); else PG8_MMAX_(B1); __builtin_amdgcn_s_setprio(0); } } } while (0)
; #define PG8_WAIT_LOOP() do { if constexpr (XR) PG8_WAIT_V(9); else PG8_WAIT_V(8); } while (0)
; #define PG8_STAGE(bufoff, gbase, voff) do { _Pragma("unroll") for (int _i = 0; _i < 2; ++_i) \
;         __builtin_amdgcn_global_load_lds((const unsigned*)((const char*)(gbase) + (voff)[_i]), (PG8_LAS unsigned*)(lds + (bufoff) + ldsw + _i * 8192), 16, 0, 0); } while (0)
; #define PG8_LDA(dst, b, h) do { _Pragma("unroll") for (int m = 0; m < 4; ++m) _Pragma("unroll") for (int k = 0; k < 2; ++k) dst[m][k] = *(const PG8_LAS bf16x8*)(lds + PG8_SA(b, h) + aoff + m * 2048 + k * 1024); } while (0)
; #define PG8_LDB(dst, b, h) do { _Pragma("unroll") for (int n = 0; n < 2; ++n) _Pragma("unroll") for (int k = 0; k < 2; ++k) dst[n][k] = *(const PG8_LAS bf16x8*)(lds + PG8_SB(b, h) + boff + n * 2048 + k * 1024); } while (0)
; #define PG8_MMA(ai, bj, At, Bt) do { __builtin_amdgcn_s_setprio(1); _Pragma("unroll") for (int m = 0; m < 4; ++m) _Pragma("unroll") for (int n = 0; n < 2; ++n) _Pragma("unroll") for (int k = 0; k < 2; ++k) \
;         acc[ai][bj][m][n] = __builtin_amdgcn_mfma_f32_16x16x32_bf16(Bt[n][k], At[m][k], acc[ai][bj][m][n], 0, 0, 0); __builtin_amdgcn_s_setprio(0); } while (0)
; #define PG8_WAIT_L(n) asm volatile("s_waitcnt lgkmcnt(" #n ")" ::: "memory")
; #define PG8_BAR __builtin_amdgcn_s_barrier()
; #define PG8_SCHED __builtin_amdgcn_sched_barrier(0)
; template <class Epi, class Sched, bool ALIGN_EPI = false, bool SP2 = false, bool DRAIN = true, bool XR = false>
; __device__ __forceinline__ void gemm_phase(PG8_LAS unsigned char* lds, const Gemm g, const Sched& S, const Epi& E) {
;     ...
;             PG8_WAIT_LOOP(); PG8_WAIT_L(0); PG8_BAR; PG8_MMA(1, 0, At, B0); PG8_MMA(1, 1, At, B1); PG8_BAR; PG8_SCHED;
;             PG8_LDB(B0, 1, 0); PG8_LDB(B1, 1, 1); PG8_SCHED; PG8_LDA(At, 1, 0); PG8_LDX(1); PG8_STAGE(PG8_SA(0, 1), a2 + hstepA, voffA);
;             PG8_WAIT_LOOP(); PG8_WAIT_L(0); PG8_BAR; PG8_MMA(0, 0, At, B0); PG8_MMA(0, 1, At, B1); PG8_MMAX(); PG8_BAR; PG8_SCHED;
.LBB0_1864:
	s_or_b64 exec, exec, s[56:57]
	s_waitcnt vmcnt(9)
	s_waitcnt lgkmcnt(0)
	s_setprio 1
	s_barrier
	v_mfma_f32_16x16x32_bf16 v[74:77], v[158:161], v[198:201], v[74:77]
	v_mfma_f32_16x16x32_bf16 v[70:73], v[166:169], v[198:201], v[70:73]
	v_mfma_f32_16x16x32_bf16 v[66:69], v[158:161], v[190:193], v[66:69]
	v_mfma_f32_16x16x32_bf16 v[62:65], v[166:169], v[190:193], v[62:65]
	v_mfma_f32_16x16x32_bf16 v[58:61], v[158:161], v[182:185], v[58:61]
	v_mfma_f32_16x16x32_bf16 v[54:57], v[166:169], v[182:185], v[54:57]
	v_mfma_f32_16x16x32_bf16 v[50:53], v[158:161], v[174:177], v[50:53]
	v_mfma_f32_16x16x32_bf16 v[46:49], v[166:169], v[174:177], v[46:49]
	v_mfma_f32_16x16x32_bf16 v[74:77], v[162:165], v[202:205], v[74:77]
	v_mfma_f32_16x16x32_bf16 v[70:73], v[170:173], v[202:205], v[70:73]
	v_mfma_f32_16x16x32_bf16 v[66:69], v[162:165], v[194:197], v[66:69]
	v_mfma_f32_16x16x32_bf16 v[62:65], v[170:173], v[194:197], v[62:65]
	v_mfma_f32_16x16x32_bf16 v[58:61], v[162:165], v[186:189], v[58:61]
	v_mfma_f32_16x16x32_bf16 v[54:57], v[170:173], v[186:189], v[54:57]
	v_mfma_f32_16x16x32_bf16 v[50:53], v[162:165], v[178:181], v[50:53]
	v_mfma_f32_16x16x32_bf16 v[46:49], v[170:173], v[178:181], v[46:49]
	v_mfma_f32_16x16x32_bf16 v[42:45], v[142:145], v[198:201], v[42:45]
	v_mfma_f32_16x16x32_bf16 v[38:41], v[150:153], v[198:201], v[38:41]
	v_mfma_f32_16x16x32_bf16 v[34:37], v[142:145], v[190:193], v[34:37]
	v_mfma_f32_16x16x32_bf16 v[30:33], v[150:153], v[190:193], v[30:33]
	v_mfma_f32_16x16x32_bf16 v[26:29], v[142:145], v[182:185], v[26:29]
	v_mfma_f32_16x16x32_bf16 v[22:25], v[150:153], v[182:185], v[22:25]
	v_mfma_f32_16x16x32_bf16 v[18:21], v[142:145], v[174:177], v[18:21]
	v_mfma_f32_16x16x32_bf16 v[14:17], v[150:153], v[174:177], v[14:17]
	v_mfma_f32_16x16x32_bf16 v[42:45], v[146:149], v[202:205], v[42:45]
	v_mfma_f32_16x16x32_bf16 v[38:41], v[154:157], v[202:205], v[38:41]
	v_mfma_f32_16x16x32_bf16 v[34:37], v[146:149], v[194:197], v[34:37]
	v_mfma_f32_16x16x32_bf16 v[30:33], v[154:157], v[194:197], v[30:33]
	v_mfma_f32_16x16x32_bf16 v[26:29], v[146:149], v[186:189], v[26:29]
	v_mfma_f32_16x16x32_bf16 v[22:25], v[154:157], v[186:189], v[22:25]
	v_mfma_f32_16x16x32_bf16 v[18:21], v[146:149], v[178:181], v[18:21]
	v_mfma_f32_16x16x32_bf16 v[14:17], v[154:157], v[178:181], v[14:17]
	s_barrier
	s_setprio 0
	v_add_u32_e32 v2, 0x18000, v237
	ds_read_b128 v[158:161], v2
	ds_read_b128 v[162:165], v2 offset:1024
	ds_read_b128 v[166:169], v2 offset:2048
	ds_read_b128 v[170:173], v2 offset:3072
	v_add_u32_e32 v2, 0x1c000, v237
	ds_read_b128 v[142:145], v2
	ds_read_b128 v[146:149], v2 offset:1024
	ds_read_b128 v[150:153], v2 offset:2048
	ds_read_b128 v[154:157], v2 offset:3072
	s_add_u32 s54, s54, s18
	s_addc_u32 s55, s55, s19
	s_mov_b32 m0, s79
	v_add_u32_e32 v2, 0x22c00, v239
	ds_read_b128 v[182:185], v238 offset:32768
	ds_read_b128 v[186:189], v238 offset:33792
	ds_read_b128 v[190:193], v238 offset:34816
	ds_read_b128 v[194:197], v238 offset:35840
	ds_read_b128 v[198:201], v238 offset:36864
	ds_read_b128 v[202:205], v238 offset:37888
	ds_read_b128 v[206:209], v238 offset:38912
	ds_read_b128 v[240:243], v238 offset:39936
	ds_read_b128 v[174:177], v2
	ds_read_b128 v[178:181], v2 offset:1024
	global_load_lds_dwordx4 v214, s[54:55]
	s_mov_b32 m0, s80
	s_nop 0
	global_load_lds_dwordx4 v218, s[54:55]
	s_waitcnt vmcnt(9)
	s_waitcnt lgkmcnt(0)
	s_setprio 1
	s_barrier
	v_mfma_f32_16x16x32_bf16 v[138:141], v[158:161], v[182:185], v[138:141]
	v_mfma_f32_16x16x32_bf16 v[134:137], v[166:169], v[182:185], v[134:137]
	v_mfma_f32_16x16x32_bf16 v[130:133], v[158:161], v[190:193], v[130:133]
	v_mfma_f32_16x16x32_bf16 v[126:129], v[166:169], v[190:193], v[126:129]
	v_mfma_f32_16x16x32_bf16 v[122:125], v[158:161], v[198:201], v[122:125]
	v_mfma_f32_16x16x32_bf16 v[118:121], v[166:169], v[198:201], v[118:121]
	v_mfma_f32_16x16x32_bf16 v[114:117], v[158:161], v[206:209], v[114:117]
	v_mfma_f32_16x16x32_bf16 v[110:113], v[166:169], v[206:209], v[110:113]
	v_mfma_f32_16x16x32_bf16 v[138:141], v[162:165], v[186:189], v[138:141]
	v_mfma_f32_16x16x32_bf16 v[134:137], v[170:173], v[186:189], v[134:137]
	v_mfma_f32_16x16x32_bf16 v[130:133], v[162:165], v[194:197], v[130:133]
	v_mfma_f32_16x16x32_bf16 v[126:129], v[170:173], v[194:197], v[126:129]
	v_mfma_f32_16x16x32_bf16 v[122:125], v[162:165], v[202:205], v[122:125]
	v_mfma_f32_16x16x32_bf16 v[118:121], v[170:173], v[202:205], v[118:121]
	v_mfma_f32_16x16x32_bf16 v[114:117], v[162:165], v[240:243], v[114:117]
	v_mfma_f32_16x16x32_bf16 v[110:113], v[170:173], v[240:243], v[110:113]
	v_mfma_f32_16x16x32_bf16 v[106:109], v[142:145], v[182:185], v[106:109]
	v_mfma_f32_16x16x32_bf16 v[102:105], v[150:153], v[182:185], v[102:105]
	v_mfma_f32_16x16x32_bf16 v[98:101], v[142:145], v[190:193], v[98:101]
	v_mfma_f32_16x16x32_bf16 v[94:97], v[150:153], v[190:193], v[94:97]
	v_mfma_f32_16x16x32_bf16 v[90:93], v[142:145], v[198:201], v[90:93]
	v_mfma_f32_16x16x32_bf16 v[86:89], v[150:153], v[198:201], v[86:89]
	v_mfma_f32_16x16x32_bf16 v[82:85], v[142:145], v[206:209], v[82:85]
	v_mfma_f32_16x16x32_bf16 v[78:81], v[150:153], v[206:209], v[78:81]
	v_mfma_f32_16x16x32_bf16 v[106:109], v[146:149], v[186:189], v[106:109]
	v_mfma_f32_16x16x32_bf16 v[102:105], v[154:157], v[186:189], v[102:105]
	v_mfma_f32_16x16x32_bf16 v[98:101], v[146:149], v[194:197], v[98:101]
	v_mfma_f32_16x16x32_bf16 v[94:97], v[154:157], v[194:197], v[94:97]
	v_mfma_f32_16x16x32_bf16 v[90:93], v[146:149], v[202:205], v[90:93]
	v_mfma_f32_16x16x32_bf16 v[86:89], v[154:157], v[202:205], v[86:89]
	v_mfma_f32_16x16x32_bf16 v[82:85], v[146:149], v[240:243], v[82:85]
	v_mfma_f32_16x16x32_bf16 v[78:81], v[154:157], v[240:243], v[78:81]
	s_setprio 0
	s_and_b64 vcc, exec, s[8:9]
	s_cbranch_vccnz .LBB0_1870
	s_setprio 1
	s_and_b64 vcc, exec, s[0:1]
	s_mov_b64 s[0:1], -1
	s_cbranch_vccnz .LBB0_1867
	v_mfma_f32_16x16x32_bf16 v[10:13], v[142:145], v[174:177], v[10:13]
	s_mov_b64 s[0:1], 0
	v_mfma_f32_16x16x32_bf16 v[6:9], v[150:153], v[174:177], v[6:9]
	v_mfma_f32_16x16x32_bf16 v[10:13], v[146:149], v[178:181], v[10:13]
	v_mfma_f32_16x16x32_bf16 v[6:9], v[154:157], v[178:181], v[6:9]

; #define PG8_STAGEX(b, gbase) do { if constexpr (XR) { if (lane < 16) __builtin_amdgcn_global_load_lds((const unsigned*)((const char*)(gbase) + voffX), (PG8_LAS unsigned*)(lds + XR_OFF + (b) * 2048 + wid * 256), 16, 0, 0); } } while (0)
; #define PG8_LDX(b) do { if constexpr (XR) { _Pragma("unroll") for (int k = 0; k < 2; ++k) Ax_[k] = *(const PG8_LAS bf16x8*)(lds + XR_OFF + (b) * 2048 + aoffx + k * 1024); } } while (0)
; #define PG8_MMAX() do { if constexpr (XR) { if (hasx) { __builtin_amdgcn_s_setprio(1); if (wr == 0) PG8_MMAX_(B0); else PG8_MMAX_(B1); __builtin_amdgcn_s_setprio(0); } } } while (0)
; #define PG8_WAIT_LOOP() do { if constexpr (XR) PG8_WAIT_V(9); else PG8_WAIT_V(8); } while (0)
; #define PG8_STAGE(bufoff, gbase, voff) do { _Pragma("unroll") for (int _i = 0; _i < 2; ++_i) \
;         __builtin_amdgcn_global_load_lds((const unsigned*)((const char*)(gbase) + (voff)[_i]), (PG8_LAS unsigned*)(lds + (bufoff) + ldsw + _i * 8192), 16, 0, 0); } while (0)
; #define PG8_LDA(dst, b, h) do { _Pragma("unroll") for (int m = 0; m < 4; ++m) _Pragma("unroll") for (int k = 0; k < 2; ++k) dst[m][k] = *(const PG8_LAS bf16x8*)(lds + PG8_SA(b, h) + aoff + m * 2048 + k * 1024); } while (0)
; #define PG8_BAR __builtin_amdgcn_s_barrier()
; template <class Epi, class Sched, bool ALIGN_EPI = false, bool SP2 = false, bool DRAIN = true, bool XR = false>
; __device__ __forceinline__ void gemm_phase(PG8_LAS unsigned char* lds, const Gemm g, const Sched& S, const Epi& E) {
;     ...
;             const char* a1 = cA + PG8_KOA(t) + kstep;
;             const char* a2 = last ? nA + ka0 : cA + PG8_KOA(t + 2); const char* b2 = last ? nB + kb0 : cB + PG8_KOB(t + 2);
;             const char* x2 = XR ? (last ? nX + kx0 : cX + PG8_KOX(t + 2)) : nullptr; const char* x3 = XR ? x2 + kstep : nullptr;
;             const char* a3 = a2 + kstep; const char* b3 = b2 + kstep;
;             if (last && has_next) S.a_ready(nxt);
;             if constexpr (SP2) {
;             PG8_LDB(B0, 0, 0); PG8_LDB(B1, 0, 1); PG8_SCHED; PG8_LDA(At, 0, 0); PG8_LDX(0); PG8_STAGE(PG8_SA(1, 1), a1 + hstepA, voffA);
;             PG8_WAIT_LOOP(); PG8_WAIT_L(0); PG8_BAR; PG8_MMA(0, 0, At, B0); PG8_MMA(0, 1, At, B1); PG8_MMAX(); PG8_BAR; PG8_SCHED;
;             PG8_LDA(At, 0, 1); PG8_STAGE(PG8_SB(0, 0), b2, voffB); PG8_STAGE(PG8_SB(0, 1), b2 + hstep, voffB); PG8_STAGE(PG8_SA(0, 0), a2, voffA); PG8_STAGEX(0, x2);
.LBB0_2023:
	s_add_i32 s40, s88, s25
	s_and_b32 s41, s40, s93
	s_lshr_b32 s84, s41, 2
	s_lshl_b32 s36, s41, 7
	s_lshl_b64 s[0:1], s[84:85], 9
	s_and_b32 s36, s36, 0x100
	s_add_u32 s0, s58, s0
	s_addc_u32 s1, s59, s1
	s_add_u32 s42, s0, s36
	s_addc_u32 s43, s1, 0
	s_add_i32 s40, s40, 2
	s_and_b32 s0, s40, s93
	s_lshr_b32 s84, s0, 2
	s_lshl_b32 s1, s0, 7
	s_lshl_b64 s[40:41], s[84:85], 9
	s_and_b32 s1, s1, 0x100
	s_add_u32 s36, s58, s40
	s_addc_u32 s40, s59, s41
	s_add_u32 s36, s36, s1
	s_mov_b32 s1, s85
	s_addc_u32 s40, s40, 0
	s_lshl_b64 s[0:1], s[0:1], 7
	s_add_u32 s44, s56, s0
	s_addc_u32 s41, s57, s1
	s_add_i32 s45, 0, 0x10000
	s_cmp_eq_u32 s92, s25
	s_cselect_b32 s1, s22, s40
	s_cselect_b32 s0, s9, s36
	v_add_u32_e32 v2, s45, v182
	s_cselect_b32 s41, s24, s41
	s_cselect_b32 s40, s23, s44
	s_add_i32 s36, 0, 0x14000
	ds_read_b128 v[134:137], v2
	ds_read_b128 v[138:141], v2 offset:1024
	ds_read_b128 v[142:145], v2 offset:2048
	ds_read_b128 v[146:149], v2 offset:3072
	v_add_u32_e32 v2, s36, v182
	ds_read_b128 v[150:153], v2
	ds_read_b128 v[154:157], v2 offset:1024
	ds_read_b128 v[158:161], v2 offset:2048
	ds_read_b128 v[162:165], v2 offset:3072
	s_add_u32 s42, s42, s68
	s_addc_u32 s43, s43, s69
	v_lshl_add_u64 v[4:5], s[42:43], 0, v[172:173]
	v_lshl_add_u64 v[4:5], v[4:5], 0, s[86:87]
	s_add_i32 m0, s49, 0xc000
	ds_read_b128 v[174:177], v199
	ds_read_b128 v[200:203], v199 offset:1024
	ds_read_b128 v[204:207], v199 offset:2048
	ds_read_b128 v[214:217], v199 offset:3072
	ds_read_b128 v[218:221], v199 offset:4096
	ds_read_b128 v[222:225], v199 offset:5120
	ds_read_b128 v[226:229], v199 offset:6144
	ds_read_b128 v[230:233], v199 offset:7168
	global_load_lds_dwordx4 v[4:5], off
	v_lshl_add_u64 v[4:5], s[42:43], 0, v[168:169]
	v_lshl_add_u64 v[4:5], v[4:5], 0, s[86:87]
	s_add_i32 m0, s49, 0xe000
	s_nop 0
	global_load_lds_dwordx4 v[4:5], off
	s_waitcnt vmcnt(8)
	s_waitcnt lgkmcnt(0)
	s_setprio 1
	s_barrier
	v_mfma_f32_16x16x32_bf16 v[130:133], v[134:137], v[174:177], v[130:133]
	v_mfma_f32_16x16x32_bf16 v[98:101], v[142:145], v[174:177], v[98:101]
	v_mfma_f32_16x16x32_bf16 v[126:129], v[134:137], v[204:207], v[126:129]
	v_mfma_f32_16x16x32_bf16 v[90:93], v[142:145], v[204:207], v[90:93]
	v_mfma_f32_16x16x32_bf16 v[122:125], v[134:137], v[218:221], v[122:125]
	v_mfma_f32_16x16x32_bf16 v[82:85], v[142:145], v[218:221], v[82:85]
	v_mfma_f32_16x16x32_bf16 v[118:121], v[134:137], v[226:229], v[118:121]
	v_mfma_f32_16x16x32_bf16 v[74:77], v[142:145], v[226:229], v[74:77]
	v_mfma_f32_16x16x32_bf16 v[130:133], v[138:141], v[200:203], v[130:133]
	v_mfma_f32_16x16x32_bf16 v[98:101], v[146:149], v[200:203], v[98:101]
	v_mfma_f32_16x16x32_bf16 v[126:129], v[138:141], v[214:217], v[126:129]
	v_mfma_f32_16x16x32_bf16 v[90:93], v[146:149], v[214:217], v[90:93]
	v_mfma_f32_16x16x32_bf16 v[122:125], v[138:141], v[222:225], v[122:125]
	v_mfma_f32_16x16x32_bf16 v[82:85], v[146:149], v[222:225], v[82:85]
	v_mfma_f32_16x16x32_bf16 v[118:121], v[138:141], v[230:233], v[118:121]
	v_mfma_f32_16x16x32_bf16 v[74:77], v[146:149], v[230:233], v[74:77]
	v_mfma_f32_16x16x32_bf16 v[114:117], v[150:153], v[174:177], v[114:117]
	v_mfma_f32_16x16x32_bf16 v[66:69], v[158:161], v[174:177], v[66:69]
	v_mfma_f32_16x16x32_bf16 v[110:113], v[150:153], v[204:207], v[110:113]
	v_mfma_f32_16x16x32_bf16 v[58:61], v[158:161], v[204:207], v[58:61]
	v_mfma_f32_16x16x32_bf16 v[106:109], v[150:153], v[218:221], v[106:109]
	v_mfma_f32_16x16x32_bf16 v[50:53], v[158:161], v[218:221], v[50:53]
	v_mfma_f32_16x16x32_bf16 v[102:105], v[150:153], v[226:229], v[102:105]
	v_mfma_f32_16x16x32_bf16 v[42:45], v[158:161], v[226:229], v[42:45]
	v_mfma_f32_16x16x32_bf16 v[114:117], v[154:157], v[200:203], v[114:117]
	v_mfma_f32_16x16x32_bf16 v[66:69], v[162:165], v[200:203], v[66:69]
	v_mfma_f32_16x16x32_bf16 v[110:113], v[154:157], v[214:217], v[110:113]
	v_mfma_f32_16x16x32_bf16 v[58:61], v[162:165], v[214:217], v[58:61]
	v_mfma_f32_16x16x32_bf16 v[106:109], v[154:157], v[222:225], v[106:109]
	v_mfma_f32_16x16x32_bf16 v[50:53], v[162:165], v[222:225], v[50:53]
	v_mfma_f32_16x16x32_bf16 v[102:105], v[154:157], v[230:233], v[102:105]
	v_mfma_f32_16x16x32_bf16 v[42:45], v[162:165], v[230:233], v[42:45]
	s_barrier
	s_setprio 0
	s_add_i32 s42, s45, s48
	v_lshl_add_u64 v[178:179], s[40:41], 0, v[170:171]
	s_mov_b32 m0, s42
	ds_read_b128 v[174:177], v199 offset:16384
	ds_read_b128 v[200:203], v199 offset:17408
	ds_read_b128 v[204:207], v199 offset:18432
	ds_read_b128 v[214:217], v199 offset:19456
	ds_read_b128 v[218:221], v199 offset:20480
	ds_read_b128 v[222:225], v199 offset:21504
	ds_read_b128 v[226:229], v199 offset:22528
	ds_read_b128 v[230:233], v199 offset:23552
	global_load_lds_dwordx4 v170, s[40:41]
	s_add_i32 m0, s42, 0x2000
	v_lshl_add_u64 v[208:209], s[40:41], 0, v[166:167]
	s_add_u32 s40, s40, s68
	s_addc_u32 s41, s41, s69
	s_add_i32 s36, s36, s48
	global_load_lds_dwordx4 v[208:209], off
	v_lshl_add_u64 v[212:213], s[40:41], 0, v[170:171]
	s_mov_b32 m0, s36
	v_lshl_add_u64 v[234:235], s[40:41], 0, v[166:167]
	global_load_lds_dwordx4 v170, s[40:41]
	s_add_i32 m0, s36, 0x2000
	v_lshl_add_u64 v[236:237], s[0:1], 0, v[172:173]
	global_load_lds_dwordx4 v166, s[40:41]
	s_mov_b32 m0, s49
	v_lshl_add_u64 v[238:239], s[0:1], 0, v[168:169]
	global_load_lds_dwordx4 v172, s[0:1]
	s_mov_b32 m0, s83
	s_nop 0
	global_load_lds_dwordx4 v168, s[0:1]
	s_waitcnt vmcnt(8)
	s_waitcnt lgkmcnt(0)
	s_setprio 1
	s_barrier
; #define PG8_LDX(b) do { if constexpr (XR) { _Pragma("unroll") for (int k = 0; k < 2; ++k) Ax_[k] = *(const PG8_LAS bf16x8*)(lds + XR_OFF + (b) * 2048 + aoffx + k * 1024); } } while (0)
; #define PG8_MMAX() do { if constexpr (XR) { if (hasx) { __builtin_amdgcn_s_setprio(1); if (wr == 0) PG8_MMAX_(B0); else PG8_MMAX_(B1); __builtin_amdgcn_s_setprio(0); } } } while (0)
; #define PG8_WAIT_LOOP() do { if constexpr (XR) PG8_WAIT_V(9); else PG8_WAIT_V(8); } while (0)
; #define PG8_STAGE(bufoff, gbase, voff) do { _Pragma("unroll") for (int _i = 0; _i < 2; ++_i) \
;         __builtin_amdgcn_global_load_lds((const unsigned*)((const char*)(gbase) + (voff)[_i]), (PG8_LAS unsigned*)(lds + (bufoff) + ldsw + _i * 8192), 16, 0, 0); } while (0)
; #define PG8_LDA(dst, b, h) do { _Pragma("unroll") for (int m = 0; m < 4; ++m) _Pragma("unroll") for (int k = 0; k < 2; ++k) dst[m][k] = *(const PG8_LAS bf16x8*)(lds + PG8_SA(b, h) + aoff + m * 2048 + k * 1024); } while (0)
; #define PG8_LDB(dst, b, h) do { _Pragma("unroll") for (int n = 0; n < 2; ++n) _Pragma("unroll") for (int k = 0; k < 2; ++k) dst[n][k] = *(const PG8_LAS bf16x8*)(lds + PG8_SB(b, h) + boff + n * 2048 + k * 1024); } while (0)
; #define PG8_MMA(ai, bj, At, Bt) do { __builtin_amdgcn_s_setprio(1); _Pragma("unroll") for (int m = 0; m < 4; ++m) _Pragma("unroll") for (int n = 0; n < 2; ++n) _Pragma("unroll") for (int k = 0; k < 2; ++k) \
;         acc[ai][bj][m][n] = __builtin_amdgcn_mfma_f32_16x16x32_bf16(Bt[n][k], At[m][k], acc[ai][bj][m][n], 0, 0, 0); __builtin_amdgcn_s_setprio(0); } while (0)
; #define PG8_WAIT_L(n) asm volatile("s_waitcnt lgkmcnt(" #n ")" ::: "memory")
; #define PG8_BAR __builtin_amdgcn_s_barrier()
; #define PG8_SCHED __builtin_amdgcn_sched_barrier(0)
; template <class Epi, class Sched, bool ALIGN_EPI = false, bool SP2 = false, bool DRAIN = true, bool XR = false>
; __device__ __forceinline__ void gemm_phase(PG8_LAS unsigned char* lds, const Gemm g, const Sched& S, const Epi& E) {
;     ...
;             PG8_WAIT_LOOP(); PG8_WAIT_L(0); PG8_BAR; PG8_MMA(1, 0, At, B0); PG8_MMA(1, 1, At, B1); PG8_BAR; PG8_SCHED;
;             PG8_LDB(B0, 1, 0); PG8_LDB(B1, 1, 1); PG8_SCHED; PG8_LDA(At, 1, 0); PG8_LDX(1); PG8_STAGE(PG8_SA(0, 1), a2 + hstepA, voffA);
;             PG8_WAIT_LOOP(); PG8_WAIT_L(0); PG8_BAR; PG8_MMA(0, 0, At, B0); PG8_MMA(0, 1, At, B1); PG8_MMAX(); PG8_BAR; PG8_SCHED;
	v_mfma_f32_16x16x32_bf16 v[94:97], v[134:137], v[174:177], v[94:97]
	v_mfma_f32_16x16x32_bf16 v[34:37], v[142:145], v[174:177], v[34:37]
	v_mfma_f32_16x16x32_bf16 v[86:89], v[134:137], v[204:207], v[86:89]
	v_mfma_f32_16x16x32_bf16 v[30:33], v[142:145], v[204:207], v[30:33]
	v_mfma_f32_16x16x32_bf16 v[78:81], v[134:137], v[218:221], v[78:81]
	v_mfma_f32_16x16x32_bf16 v[26:29], v[142:145], v[218:221], v[26:29]
	v_mfma_f32_16x16x32_bf16 v[70:73], v[134:137], v[226:229], v[70:73]
	v_mfma_f32_16x16x32_bf16 v[22:25], v[142:145], v[226:229], v[22:25]
	v_mfma_f32_16x16x32_bf16 v[94:97], v[138:141], v[200:203], v[94:97]
	v_mfma_f32_16x16x32_bf16 v[34:37], v[146:149], v[200:203], v[34:37]
	v_mfma_f32_16x16x32_bf16 v[86:89], v[138:141], v[214:217], v[86:89]
	v_mfma_f32_16x16x32_bf16 v[30:33], v[146:149], v[214:217], v[30:33]
	v_mfma_f32_16x16x32_bf16 v[78:81], v[138:141], v[222:225], v[78:81]
	v_mfma_f32_16x16x32_bf16 v[26:29], v[146:149], v[222:225], v[26:29]
	v_mfma_f32_16x16x32_bf16 v[70:73], v[138:141], v[230:233], v[70:73]
	v_mfma_f32_16x16x32_bf16 v[22:25], v[146:149], v[230:233], v[22:25]
	v_mfma_f32_16x16x32_bf16 v[62:65], v[150:153], v[174:177], v[62:65]
	v_mfma_f32_16x16x32_bf16 v[18:21], v[158:161], v[174:177], v[18:21]
	v_mfma_f32_16x16x32_bf16 v[54:57], v[150:153], v[204:207], v[54:57]
	v_mfma_f32_16x16x32_bf16 v[14:17], v[158:161], v[204:207], v[14:17]
	v_mfma_f32_16x16x32_bf16 v[46:49], v[150:153], v[218:221], v[46:49]
	v_mfma_f32_16x16x32_bf16 v[10:13], v[158:161], v[218:221], v[10:13]
	v_mfma_f32_16x16x32_bf16 v[38:41], v[150:153], v[226:229], v[38:41]
	v_mfma_f32_16x16x32_bf16 v[4:7], v[158:161], v[226:229], v[6:9]
	v_mfma_f32_16x16x32_bf16 v[62:65], v[154:157], v[200:203], v[62:65]
	v_mfma_f32_16x16x32_bf16 v[18:21], v[162:165], v[200:203], v[18:21]
	v_mfma_f32_16x16x32_bf16 v[54:57], v[154:157], v[214:217], v[54:57]
	v_mfma_f32_16x16x32_bf16 v[14:17], v[162:165], v[214:217], v[14:17]
	v_mfma_f32_16x16x32_bf16 v[46:49], v[154:157], v[222:225], v[46:49]
	v_mfma_f32_16x16x32_bf16 v[10:13], v[162:165], v[222:225], v[10:13]
	v_mfma_f32_16x16x32_bf16 v[38:41], v[154:157], v[230:233], v[38:41]
	v_mfma_f32_16x16x32_bf16 v[4:7], v[162:165], v[230:233], v[4:7]
	s_barrier
	s_setprio 0
	s_add_i32 s36, 0, 0x18000
	v_add_u32_e32 v2, s36, v182
	s_add_i32 s40, 0, 0x1c000
	ds_read_b128 v[134:137], v2
	ds_read_b128 v[138:141], v2 offset:1024
	ds_read_b128 v[142:145], v2 offset:2048
	ds_read_b128 v[146:149], v2 offset:3072
	v_add_u32_e32 v2, s40, v182
	ds_read_b128 v[150:153], v2
	ds_read_b128 v[154:157], v2 offset:1024
	ds_read_b128 v[158:161], v2 offset:2048
	ds_read_b128 v[162:165], v2 offset:3072
	s_add_u32 s0, s0, s68
	s_addc_u32 s1, s1, s69
	s_mov_b32 m0, s4
	ds_read_b128 v[174:177], v199 offset:32768
	ds_read_b128 v[200:203], v199 offset:33792
	ds_read_b128 v[204:207], v199 offset:34816
	ds_read_b128 v[214:217], v199 offset:35840
	ds_read_b128 v[218:221], v199 offset:36864
	ds_read_b128 v[222:225], v199 offset:37888
	ds_read_b128 v[226:229], v199 offset:38912
	ds_read_b128 v[230:233], v199 offset:39936
	global_load_lds_dwordx4 v172, s[0:1]
	s_mov_b32 m0, s5
	s_nop 0
	global_load_lds_dwordx4 v168, s[0:1]
	s_waitcnt vmcnt(8)
	s_waitcnt lgkmcnt(0)
	s_setprio 1
	s_barrier
	v_mfma_f32_16x16x32_bf16 v[130:133], v[134:137], v[174:177], v[130:133]
	v_mfma_f32_16x16x32_bf16 v[98:101], v[142:145], v[174:177], v[98:101]
	v_mfma_f32_16x16x32_bf16 v[126:129], v[134:137], v[204:207], v[126:129]
	v_mfma_f32_16x16x32_bf16 v[90:93], v[142:145], v[204:207], v[90:93]
	v_mfma_f32_16x16x32_bf16 v[122:125], v[134:137], v[218:221], v[122:125]
	v_mfma_f32_16x16x32_bf16 v[82:85], v[142:145], v[218:221], v[82:85]
	v_mfma_f32_16x16x32_bf16 v[118:121], v[134:137], v[226:229], v[118:121]
	v_mfma_f32_16x16x32_bf16 v[74:77], v[142:145], v[226:229], v[74:77]
	v_mfma_f32_16x16x32_bf16 v[130:133], v[138:141], v[200:203], v[130:133]
	v_mfma_f32_16x16x32_bf16 v[98:101], v[146:149], v[200:203], v[98:101]
	v_mfma_f32_16x16x32_bf16 v[126:129], v[138:141], v[214:217], v[126:129]
	v_mfma_f32_16x16x32_bf16 v[90:93], v[146:149], v[214:217], v[90:93]
	v_mfma_f32_16x16x32_bf16 v[122:125], v[138:141], v[222:225], v[122:125]
	v_mfma_f32_16x16x32_bf16 v[82:85], v[146:149], v[222:225], v[82:85]
	v_mfma_f32_16x16x32_bf16 v[118:121], v[138:141], v[230:233], v[118:121]
	v_mfma_f32_16x16x32_bf16 v[74:77], v[146:149], v[230:233], v[74:77]
	v_mfma_f32_16x16x32_bf16 v[114:117], v[150:153], v[174:177], v[114:117]
	v_mfma_f32_16x16x32_bf16 v[66:69], v[158:161], v[174:177], v[66:69]
	v_mfma_f32_16x16x32_bf16 v[110:113], v[150:153], v[204:207], v[110:113]
	v_mfma_f32_16x16x32_bf16 v[58:61], v[158:161], v[204:207], v[58:61]
	v_mfma_f32_16x16x32_bf16 v[106:109], v[150:153], v[218:221], v[106:109]
	v_mfma_f32_16x16x32_bf16 v[50:53], v[158:161], v[218:221], v[50:53]
	v_mfma_f32_16x16x32_bf16 v[102:105], v[150:153], v[226:229], v[102:105]
	v_mfma_f32_16x16x32_bf16 v[42:45], v[158:161], v[226:229], v[42:45]
	v_mfma_f32_16x16x32_bf16 v[114:117], v[154:157], v[200:203], v[114:117]
	v_mfma_f32_16x16x32_bf16 v[66:69], v[162:165], v[200:203], v[66:69]
	v_mfma_f32_16x16x32_bf16 v[110:113], v[154:157], v[214:217], v[110:113]
	v_mfma_f32_16x16x32_bf16 v[58:61], v[162:165], v[214:217], v[58:61]
	v_mfma_f32_16x16x32_bf16 v[106:109], v[154:157], v[222:225], v[106:109]
	v_mfma_f32_16x16x32_bf16 v[50:53], v[162:165], v[222:225], v[50:53]
	v_mfma_f32_16x16x32_bf16 v[102:105], v[154:157], v[230:233], v[102:105]
	v_mfma_f32_16x16x32_bf16 v[42:45], v[162:165], v[230:233], v[42:45]
	s_barrier
; #define PG8_STAGEX(b, gbase) do { if constexpr (XR) { if (lane < 16) __builtin_amdgcn_global_load_lds((const unsigned*)((const char*)(gbase) + voffX), (PG8_LAS unsigned*)(lds + XR_OFF + (b) * 2048 + wid * 256), 16, 0, 0); } } while (0)
; #define PG8_WAIT_LOOP() do { if constexpr (XR) PG8_WAIT_V(9); else PG8_WAIT_V(8); } while (0)
; #define PG8_STAGE(bufoff, gbase, voff) do { _Pragma("unroll") for (int _i = 0; _i < 2; ++_i) \
;         __builtin_amdgcn_global_load_lds((const unsigned*)((const char*)(gbase) + (voff)[_i]), (PG8_LAS unsigned*)(lds + (bufoff) + ldsw + _i * 8192), 16, 0, 0); } while (0)
; #define PG8_LDA(dst, b, h) do { _Pragma("unroll") for (int m = 0; m < 4; ++m) _Pragma("unroll") for (int k = 0; k < 2; ++k) dst[m][k] = *(const PG8_LAS bf16x8*)(lds + PG8_SA(b, h) + aoff + m * 2048 + k * 1024); } while (0)
; #define PG8_MMA(ai, bj, At, Bt) do { __builtin_amdgcn_s_setprio(1); _Pragma("unroll") for (int m = 0; m < 4; ++m) _Pragma("unroll") for (int n = 0; n < 2; ++n) _Pragma("unroll") for (int k = 0; k < 2; ++k) \
;         acc[ai][bj][m][n] = __builtin_amdgcn_mfma_f32_16x16x32_bf16(Bt[n][k], At[m][k], acc[ai][bj][m][n], 0, 0, 0); __builtin_amdgcn_s_setprio(0); } while (0)
; #define PG8_WAIT_L(n) asm volatile("s_waitcnt lgkmcnt(" #n ")" ::: "memory")
; #define PG8_BAR __builtin_amdgcn_s_barrier()
; #define PG8_SCHED __builtin_amdgcn_sched_barrier(0)
; template <class Epi, class Sched, bool ALIGN_EPI = false, bool SP2 = false, bool DRAIN = true, bool XR = false>
; __device__ __forceinline__ void gemm_phase(PG8_LAS unsigned char* lds, const Gemm g, const Sched& S, const Epi& E) {
;     ...
;         for (int t = 0; t < nt; t += 2) {
;     ...
;             PG8_LDA(At, 1, 1); PG8_STAGE(PG8_SB(1, 0), b3, voffB); PG8_STAGE(PG8_SB(1, 1), b3 + hstep, voffB); PG8_STAGE(PG8_SA(1, 0), a3, voffA); PG8_STAGEX(1, x3);
;             PG8_WAIT_LOOP(); PG8_WAIT_L(0); PG8_BAR; PG8_MMA(1, 0, At, B0); PG8_MMA(1, 1, At, B1); PG8_BAR; PG8_SCHED;
	s_setprio 0
	s_add_i32 s0, s36, s48
	v_lshl_add_u64 v[8:9], v[178:179], 0, s[86:87]
	s_mov_b32 m0, s0
	ds_read_b128 v[174:177], v199 offset:49152
	ds_read_b128 v[200:203], v199 offset:50176
	ds_read_b128 v[204:207], v199 offset:51200
	ds_read_b128 v[214:217], v199 offset:52224
	ds_read_b128 v[218:221], v199 offset:53248
	ds_read_b128 v[222:225], v199 offset:54272
	ds_read_b128 v[226:229], v199 offset:55296
	ds_read_b128 v[230:233], v199 offset:56320
	global_load_lds_dwordx4 v[8:9], off
	v_lshl_add_u64 v[8:9], v[208:209], 0, s[86:87]
	s_add_i32 m0, s0, 0x2000
	s_add_i32 s0, s40, s48
	global_load_lds_dwordx4 v[8:9], off
	v_lshl_add_u64 v[8:9], v[212:213], 0, s[86:87]
	s_mov_b32 m0, s0
	s_nop 0
	global_load_lds_dwordx4 v[8:9], off
	v_lshl_add_u64 v[8:9], v[234:235], 0, s[86:87]
	s_add_i32 m0, s0, 0x2000
	s_nop 0
	global_load_lds_dwordx4 v[8:9], off
	v_lshl_add_u64 v[8:9], v[236:237], 0, s[86:87]
	s_mov_b32 m0, s77
	s_nop 0
	global_load_lds_dwordx4 v[8:9], off
	v_lshl_add_u64 v[8:9], v[238:239], 0, s[86:87]
	s_mov_b32 m0, s6
	s_nop 0
	global_load_lds_dwordx4 v[8:9], off
	s_waitcnt vmcnt(8)
	s_waitcnt lgkmcnt(0)
	s_setprio 1
	s_barrier
	v_mfma_f32_16x16x32_bf16 v[94:97], v[134:137], v[174:177], v[94:97]
	v_mfma_f32_16x16x32_bf16 v[34:37], v[142:145], v[174:177], v[34:37]
	v_mfma_f32_16x16x32_bf16 v[86:89], v[134:137], v[204:207], v[86:89]
	v_mfma_f32_16x16x32_bf16 v[30:33], v[142:145], v[204:207], v[30:33]
	v_mfma_f32_16x16x32_bf16 v[78:81], v[134:137], v[218:221], v[78:81]
	v_mfma_f32_16x16x32_bf16 v[26:29], v[142:145], v[218:221], v[26:29]
	v_mfma_f32_16x16x32_bf16 v[70:73], v[134:137], v[226:229], v[70:73]
	v_mfma_f32_16x16x32_bf16 v[22:25], v[142:145], v[226:229], v[22:25]
	v_mfma_f32_16x16x32_bf16 v[94:97], v[138:141], v[200:203], v[94:97]
	v_mfma_f32_16x16x32_bf16 v[34:37], v[146:149], v[200:203], v[34:37]
	v_mfma_f32_16x16x32_bf16 v[86:89], v[138:141], v[214:217], v[86:89]
	v_mfma_f32_16x16x32_bf16 v[30:33], v[146:149], v[214:217], v[30:33]
	v_mfma_f32_16x16x32_bf16 v[78:81], v[138:141], v[222:225], v[78:81]
	v_mfma_f32_16x16x32_bf16 v[26:29], v[146:149], v[222:225], v[26:29]
	v_mfma_f32_16x16x32_bf16 v[70:73], v[138:141], v[230:233], v[70:73]
	v_mfma_f32_16x16x32_bf16 v[22:25], v[146:149], v[230:233], v[22:25]
	v_mfma_f32_16x16x32_bf16 v[62:65], v[150:153], v[174:177], v[62:65]
	v_mfma_f32_16x16x32_bf16 v[18:21], v[158:161], v[174:177], v[18:21]
	v_mfma_f32_16x16x32_bf16 v[54:57], v[150:153], v[204:207], v[54:57]
	v_mfma_f32_16x16x32_bf16 v[14:17], v[158:161], v[204:207], v[14:17]
	v_mfma_f32_16x16x32_bf16 v[46:49], v[150:153], v[218:221], v[46:49]
	v_mfma_f32_16x16x32_bf16 v[8:11], v[158:161], v[218:221], v[10:13]
	v_mfma_f32_16x16x32_bf16 v[38:41], v[150:153], v[226:229], v[38:41]
	v_mfma_f32_16x16x32_bf16 v[4:7], v[158:161], v[226:229], v[4:7]
	v_mfma_f32_16x16x32_bf16 v[62:65], v[154:157], v[200:203], v[62:65]
	v_mfma_f32_16x16x32_bf16 v[18:21], v[162:165], v[200:203], v[18:21]
	v_mfma_f32_16x16x32_bf16 v[54:57], v[154:157], v[214:217], v[54:57]
	v_mfma_f32_16x16x32_bf16 v[14:17], v[162:165], v[214:217], v[14:17]
	v_mfma_f32_16x16x32_bf16 v[46:49], v[154:157], v[222:225], v[46:49]
	v_mfma_f32_16x16x32_bf16 v[10:13], v[162:165], v[222:225], v[8:11]
	v_mfma_f32_16x16x32_bf16 v[38:41], v[154:157], v[230:233], v[38:41]
	v_mfma_f32_16x16x32_bf16 v[6:9], v[162:165], v[230:233], v[4:7]
	s_barrier
	s_setprio 0
	s_add_i32 s25, s25, 2
	s_cmp_ge_i32 s25, s78
	s_cbranch_scc0 .LBB0_2023
